# snake MFMA order with the closing barrier ahead of the last 2 (instead of 4) MFMAs
# speedup vs baseline: 1.0196x; 1.0037x over previous
; #define PG8_STAGE(bufoff, gbase, voff) do { _Pragma("unroll") for (int _i = 0; _i < 2; ++_i) \
;         __builtin_amdgcn_global_load_lds((const unsigned*)((const char*)(gbase) + (voff)[_i]), (PG8_LAS unsigned*)(lds + (bufoff) + ldsw + _i * 8192), 16, 0, 0); } while (0)
; #define PG8_LDA(dst, b, h) do { _Pragma("unroll") for (int m = 0; m < 4; ++m) _Pragma("unroll") for (int k = 0; k < 2; ++k) dst[m][k] = *(const PG8_LAS bf16x8*)(lds + PG8_SA(b, h) + aoff + m * 2048 + k * 1024); } while (0)
; #define PG8_LDB(dst, b, h) do { _Pragma("unroll") for (int n = 0; n < 2; ++n) _Pragma("unroll") for (int k = 0; k < 2; ++k) dst[n][k] = *(const PG8_LAS bf16x8*)(lds + PG8_SB(b, h) + boff + n * 2048 + k * 1024); } while (0)
; #define PG8_BAR __builtin_amdgcn_s_barrier()
; template <class Epi, class Sched, bool ALIGN_EPI = false, bool SP2 = false>
; __device__ __forceinline__ void gemm_phase(PG8_LAS unsigned char* lds, const Gemm g, const Sched& S, const Epi& E) {
;     ...
;             const bool last = (t == nt - 2);
;             const char* a1 = cA + (size_t)(t + 1) * kstep;
;             const char* a2 = last ? nA : cA + (size_t)(t + 2) * kstep; const char* b2 = last ? nB : cB + (size_t)(t + 2) * kstep;
;             const char* a3 = a2 + kstep; const char* b3 = b2 + kstep;
;             if (last && has_next) S.a_ready(nxt);
;             if constexpr (SP2) {
;             PG8_LDB(B0, 0, 0); PG8_LDB(B1, 0, 1); PG8_SCHED; PG8_LDA(At, 0, 0); PG8_STAGE(PG8_SA(1, 1), a1 + hstep, voffA);
;             PG8_WAIT_V(8); PG8_WAIT_L(0); PG8_BAR; PG8_MMA(0, 0, At, B0); PG8_MMA(0, 1, At, B1); PG8_BAR; PG8_SCHED;
;             PG8_LDA(At, 0, 1); PG8_STAGE(PG8_SB(0, 0), b2, voffB); PG8_STAGE(PG8_SB(0, 1), b2 + hstep, voffB); PG8_STAGE(PG8_SA(0, 0), a2, voffA);
;             PG8_WAIT_V(8); PG8_WAIT_L(0); PG8_BAR; PG8_MMA(1, 0, At, B0); PG8_MMA(1, 1, At, B1); PG8_BAR; PG8_SCHED;
;             PG8_LDB(B0, 1, 0); PG8_LDB(B1, 1, 1); PG8_SCHED; PG8_LDA(At, 1, 0); PG8_STAGE(PG8_SA(0, 1), a2 + hstep, voffA);
;             PG8_WAIT_V(8); PG8_WAIT_L(0); PG8_BAR; PG8_MMA(0, 0, At, B0); PG8_MMA(0, 1, At, B1); PG8_BAR; PG8_SCHED;
;             PG8_LDA(At, 1, 1); PG8_STAGE(PG8_SB(1, 0), b3, voffB); PG8_STAGE(PG8_SB(1, 1), b3 + hstep, voffB); PG8_STAGE(PG8_SA(1, 0), a3, voffA);
;             PG8_WAIT_V(8); PG8_WAIT_L(0); PG8_BAR; PG8_MMA(1, 0, At, B0); PG8_MMA(1, 1, At, B1); PG8_BAR; PG8_SCHED;
.LBB0_110:
	ds_read_b128 v[136:139], v161
	ds_read_b128 v[140:143], v161 offset:1024
	ds_read_b128 v[176:179], v161 offset:2048
	ds_read_b128 v[180:183], v161 offset:3072
	ds_read_b128 v[184:187], v162
	ds_read_b128 v[202:205], v162 offset:1024
	ds_read_b128 v[206:209], v162 offset:2048
	ds_read_b128 v[210:213], v162 offset:3072
	s_add_u32 s28, s52, 0xfff80080
	s_addc_u32 s29, s53, -1
	s_cmp_eq_u32 s74, 28
	s_cselect_b32 s49, s25, s29
	s_cselect_b32 s48, s34, s28
	s_cselect_b32 s29, s23, s73
	s_cselect_b32 s28, s35, s72
	v_lshl_add_u64 v[246:247], s[52:53], 0, v[128:129]
	s_add_i32 m0, s9, 0xc000
	ds_read_b128 v[214:217], v163
	ds_read_b128 v[218:221], v163 offset:1024
	ds_read_b128 v[222:225], v163 offset:2048
	ds_read_b128 v[226:229], v163 offset:3072
	ds_read_b128 v[230:233], v163 offset:4096
	ds_read_b128 v[234:237], v163 offset:5120
	ds_read_b128 v[238:241], v163 offset:6144
	ds_read_b128 v[242:245], v163 offset:7168
	global_load_lds_dwordx4 v[246:247], off
	v_lshl_add_u64 v[246:247], s[52:53], 0, v[130:131]
	s_add_i32 m0, s9, 0xe000
	s_nop 0
	global_load_lds_dwordx4 v[246:247], off
	s_waitcnt vmcnt(8)
	s_waitcnt lgkmcnt(0)
	s_barrier
	s_setprio 1
	s_waitcnt lgkmcnt(0)
	v_mfma_f32_16x16x32_bf16 v[124:127], v[136:139], v[214:217], v[124:127]
	v_mfma_f32_16x16x32_bf16 v[124:127], v[140:143], v[218:221], v[124:127]
	v_mfma_f32_16x16x32_bf16 v[120:123], v[180:183], v[218:221], v[120:123]
	v_mfma_f32_16x16x32_bf16 v[120:123], v[176:179], v[214:217], v[120:123]
	v_mfma_f32_16x16x32_bf16 v[104:107], v[176:179], v[222:225], v[104:107]
	v_mfma_f32_16x16x32_bf16 v[104:107], v[180:183], v[226:229], v[104:107]
	v_mfma_f32_16x16x32_bf16 v[108:111], v[140:143], v[226:229], v[108:111]
	v_mfma_f32_16x16x32_bf16 v[108:111], v[136:139], v[222:225], v[108:111]
	v_mfma_f32_16x16x32_bf16 v[96:99], v[136:139], v[230:233], v[96:99]
	v_mfma_f32_16x16x32_bf16 v[96:99], v[140:143], v[234:237], v[96:99]
	v_mfma_f32_16x16x32_bf16 v[88:91], v[180:183], v[234:237], v[88:91]
	v_mfma_f32_16x16x32_bf16 v[88:91], v[176:179], v[230:233], v[88:91]
	v_mfma_f32_16x16x32_bf16 v[72:75], v[176:179], v[238:241], v[72:75]
	v_mfma_f32_16x16x32_bf16 v[72:75], v[180:183], v[242:245], v[72:75]
	v_mfma_f32_16x16x32_bf16 v[80:83], v[140:143], v[242:245], v[80:83]
	v_mfma_f32_16x16x32_bf16 v[80:83], v[136:139], v[238:241], v[80:83]
	s_setprio 0
	s_setprio 1
	v_mfma_f32_16x16x32_bf16 v[116:119], v[184:187], v[214:217], v[116:119]
	v_mfma_f32_16x16x32_bf16 v[116:119], v[202:205], v[218:221], v[116:119]
	v_mfma_f32_16x16x32_bf16 v[112:115], v[210:213], v[218:221], v[112:115]
	v_mfma_f32_16x16x32_bf16 v[112:115], v[206:209], v[214:217], v[112:115]
	v_mfma_f32_16x16x32_bf16 v[92:95], v[206:209], v[222:225], v[92:95]
	v_mfma_f32_16x16x32_bf16 v[92:95], v[210:213], v[226:229], v[92:95]
	v_mfma_f32_16x16x32_bf16 v[100:103], v[202:205], v[226:229], v[100:103]
	v_mfma_f32_16x16x32_bf16 v[100:103], v[184:187], v[222:225], v[100:103]
	v_mfma_f32_16x16x32_bf16 v[84:87], v[184:187], v[230:233], v[84:87]
	v_mfma_f32_16x16x32_bf16 v[84:87], v[202:205], v[234:237], v[84:87]
	v_mfma_f32_16x16x32_bf16 v[76:79], v[210:213], v[234:237], v[76:79]
	v_mfma_f32_16x16x32_bf16 v[76:79], v[206:209], v[230:233], v[76:79]
	v_mfma_f32_16x16x32_bf16 v[64:67], v[206:209], v[238:241], v[64:67]
	v_mfma_f32_16x16x32_bf16 v[64:67], v[210:213], v[242:245], v[64:67]
	s_setprio 2
	s_barrier
	v_mfma_f32_16x16x32_bf16 v[68:71], v[202:205], v[242:245], v[68:71]
	v_mfma_f32_16x16x32_bf16 v[68:71], v[184:187], v[238:241], v[68:71]
	s_setprio 0
	s_add_i32 s75, s63, s45
	v_lshl_add_u64 v[246:247], s[28:29], 0, v[166:167]
	s_mov_b32 m0, s75
	ds_read_b128 v[214:217], v163 offset:16384
	ds_read_b128 v[218:221], v163 offset:17408
	ds_read_b128 v[222:225], v163 offset:18432
	ds_read_b128 v[226:229], v163 offset:19456
	ds_read_b128 v[230:233], v163 offset:20480
	ds_read_b128 v[234:237], v163 offset:21504
	ds_read_b128 v[238:241], v163 offset:22528
	ds_read_b128 v[242:245], v163 offset:23552
	global_load_lds_dwordx4 v[246:247], off
	s_add_i32 m0, s75, 0x2000
	s_add_u32 s76, s28, 0x80000
	v_lshl_add_u64 v[248:249], s[28:29], 0, v[170:171]
	s_addc_u32 s77, s29, 0
	s_add_i32 s75, s64, s45
	global_load_lds_dwordx4 v[248:249], off
	v_lshl_add_u64 v[250:251], s[76:77], 0, v[166:167]
	s_mov_b32 m0, s75
	v_lshl_add_u64 v[252:253], s[48:49], 0, v[168:169]
	global_load_lds_dwordx4 v[250:251], off
	v_lshl_add_u64 v[250:251], s[76:77], 0, v[170:171]
	s_add_i32 m0, s75, 0x2000
	s_nop 0
	global_load_lds_dwordx4 v[250:251], off
	v_lshl_add_u64 v[250:251], s[48:49], 0, v[164:165]
	s_mov_b32 m0, s9
	s_nop 0
	global_load_lds_dwordx4 v[250:251], off
	s_mov_b32 m0, s57
	s_nop 0
	global_load_lds_dwordx4 v[252:253], off
	s_waitcnt vmcnt(8)
	s_waitcnt lgkmcnt(0)
	s_barrier
; #define PG8_STAGE(bufoff, gbase, voff) do { _Pragma("unroll") for (int _i = 0; _i < 2; ++_i) \
;         __builtin_amdgcn_global_load_lds((const unsigned*)((const char*)(gbase) + (voff)[_i]), (PG8_LAS unsigned*)(lds + (bufoff) + ldsw + _i * 8192), 16, 0, 0); } while (0)
; #define PG8_LDA(dst, b, h) do { _Pragma("unroll") for (int m = 0; m < 4; ++m) _Pragma("unroll") for (int k = 0; k < 2; ++k) dst[m][k] = *(const PG8_LAS bf16x8*)(lds + PG8_SA(b, h) + aoff + m * 2048 + k * 1024); } while (0)
; #define PG8_LDB(dst, b, h) do { _Pragma("unroll") for (int n = 0; n < 2; ++n) _Pragma("unroll") for (int k = 0; k < 2; ++k) dst[n][k] = *(const PG8_LAS bf16x8*)(lds + PG8_SB(b, h) + boff + n * 2048 + k * 1024); } while (0)
; #define PG8_MMA(ai, bj, At, Bt) do { __builtin_amdgcn_s_setprio(1); _Pragma("unroll") for (int m = 0; m < 4; ++m) _Pragma("unroll") for (int n = 0; n < 2; ++n) _Pragma("unroll") for (int k = 0; k < 2; ++k) \
;         acc[ai][bj][m][n] = __builtin_amdgcn_mfma_f32_16x16x32_bf16(Bt[n][k], At[m][k], acc[ai][bj][m][n], 0, 0, 0); __builtin_amdgcn_s_setprio(0); } while (0)
; #define PG8_WAIT_V(n) asm volatile("s_waitcnt vmcnt(" #n ")" ::: "memory")
; template <class Epi, class Sched, bool ALIGN_EPI = false, bool SP2 = false>
; __device__ __forceinline__ void gemm_phase(PG8_LAS unsigned char* lds, const Gemm g, const Sched& S, const Epi& E) {
;     ...
;             PG8_LDB(B0, 0, 0); PG8_LDB(B1, 0, 1); PG8_SCHED; PG8_LDA(At, 0, 0); PG8_STAGE(PG8_SA(1, 1), a1 + hstep, voffA);
;             PG8_WAIT_V(8); PG8_WAIT_L(0); PG8_BAR; PG8_MMA(0, 0, At, B0); PG8_MMA(0, 1, At, B1); PG8_BAR; PG8_SCHED;
;             PG8_LDA(At, 0, 1); PG8_STAGE(PG8_SB(0, 0), b2, voffB); PG8_STAGE(PG8_SB(0, 1), b2 + hstep, voffB); PG8_STAGE(PG8_SA(0, 0), a2, voffA);
;             PG8_WAIT_V(8); PG8_WAIT_L(0); PG8_BAR; PG8_MMA(1, 0, At, B0); PG8_MMA(1, 1, At, B1); PG8_BAR; PG8_SCHED;
;             PG8_LDB(B0, 1, 0); PG8_LDB(B1, 1, 1); PG8_SCHED; PG8_LDA(At, 1, 0); PG8_STAGE(PG8_SA(0, 1), a2 + hstep, voffA);
;             PG8_WAIT_V(8); PG8_WAIT_L(0); PG8_BAR; PG8_MMA(0, 0, At, B0); PG8_MMA(0, 1, At, B1); PG8_BAR; PG8_SCHED;
;             PG8_LDA(At, 1, 1); PG8_STAGE(PG8_SB(1, 0), b3, voffB); PG8_STAGE(PG8_SB(1, 1), b3 + hstep, voffB); PG8_STAGE(PG8_SA(1, 0), a3, voffA);
;             PG8_WAIT_V(8); PG8_WAIT_L(0); PG8_BAR; PG8_MMA(1, 0, At, B0); PG8_MMA(1, 1, At, B1); PG8_BAR; PG8_SCHED;
	s_setprio 1
	s_waitcnt lgkmcnt(0)
	v_mfma_f32_16x16x32_bf16 v[60:63], v[136:139], v[214:217], v[60:63]
	v_mfma_f32_16x16x32_bf16 v[60:63], v[140:143], v[218:221], v[60:63]
	v_mfma_f32_16x16x32_bf16 v[56:59], v[180:183], v[218:221], v[56:59]
	v_mfma_f32_16x16x32_bf16 v[56:59], v[176:179], v[214:217], v[56:59]
	v_mfma_f32_16x16x32_bf16 v[40:43], v[176:179], v[222:225], v[40:43]
	v_mfma_f32_16x16x32_bf16 v[40:43], v[180:183], v[226:229], v[40:43]
	v_mfma_f32_16x16x32_bf16 v[48:51], v[140:143], v[226:229], v[48:51]
	v_mfma_f32_16x16x32_bf16 v[48:51], v[136:139], v[222:225], v[48:51]
	v_mfma_f32_16x16x32_bf16 v[32:35], v[136:139], v[230:233], v[32:35]
	v_mfma_f32_16x16x32_bf16 v[32:35], v[140:143], v[234:237], v[32:35]
	v_mfma_f32_16x16x32_bf16 v[24:27], v[180:183], v[234:237], v[24:27]
	v_mfma_f32_16x16x32_bf16 v[24:27], v[176:179], v[230:233], v[24:27]
	v_mfma_f32_16x16x32_bf16 v[8:11], v[176:179], v[238:241], v[8:11]
	v_mfma_f32_16x16x32_bf16 v[8:11], v[180:183], v[242:245], v[8:11]
	v_mfma_f32_16x16x32_bf16 v[12:15], v[140:143], v[242:245], v[12:15]
	v_mfma_f32_16x16x32_bf16 v[12:15], v[136:139], v[238:241], v[12:15]
	s_setprio 0
	s_setprio 1
	v_mfma_f32_16x16x32_bf16 v[52:55], v[184:187], v[214:217], v[52:55]
	v_mfma_f32_16x16x32_bf16 v[52:55], v[202:205], v[218:221], v[52:55]
	v_mfma_f32_16x16x32_bf16 v[44:47], v[210:213], v[218:221], v[44:47]
	v_mfma_f32_16x16x32_bf16 v[44:47], v[206:209], v[214:217], v[44:47]
	v_mfma_f32_16x16x32_bf16 v[28:31], v[206:209], v[222:225], v[28:31]
	v_mfma_f32_16x16x32_bf16 v[28:31], v[210:213], v[226:229], v[28:31]
	v_mfma_f32_16x16x32_bf16 v[36:39], v[202:205], v[226:229], v[36:39]
	v_mfma_f32_16x16x32_bf16 v[36:39], v[184:187], v[222:225], v[36:39]
	v_mfma_f32_16x16x32_bf16 v[20:23], v[184:187], v[230:233], v[20:23]
	v_mfma_f32_16x16x32_bf16 v[20:23], v[202:205], v[234:237], v[20:23]
	v_mfma_f32_16x16x32_bf16 v[16:19], v[210:213], v[234:237], v[16:19]
	v_mfma_f32_16x16x32_bf16 v[16:19], v[206:209], v[230:233], v[16:19]
	v_mfma_f32_16x16x32_bf16 v[0:3], v[206:209], v[238:241], v[0:3]
	v_mfma_f32_16x16x32_bf16 v[0:3], v[210:213], v[242:245], v[0:3]
	s_setprio 2
	s_barrier
	v_mfma_f32_16x16x32_bf16 v[4:7], v[202:205], v[242:245], v[4:7]
	v_mfma_f32_16x16x32_bf16 v[4:7], v[184:187], v[238:241], v[4:7]
	s_setprio 0
	s_add_i32 s75, 0, 0x18000
	v_add_u32_e32 v144, s75, v151
	s_add_i32 s76, 0, 0x1c000
	ds_read_b128 v[136:139], v144
	ds_read_b128 v[140:143], v144 offset:1024
	ds_read_b128 v[176:179], v144 offset:2048
	ds_read_b128 v[180:183], v144 offset:3072
	v_add_u32_e32 v144, s76, v151
	ds_read_b128 v[184:187], v144
	ds_read_b128 v[202:205], v144 offset:1024
	ds_read_b128 v[206:209], v144 offset:2048
	ds_read_b128 v[210:213], v144 offset:3072
	s_add_u32 s48, s48, 0x80000
	s_addc_u32 s49, s49, 0
	s_mov_b32 m0, s58
	v_lshl_add_u64 v[200:201], s[48:49], 0, v[164:165]
	ds_read_b128 v[214:217], v163 offset:32768
	ds_read_b128 v[218:221], v163 offset:33792
	ds_read_b128 v[222:225], v163 offset:34816
	ds_read_b128 v[226:229], v163 offset:35840
	ds_read_b128 v[230:233], v163 offset:36864
	ds_read_b128 v[234:237], v163 offset:37888
	ds_read_b128 v[238:241], v163 offset:38912
	ds_read_b128 v[242:245], v163 offset:39936
	global_load_lds_dwordx4 v[200:201], off
	v_lshl_add_u64 v[200:201], s[48:49], 0, v[168:169]
	s_mov_b32 m0, s59
	s_nop 0
	global_load_lds_dwordx4 v[200:201], off
	s_waitcnt vmcnt(8)
	s_waitcnt lgkmcnt(0)
	s_barrier
	s_setprio 1
	s_waitcnt lgkmcnt(0)
	v_mfma_f32_16x16x32_bf16 v[124:127], v[136:139], v[214:217], v[124:127]
	v_mfma_f32_16x16x32_bf16 v[124:127], v[140:143], v[218:221], v[124:127]
	v_mfma_f32_16x16x32_bf16 v[120:123], v[180:183], v[218:221], v[120:123]
	v_mfma_f32_16x16x32_bf16 v[120:123], v[176:179], v[214:217], v[120:123]
	v_mfma_f32_16x16x32_bf16 v[104:107], v[176:179], v[222:225], v[104:107]
	v_mfma_f32_16x16x32_bf16 v[104:107], v[180:183], v[226:229], v[104:107]
	v_mfma_f32_16x16x32_bf16 v[108:111], v[140:143], v[226:229], v[108:111]
	v_mfma_f32_16x16x32_bf16 v[108:111], v[136:139], v[222:225], v[108:111]
	v_mfma_f32_16x16x32_bf16 v[96:99], v[136:139], v[230:233], v[96:99]
	v_mfma_f32_16x16x32_bf16 v[96:99], v[140:143], v[234:237], v[96:99]
	v_mfma_f32_16x16x32_bf16 v[88:91], v[180:183], v[234:237], v[88:91]
	v_mfma_f32_16x16x32_bf16 v[88:91], v[176:179], v[230:233], v[88:91]
	v_mfma_f32_16x16x32_bf16 v[72:75], v[176:179], v[238:241], v[72:75]
	v_mfma_f32_16x16x32_bf16 v[72:75], v[180:183], v[242:245], v[72:75]
	v_mfma_f32_16x16x32_bf16 v[80:83], v[140:143], v[242:245], v[80:83]
	v_mfma_f32_16x16x32_bf16 v[80:83], v[136:139], v[238:241], v[80:83]
	s_setprio 0
	s_setprio 1
	v_mfma_f32_16x16x32_bf16 v[116:119], v[184:187], v[214:217], v[116:119]
	v_mfma_f32_16x16x32_bf16 v[116:119], v[202:205], v[218:221], v[116:119]
	v_mfma_f32_16x16x32_bf16 v[112:115], v[210:213], v[218:221], v[112:115]
	v_mfma_f32_16x16x32_bf16 v[112:115], v[206:209], v[214:217], v[112:115]
	v_mfma_f32_16x16x32_bf16 v[92:95], v[206:209], v[222:225], v[92:95]
	v_mfma_f32_16x16x32_bf16 v[92:95], v[210:213], v[226:229], v[92:95]
	v_mfma_f32_16x16x32_bf16 v[100:103], v[202:205], v[226:229], v[100:103]
	v_mfma_f32_16x16x32_bf16 v[100:103], v[184:187], v[222:225], v[100:103]
	v_mfma_f32_16x16x32_bf16 v[84:87], v[184:187], v[230:233], v[84:87]
	v_mfma_f32_16x16x32_bf16 v[84:87], v[202:205], v[234:237], v[84:87]
	v_mfma_f32_16x16x32_bf16 v[76:79], v[210:213], v[234:237], v[76:79]
	v_mfma_f32_16x16x32_bf16 v[76:79], v[206:209], v[230:233], v[76:79]
	v_mfma_f32_16x16x32_bf16 v[64:67], v[206:209], v[238:241], v[64:67]
	v_mfma_f32_16x16x32_bf16 v[64:67], v[210:213], v[242:245], v[64:67]
	s_setprio 2
	s_barrier
; #define PG8_STAGE(bufoff, gbase, voff) do { _Pragma("unroll") for (int _i = 0; _i < 2; ++_i) \
;         __builtin_amdgcn_global_load_lds((const unsigned*)((const char*)(gbase) + (voff)[_i]), (PG8_LAS unsigned*)(lds + (bufoff) + ldsw + _i * 8192), 16, 0, 0); } while (0)
; #define PG8_LDA(dst, b, h) do { _Pragma("unroll") for (int m = 0; m < 4; ++m) _Pragma("unroll") for (int k = 0; k < 2; ++k) dst[m][k] = *(const PG8_LAS bf16x8*)(lds + PG8_SA(b, h) + aoff + m * 2048 + k * 1024); } while (0)
; #define PG8_LDB(dst, b, h) do { _Pragma("unroll") for (int n = 0; n < 2; ++n) _Pragma("unroll") for (int k = 0; k < 2; ++k) dst[n][k] = *(const PG8_LAS bf16x8*)(lds + PG8_SB(b, h) + boff + n * 2048 + k * 1024); } while (0)
; template <class Epi, class Sched, bool ALIGN_EPI = false, bool SP2 = false>
; __device__ __forceinline__ void gemm_phase(PG8_LAS unsigned char* lds, const Gemm g, const Sched& S, const Epi& E) {
;     ...
;         for (int t = 0; t < nt; t += 2) {
;             const bool last = (t == nt - 2);
;             const char* a1 = cA + (size_t)(t + 1) * kstep;
;             const char* a2 = last ? nA : cA + (size_t)(t + 2) * kstep; const char* b2 = last ? nB : cB + (size_t)(t + 2) * kstep;
;             const char* a3 = a2 + kstep; const char* b3 = b2 + kstep;
;             if (last && has_next) S.a_ready(nxt);
;             if constexpr (SP2) {
;             PG8_LDB(B0, 0, 0); PG8_LDB(B1, 0, 1); PG8_SCHED; PG8_LDA(At, 0, 0); PG8_STAGE(PG8_SA(1, 1), a1 + hstep, voffA);
;             PG8_WAIT_V(8); PG8_WAIT_L(0); PG8_BAR; PG8_MMA(0, 0, At, B0); PG8_MMA(0, 1, At, B1); PG8_BAR; PG8_SCHED;
;             PG8_LDA(At, 0, 1); PG8_STAGE(PG8_SB(0, 0), b2, voffB); PG8_STAGE(PG8_SB(0, 1), b2 + hstep, voffB); PG8_STAGE(PG8_SA(0, 0), a2, voffA);
;             PG8_WAIT_V(8); PG8_WAIT_L(0); PG8_BAR; PG8_MMA(1, 0, At, B0); PG8_MMA(1, 1, At, B1); PG8_BAR; PG8_SCHED;
;             PG8_LDB(B0, 1, 0); PG8_LDB(B1, 1, 1); PG8_SCHED; PG8_LDA(At, 1, 0); PG8_STAGE(PG8_SA(0, 1), a2 + hstep, voffA);
;             PG8_WAIT_V(8); PG8_WAIT_L(0); PG8_BAR; PG8_MMA(0, 0, At, B0); PG8_MMA(0, 1, At, B1); PG8_BAR; PG8_SCHED;
;             PG8_LDA(At, 1, 1); PG8_STAGE(PG8_SB(1, 0), b3, voffB); PG8_STAGE(PG8_SB(1, 1), b3 + hstep, voffB); PG8_STAGE(PG8_SA(1, 0), a3, voffA);
;             PG8_WAIT_V(8); PG8_WAIT_L(0); PG8_BAR; PG8_MMA(1, 0, At, B0); PG8_MMA(1, 1, At, B1); PG8_BAR; PG8_SCHED;
	v_mfma_f32_16x16x32_bf16 v[68:71], v[202:205], v[242:245], v[68:71]
	v_mfma_f32_16x16x32_bf16 v[68:71], v[184:187], v[238:241], v[68:71]
	s_setprio 0
	s_add_i32 s48, s75, s45
	v_lshl_add_u64 v[200:201], v[246:247], 0, s[18:19]
	s_mov_b32 m0, s48
	ds_read_b128 v[214:217], v163 offset:49152
	ds_read_b128 v[218:221], v163 offset:50176
	ds_read_b128 v[222:225], v163 offset:51200
	ds_read_b128 v[226:229], v163 offset:52224
	ds_read_b128 v[230:233], v163 offset:53248
	ds_read_b128 v[234:237], v163 offset:54272
	ds_read_b128 v[238:241], v163 offset:55296
	ds_read_b128 v[242:245], v163 offset:56320
	global_load_lds_dwordx4 v[200:201], off
	s_add_i32 m0, s48, 0x2000
	s_add_u32 s28, s28, 0x80080
	v_lshl_add_u64 v[200:201], v[248:249], 0, s[18:19]
	s_addc_u32 s29, s29, 0
	s_add_i32 s48, s76, s45
	global_load_lds_dwordx4 v[200:201], off
	v_lshl_add_u64 v[200:201], s[28:29], 0, v[166:167]
	s_mov_b32 m0, s48
	s_nop 0
	global_load_lds_dwordx4 v[200:201], off
	v_lshl_add_u64 v[200:201], s[28:29], 0, v[170:171]
	s_add_i32 m0, s48, 0x2000
	s_nop 0
	global_load_lds_dwordx4 v[200:201], off
	v_lshl_add_u64 v[200:201], v[250:251], 0, s[18:19]
	s_mov_b32 m0, s61
	s_nop 0
	global_load_lds_dwordx4 v[200:201], off
	v_lshl_add_u64 v[200:201], v[252:253], 0, s[18:19]
	s_mov_b32 m0, s62
	s_nop 0
	global_load_lds_dwordx4 v[200:201], off
	s_waitcnt vmcnt(8)
	s_waitcnt lgkmcnt(0)
	s_barrier
	s_setprio 1
	s_waitcnt lgkmcnt(0)
	v_mfma_f32_16x16x32_bf16 v[60:63], v[136:139], v[214:217], v[60:63]
	v_mfma_f32_16x16x32_bf16 v[60:63], v[140:143], v[218:221], v[60:63]
	v_mfma_f32_16x16x32_bf16 v[56:59], v[180:183], v[218:221], v[56:59]
	v_mfma_f32_16x16x32_bf16 v[56:59], v[176:179], v[214:217], v[56:59]
	v_mfma_f32_16x16x32_bf16 v[40:43], v[176:179], v[222:225], v[40:43]
	v_mfma_f32_16x16x32_bf16 v[40:43], v[180:183], v[226:229], v[40:43]
	v_mfma_f32_16x16x32_bf16 v[48:51], v[140:143], v[226:229], v[48:51]
	v_mfma_f32_16x16x32_bf16 v[48:51], v[136:139], v[222:225], v[48:51]
	v_mfma_f32_16x16x32_bf16 v[32:35], v[136:139], v[230:233], v[32:35]
	v_mfma_f32_16x16x32_bf16 v[32:35], v[140:143], v[234:237], v[32:35]
	v_mfma_f32_16x16x32_bf16 v[24:27], v[180:183], v[234:237], v[24:27]
	v_mfma_f32_16x16x32_bf16 v[24:27], v[176:179], v[230:233], v[24:27]
	v_mfma_f32_16x16x32_bf16 v[8:11], v[176:179], v[238:241], v[8:11]
	v_mfma_f32_16x16x32_bf16 v[8:11], v[180:183], v[242:245], v[8:11]
	v_mfma_f32_16x16x32_bf16 v[12:15], v[140:143], v[242:245], v[12:15]
	v_mfma_f32_16x16x32_bf16 v[12:15], v[136:139], v[238:241], v[12:15]
	s_setprio 0
	s_setprio 1
	v_mfma_f32_16x16x32_bf16 v[52:55], v[184:187], v[214:217], v[52:55]
	v_mfma_f32_16x16x32_bf16 v[52:55], v[202:205], v[218:221], v[52:55]
	v_mfma_f32_16x16x32_bf16 v[44:47], v[210:213], v[218:221], v[44:47]
	v_mfma_f32_16x16x32_bf16 v[44:47], v[206:209], v[214:217], v[44:47]
	v_mfma_f32_16x16x32_bf16 v[28:31], v[206:209], v[222:225], v[28:31]
	v_mfma_f32_16x16x32_bf16 v[28:31], v[210:213], v[226:229], v[28:31]
	v_mfma_f32_16x16x32_bf16 v[36:39], v[202:205], v[226:229], v[36:39]
	v_mfma_f32_16x16x32_bf16 v[36:39], v[184:187], v[222:225], v[36:39]
	v_mfma_f32_16x16x32_bf16 v[20:23], v[184:187], v[230:233], v[20:23]
	v_mfma_f32_16x16x32_bf16 v[20:23], v[202:205], v[234:237], v[20:23]
	v_mfma_f32_16x16x32_bf16 v[16:19], v[210:213], v[234:237], v[16:19]
	v_mfma_f32_16x16x32_bf16 v[16:19], v[206:209], v[230:233], v[16:19]
	v_mfma_f32_16x16x32_bf16 v[0:3], v[206:209], v[238:241], v[0:3]
	v_mfma_f32_16x16x32_bf16 v[0:3], v[210:213], v[242:245], v[0:3]
	s_setprio 2
	s_barrier
	v_mfma_f32_16x16x32_bf16 v[4:7], v[202:205], v[242:245], v[4:7]
	v_mfma_f32_16x16x32_bf16 v[4:7], v[184:187], v[238:241], v[4:7]
	s_setprio 0
	s_add_i32 s74, s74, 2
	s_add_u32 s52, s52, 0x100
	s_addc_u32 s53, s53, 0
	s_add_u32 s72, s72, 0x100
	s_addc_u32 s73, s73, 0
	s_cmp_gt_u32 s74, 29
	s_cbranch_scc0 .LBB0_110
	s_and_b64 vcc, exec, s[20:21]
	s_cbranch_vccz .LBB0_113
	s_barrier

; #define PG8_STAGE(bufoff, gbase, voff) do { _Pragma("unroll") for (int _i = 0; _i < 2; ++_i) \
;         __builtin_amdgcn_global_load_lds((const unsigned*)((const char*)(gbase) + (voff)[_i]), (PG8_LAS unsigned*)(lds + (bufoff) + ldsw + _i * 8192), 16, 0, 0); } while (0)
; #define PG8_LDA(dst, b, h) do { _Pragma("unroll") for (int m = 0; m < 4; ++m) _Pragma("unroll") for (int k = 0; k < 2; ++k) dst[m][k] = *(const PG8_LAS bf16x8*)(lds + PG8_SA(b, h) + aoff + m * 2048 + k * 1024); } while (0)
; #define PG8_LDB(dst, b, h) do { _Pragma("unroll") for (int n = 0; n < 2; ++n) _Pragma("unroll") for (int k = 0; k < 2; ++k) dst[n][k] = *(const PG8_LAS bf16x8*)(lds + PG8_SB(b, h) + boff + n * 2048 + k * 1024); } while (0)
; #define PG8_BAR __builtin_amdgcn_s_barrier()
; template <class Epi, class Sched, bool ALIGN_EPI = false, bool SP2 = false>
; __device__ __forceinline__ void gemm_phase(PG8_LAS unsigned char* lds, const Gemm g, const Sched& S, const Epi& E) {
;     ...
;             const bool last = (t == nt - 2);
;             const char* a1 = cA + (size_t)(t + 1) * kstep;
;             const char* a2 = last ? nA : cA + (size_t)(t + 2) * kstep; const char* b2 = last ? nB : cB + (size_t)(t + 2) * kstep;
;             const char* a3 = a2 + kstep; const char* b3 = b2 + kstep;
;             if (last && has_next) S.a_ready(nxt);
;             if constexpr (SP2) {
;             PG8_LDB(B0, 0, 0); PG8_LDB(B1, 0, 1); PG8_SCHED; PG8_LDA(At, 0, 0); PG8_STAGE(PG8_SA(1, 1), a1 + hstep, voffA);
;             PG8_WAIT_V(8); PG8_WAIT_L(0); PG8_BAR; PG8_MMA(0, 0, At, B0); PG8_MMA(0, 1, At, B1); PG8_BAR; PG8_SCHED;
;             PG8_LDA(At, 0, 1); PG8_STAGE(PG8_SB(0, 0), b2, voffB); PG8_STAGE(PG8_SB(0, 1), b2 + hstep, voffB); PG8_STAGE(PG8_SA(0, 0), a2, voffA);
;             PG8_WAIT_V(8); PG8_WAIT_L(0); PG8_BAR; PG8_MMA(1, 0, At, B0); PG8_MMA(1, 1, At, B1); PG8_BAR; PG8_SCHED;
;             PG8_LDB(B0, 1, 0); PG8_LDB(B1, 1, 1); PG8_SCHED; PG8_LDA(At, 1, 0); PG8_STAGE(PG8_SA(0, 1), a2 + hstep, voffA);
;             PG8_WAIT_V(8); PG8_WAIT_L(0); PG8_BAR; PG8_MMA(0, 0, At, B0); PG8_MMA(0, 1, At, B1); PG8_BAR; PG8_SCHED;
;             PG8_LDA(At, 1, 1); PG8_STAGE(PG8_SB(1, 0), b3, voffB); PG8_STAGE(PG8_SB(1, 1), b3 + hstep, voffB); PG8_STAGE(PG8_SA(1, 0), a3, voffA);
;             PG8_WAIT_V(8); PG8_WAIT_L(0); PG8_BAR; PG8_MMA(1, 0, At, B0); PG8_MMA(1, 1, At, B1); PG8_BAR; PG8_SCHED;
.LBB0_177:
	ds_read_b128 v[80:83], v171
	ds_read_b128 v[84:87], v171 offset:1024
	ds_read_b128 v[92:95], v171 offset:2048
	ds_read_b128 v[100:103], v171 offset:3072
	ds_read_b128 v[144:147], v206
	ds_read_b128 v[148:151], v206 offset:1024
	ds_read_b128 v[152:155], v206 offset:2048
	ds_read_b128 v[156:159], v206 offset:3072
	s_add_u32 s28, s72, 0xffea0080
	s_addc_u32 s29, s73, -1
	s_cmpk_eq_i32 s76, 0x54
	s_cselect_b32 s49, s69, s29
	s_cselect_b32 s48, s68, s28
	s_cselect_b32 s29, s71, s35
	s_cselect_b32 s28, s70, s34
	v_lshl_add_u64 v[234:235], s[72:73], 0, v[174:175]
	s_add_i32 m0, s40, 0xc000
	ds_read_b128 v[180:183], v207
	ds_read_b128 v[184:187], v207 offset:1024
	ds_read_b128 v[210:213], v207 offset:2048
	ds_read_b128 v[214:217], v207 offset:3072
	ds_read_b128 v[218:221], v207 offset:4096
	ds_read_b128 v[222:225], v207 offset:5120
	ds_read_b128 v[226:229], v207 offset:6144
	ds_read_b128 v[230:233], v207 offset:7168
	global_load_lds_dwordx4 v[234:235], off
	v_lshl_add_u64 v[234:235], s[72:73], 0, v[176:177]
	s_add_i32 m0, s40, 0xe000
	s_nop 0
	global_load_lds_dwordx4 v[234:235], off
	s_waitcnt vmcnt(8)
	s_waitcnt lgkmcnt(0)
	s_barrier
	s_setprio 1
	s_waitcnt lgkmcnt(0)
	v_mfma_f32_16x16x32_bf16 v[140:143], v[80:83], v[180:183], v[140:143]
	v_mfma_f32_16x16x32_bf16 v[140:143], v[84:87], v[184:187], v[140:143]
	v_mfma_f32_16x16x32_bf16 v[136:139], v[100:103], v[184:187], v[136:139]
	v_mfma_f32_16x16x32_bf16 v[136:139], v[92:95], v[180:183], v[136:139]
	v_mfma_f32_16x16x32_bf16 v[120:123], v[92:95], v[210:213], v[120:123]
	v_mfma_f32_16x16x32_bf16 v[120:123], v[100:103], v[214:217], v[120:123]
	v_mfma_f32_16x16x32_bf16 v[124:127], v[84:87], v[214:217], v[124:127]
	v_mfma_f32_16x16x32_bf16 v[124:127], v[80:83], v[210:213], v[124:127]
	v_mfma_f32_16x16x32_bf16 v[108:111], v[80:83], v[218:221], v[108:111]
	v_mfma_f32_16x16x32_bf16 v[108:111], v[84:87], v[222:225], v[108:111]
	v_mfma_f32_16x16x32_bf16 v[104:107], v[100:103], v[222:225], v[104:107]
	v_mfma_f32_16x16x32_bf16 v[104:107], v[92:95], v[218:221], v[104:107]
	v_mfma_f32_16x16x32_bf16 v[72:75], v[92:95], v[226:229], v[72:75]
	v_mfma_f32_16x16x32_bf16 v[72:75], v[100:103], v[230:233], v[72:75]
	v_mfma_f32_16x16x32_bf16 v[76:79], v[84:87], v[230:233], v[76:79]
	v_mfma_f32_16x16x32_bf16 v[76:79], v[80:83], v[226:229], v[76:79]
	s_setprio 0
	s_setprio 1
	v_mfma_f32_16x16x32_bf16 v[132:135], v[144:147], v[180:183], v[132:135]
	v_mfma_f32_16x16x32_bf16 v[132:135], v[148:151], v[184:187], v[132:135]
	v_mfma_f32_16x16x32_bf16 v[128:131], v[156:159], v[184:187], v[128:131]
	v_mfma_f32_16x16x32_bf16 v[128:131], v[152:155], v[180:183], v[128:131]
	v_mfma_f32_16x16x32_bf16 v[112:115], v[152:155], v[210:213], v[112:115]
	v_mfma_f32_16x16x32_bf16 v[112:115], v[156:159], v[214:217], v[112:115]
	v_mfma_f32_16x16x32_bf16 v[116:119], v[148:151], v[214:217], v[116:119]
	v_mfma_f32_16x16x32_bf16 v[116:119], v[144:147], v[210:213], v[116:119]
	v_mfma_f32_16x16x32_bf16 v[96:99], v[144:147], v[218:221], v[96:99]
	v_mfma_f32_16x16x32_bf16 v[96:99], v[148:151], v[222:225], v[96:99]
	v_mfma_f32_16x16x32_bf16 v[88:91], v[156:159], v[222:225], v[88:91]
	v_mfma_f32_16x16x32_bf16 v[88:91], v[152:155], v[218:221], v[88:91]
	v_mfma_f32_16x16x32_bf16 v[64:67], v[152:155], v[226:229], v[64:67]
	v_mfma_f32_16x16x32_bf16 v[64:67], v[156:159], v[230:233], v[64:67]
	s_setprio 2
	s_barrier
	v_mfma_f32_16x16x32_bf16 v[68:71], v[148:151], v[230:233], v[68:71]
	v_mfma_f32_16x16x32_bf16 v[68:71], v[144:147], v[226:229], v[68:71]
	s_setprio 0
	s_add_i32 s77, s61, s13
	v_lshl_add_u64 v[234:235], s[28:29], 0, v[160:161]
	s_mov_b32 m0, s77
	ds_read_b128 v[180:183], v207 offset:16384
	ds_read_b128 v[184:187], v207 offset:17408
	ds_read_b128 v[210:213], v207 offset:18432
	ds_read_b128 v[214:217], v207 offset:19456
	ds_read_b128 v[218:221], v207 offset:20480
	ds_read_b128 v[222:225], v207 offset:21504
	ds_read_b128 v[226:229], v207 offset:22528
	ds_read_b128 v[230:233], v207 offset:23552
	global_load_lds_dwordx4 v[234:235], off
	s_add_i32 m0, s77, 0x2000
	s_add_u32 s78, s28, 0x160000
	v_lshl_add_u64 v[236:237], s[28:29], 0, v[162:163]
	s_addc_u32 s79, s29, 0
	s_add_i32 s77, s62, s13
	global_load_lds_dwordx4 v[236:237], off
	v_lshl_add_u64 v[238:239], s[78:79], 0, v[160:161]
	s_mov_b32 m0, s77
	v_lshl_add_u64 v[240:241], s[48:49], 0, v[162:163]
	global_load_lds_dwordx4 v[238:239], off
	v_lshl_add_u64 v[238:239], s[78:79], 0, v[162:163]
	s_add_i32 m0, s77, 0x2000
	s_nop 0
	global_load_lds_dwordx4 v[238:239], off
	v_lshl_add_u64 v[238:239], s[48:49], 0, v[160:161]
	s_mov_b32 m0, s40
	s_nop 0
	global_load_lds_dwordx4 v[238:239], off
	s_mov_b32 m0, s41
	s_nop 0
	global_load_lds_dwordx4 v[240:241], off
	s_waitcnt vmcnt(8)
	s_waitcnt lgkmcnt(0)
	s_barrier
; #define PG8_STAGE(bufoff, gbase, voff) do { _Pragma("unroll") for (int _i = 0; _i < 2; ++_i) \
;         __builtin_amdgcn_global_load_lds((const unsigned*)((const char*)(gbase) + (voff)[_i]), (PG8_LAS unsigned*)(lds + (bufoff) + ldsw + _i * 8192), 16, 0, 0); } while (0)
; #define PG8_LDA(dst, b, h) do { _Pragma("unroll") for (int m = 0; m < 4; ++m) _Pragma("unroll") for (int k = 0; k < 2; ++k) dst[m][k] = *(const PG8_LAS bf16x8*)(lds + PG8_SA(b, h) + aoff + m * 2048 + k * 1024); } while (0)
; #define PG8_LDB(dst, b, h) do { _Pragma("unroll") for (int n = 0; n < 2; ++n) _Pragma("unroll") for (int k = 0; k < 2; ++k) dst[n][k] = *(const PG8_LAS bf16x8*)(lds + PG8_SB(b, h) + boff + n * 2048 + k * 1024); } while (0)
; #define PG8_MMA(ai, bj, At, Bt) do { __builtin_amdgcn_s_setprio(1); _Pragma("unroll") for (int m = 0; m < 4; ++m) _Pragma("unroll") for (int n = 0; n < 2; ++n) _Pragma("unroll") for (int k = 0; k < 2; ++k) \
;         acc[ai][bj][m][n] = __builtin_amdgcn_mfma_f32_16x16x32_bf16(Bt[n][k], At[m][k], acc[ai][bj][m][n], 0, 0, 0); __builtin_amdgcn_s_setprio(0); } while (0)
; #define PG8_WAIT_V(n) asm volatile("s_waitcnt vmcnt(" #n ")" ::: "memory")
; #define PG8_WAIT_L(n) asm volatile("s_waitcnt lgkmcnt(" #n ")" ::: "memory")
; #define PG8_BAR __builtin_amdgcn_s_barrier()
; #define PG8_SCHED __builtin_amdgcn_sched_barrier(0)
; template <class Epi, class Sched, bool ALIGN_EPI = false, bool SP2 = false>
; __device__ __forceinline__ void gemm_phase(PG8_LAS unsigned char* lds, const Gemm g, const Sched& S, const Epi& E) {
;     ...
;             PG8_WAIT_V(8); PG8_WAIT_L(0); PG8_BAR; PG8_MMA(1, 0, At, B0); PG8_MMA(1, 1, At, B1); PG8_BAR; PG8_SCHED;
;             PG8_LDB(B0, 1, 0); PG8_LDB(B1, 1, 1); PG8_SCHED; PG8_LDA(At, 1, 0); PG8_STAGE(PG8_SA(0, 1), a2 + hstep, voffA);
;             PG8_WAIT_V(8); PG8_WAIT_L(0); PG8_BAR; PG8_MMA(0, 0, At, B0); PG8_MMA(0, 1, At, B1); PG8_BAR; PG8_SCHED;
	s_setprio 1
	s_waitcnt lgkmcnt(0)
	v_mfma_f32_16x16x32_bf16 v[60:63], v[80:83], v[180:183], v[60:63]
	v_mfma_f32_16x16x32_bf16 v[60:63], v[84:87], v[184:187], v[60:63]
	v_mfma_f32_16x16x32_bf16 v[56:59], v[100:103], v[184:187], v[56:59]
	v_mfma_f32_16x16x32_bf16 v[56:59], v[92:95], v[180:183], v[56:59]
	v_mfma_f32_16x16x32_bf16 v[40:43], v[92:95], v[210:213], v[40:43]
	v_mfma_f32_16x16x32_bf16 v[40:43], v[100:103], v[214:217], v[40:43]
	v_mfma_f32_16x16x32_bf16 v[44:47], v[84:87], v[214:217], v[44:47]
	v_mfma_f32_16x16x32_bf16 v[44:47], v[80:83], v[210:213], v[44:47]
	v_mfma_f32_16x16x32_bf16 v[28:31], v[80:83], v[218:221], v[28:31]
	v_mfma_f32_16x16x32_bf16 v[28:31], v[84:87], v[222:225], v[28:31]
	v_mfma_f32_16x16x32_bf16 v[24:27], v[100:103], v[222:225], v[24:27]
	v_mfma_f32_16x16x32_bf16 v[24:27], v[92:95], v[218:221], v[24:27]
	v_mfma_f32_16x16x32_bf16 v[8:11], v[92:95], v[226:229], v[8:11]
	v_mfma_f32_16x16x32_bf16 v[8:11], v[100:103], v[230:233], v[8:11]
	v_mfma_f32_16x16x32_bf16 v[12:15], v[84:87], v[230:233], v[12:15]
	v_mfma_f32_16x16x32_bf16 v[12:15], v[80:83], v[226:229], v[12:15]
	s_setprio 0
	s_setprio 1
	v_mfma_f32_16x16x32_bf16 v[52:55], v[144:147], v[180:183], v[52:55]
	v_mfma_f32_16x16x32_bf16 v[52:55], v[148:151], v[184:187], v[52:55]
	v_mfma_f32_16x16x32_bf16 v[48:51], v[156:159], v[184:187], v[48:51]
	v_mfma_f32_16x16x32_bf16 v[48:51], v[152:155], v[180:183], v[48:51]
	v_mfma_f32_16x16x32_bf16 v[32:35], v[152:155], v[210:213], v[32:35]
	v_mfma_f32_16x16x32_bf16 v[32:35], v[156:159], v[214:217], v[32:35]
	v_mfma_f32_16x16x32_bf16 v[36:39], v[148:151], v[214:217], v[36:39]
	v_mfma_f32_16x16x32_bf16 v[36:39], v[144:147], v[210:213], v[36:39]
	v_mfma_f32_16x16x32_bf16 v[20:23], v[144:147], v[218:221], v[20:23]
	v_mfma_f32_16x16x32_bf16 v[20:23], v[148:151], v[222:225], v[20:23]
	v_mfma_f32_16x16x32_bf16 v[16:19], v[156:159], v[222:225], v[16:19]
	v_mfma_f32_16x16x32_bf16 v[16:19], v[152:155], v[218:221], v[16:19]
	v_mfma_f32_16x16x32_bf16 v[0:3], v[152:155], v[226:229], v[0:3]
	v_mfma_f32_16x16x32_bf16 v[0:3], v[156:159], v[230:233], v[0:3]
	s_setprio 2
	s_barrier
	v_mfma_f32_16x16x32_bf16 v[4:7], v[148:151], v[230:233], v[4:7]
	v_mfma_f32_16x16x32_bf16 v[4:7], v[144:147], v[226:229], v[4:7]
	s_setprio 0
	s_add_i32 s77, 0, 0x18000
	s_add_i32 s78, 0, 0x1c000
	v_add_u32_e32 v100, s77, v167
	v_add_u32_e32 v156, s78, v167
	ds_read_b128 v[80:83], v100
	ds_read_b128 v[84:87], v100 offset:1024
	ds_read_b128 v[92:95], v100 offset:2048
	ds_read_b128 v[100:103], v100 offset:3072
	ds_read_b128 v[144:147], v156
	ds_read_b128 v[148:151], v156 offset:1024
	ds_read_b128 v[152:155], v156 offset:2048
	ds_read_b128 v[156:159], v156 offset:3072
	s_add_u32 s48, s48, 0x160000
	s_addc_u32 s49, s49, 0
	s_mov_b32 m0, s44
	v_lshl_add_u64 v[242:243], s[48:49], 0, v[160:161]
	ds_read_b128 v[180:183], v207 offset:32768
	ds_read_b128 v[184:187], v207 offset:33792
	ds_read_b128 v[210:213], v207 offset:34816
	ds_read_b128 v[214:217], v207 offset:35840
	ds_read_b128 v[218:221], v207 offset:36864
	ds_read_b128 v[222:225], v207 offset:37888
	ds_read_b128 v[226:229], v207 offset:38912
	ds_read_b128 v[230:233], v207 offset:39936
	global_load_lds_dwordx4 v[242:243], off
	v_lshl_add_u64 v[242:243], s[48:49], 0, v[162:163]
	s_mov_b32 m0, s45
	s_nop 0
	global_load_lds_dwordx4 v[242:243], off
	s_waitcnt vmcnt(8)
	s_waitcnt lgkmcnt(0)
	s_barrier
	s_setprio 1
	s_waitcnt lgkmcnt(0)
	v_mfma_f32_16x16x32_bf16 v[140:143], v[80:83], v[180:183], v[140:143]
	v_mfma_f32_16x16x32_bf16 v[140:143], v[84:87], v[184:187], v[140:143]
	v_mfma_f32_16x16x32_bf16 v[136:139], v[100:103], v[184:187], v[136:139]
	v_mfma_f32_16x16x32_bf16 v[136:139], v[92:95], v[180:183], v[136:139]
	v_mfma_f32_16x16x32_bf16 v[120:123], v[92:95], v[210:213], v[120:123]
	v_mfma_f32_16x16x32_bf16 v[120:123], v[100:103], v[214:217], v[120:123]
	v_mfma_f32_16x16x32_bf16 v[124:127], v[84:87], v[214:217], v[124:127]
	v_mfma_f32_16x16x32_bf16 v[124:127], v[80:83], v[210:213], v[124:127]
	v_mfma_f32_16x16x32_bf16 v[108:111], v[80:83], v[218:221], v[108:111]
	v_mfma_f32_16x16x32_bf16 v[108:111], v[84:87], v[222:225], v[108:111]
	v_mfma_f32_16x16x32_bf16 v[104:107], v[100:103], v[222:225], v[104:107]
	v_mfma_f32_16x16x32_bf16 v[104:107], v[92:95], v[218:221], v[104:107]
	v_mfma_f32_16x16x32_bf16 v[72:75], v[92:95], v[226:229], v[72:75]
	v_mfma_f32_16x16x32_bf16 v[72:75], v[100:103], v[230:233], v[72:75]
	v_mfma_f32_16x16x32_bf16 v[76:79], v[84:87], v[230:233], v[76:79]
	v_mfma_f32_16x16x32_bf16 v[76:79], v[80:83], v[226:229], v[76:79]
	s_setprio 0
	s_setprio 1
	v_mfma_f32_16x16x32_bf16 v[132:135], v[144:147], v[180:183], v[132:135]
	v_mfma_f32_16x16x32_bf16 v[132:135], v[148:151], v[184:187], v[132:135]
	v_mfma_f32_16x16x32_bf16 v[128:131], v[156:159], v[184:187], v[128:131]
	v_mfma_f32_16x16x32_bf16 v[128:131], v[152:155], v[180:183], v[128:131]
	v_mfma_f32_16x16x32_bf16 v[112:115], v[152:155], v[210:213], v[112:115]
	v_mfma_f32_16x16x32_bf16 v[112:115], v[156:159], v[214:217], v[112:115]
	v_mfma_f32_16x16x32_bf16 v[116:119], v[148:151], v[214:217], v[116:119]
	v_mfma_f32_16x16x32_bf16 v[116:119], v[144:147], v[210:213], v[116:119]
	v_mfma_f32_16x16x32_bf16 v[96:99], v[144:147], v[218:221], v[96:99]
	v_mfma_f32_16x16x32_bf16 v[96:99], v[148:151], v[222:225], v[96:99]
	v_mfma_f32_16x16x32_bf16 v[88:91], v[156:159], v[222:225], v[88:91]
	v_mfma_f32_16x16x32_bf16 v[88:91], v[152:155], v[218:221], v[88:91]
	v_mfma_f32_16x16x32_bf16 v[64:67], v[152:155], v[226:229], v[64:67]
	v_mfma_f32_16x16x32_bf16 v[64:67], v[156:159], v[230:233], v[64:67]
	s_setprio 2
	s_barrier
; #define PG8_STAGE(bufoff, gbase, voff) do { _Pragma("unroll") for (int _i = 0; _i < 2; ++_i) \
;         __builtin_amdgcn_global_load_lds((const unsigned*)((const char*)(gbase) + (voff)[_i]), (PG8_LAS unsigned*)(lds + (bufoff) + ldsw + _i * 8192), 16, 0, 0); } while (0)
; #define PG8_LDA(dst, b, h) do { _Pragma("unroll") for (int m = 0; m < 4; ++m) _Pragma("unroll") for (int k = 0; k < 2; ++k) dst[m][k] = *(const PG8_LAS bf16x8*)(lds + PG8_SA(b, h) + aoff + m * 2048 + k * 1024); } while (0)
; #define PG8_MMA(ai, bj, At, Bt) do { __builtin_amdgcn_s_setprio(1); _Pragma("unroll") for (int m = 0; m < 4; ++m) _Pragma("unroll") for (int n = 0; n < 2; ++n) _Pragma("unroll") for (int k = 0; k < 2; ++k) \
;         acc[ai][bj][m][n] = __builtin_amdgcn_mfma_f32_16x16x32_bf16(Bt[n][k], At[m][k], acc[ai][bj][m][n], 0, 0, 0); __builtin_amdgcn_s_setprio(0); } while (0)
; #define PG8_WAIT_V(n) asm volatile("s_waitcnt vmcnt(" #n ")" ::: "memory")
; #define PG8_WAIT_L(n) asm volatile("s_waitcnt lgkmcnt(" #n ")" ::: "memory")
; #define PG8_BAR __builtin_amdgcn_s_barrier()
; #define PG8_SCHED __builtin_amdgcn_sched_barrier(0)
; template <class Epi, class Sched, bool ALIGN_EPI = false, bool SP2 = false>
; __device__ __forceinline__ void gemm_phase(PG8_LAS unsigned char* lds, const Gemm g, const Sched& S, const Epi& E) {
;     ...
;             PG8_LDA(At, 1, 1); PG8_STAGE(PG8_SB(1, 0), b3, voffB); PG8_STAGE(PG8_SB(1, 1), b3 + hstep, voffB); PG8_STAGE(PG8_SA(1, 0), a3, voffA);
;             PG8_WAIT_V(8); PG8_WAIT_L(0); PG8_BAR; PG8_MMA(1, 0, At, B0); PG8_MMA(1, 1, At, B1); PG8_BAR; PG8_SCHED;
;     ...
;         if constexpr (ALIGN_EPI) { if (wr == 0) PG8_BAR; }
;         if constexpr (!Epi::AFTER_DRAIN) { E(acc, cur, wr, wc, fr, fq); S.done(cur); }
;         if (!has_next) break;
	v_mfma_f32_16x16x32_bf16 v[68:71], v[148:151], v[230:233], v[68:71]
	v_mfma_f32_16x16x32_bf16 v[68:71], v[144:147], v[226:229], v[68:71]
	s_setprio 0
	s_add_i32 s48, s77, s13
	v_lshl_add_u64 v[234:235], v[234:235], 0, s[50:51]
	s_mov_b32 m0, s48
	ds_read_b128 v[180:183], v207 offset:49152
	ds_read_b128 v[184:187], v207 offset:50176
	ds_read_b128 v[210:213], v207 offset:51200
	ds_read_b128 v[214:217], v207 offset:52224
	ds_read_b128 v[218:221], v207 offset:53248
	ds_read_b128 v[222:225], v207 offset:54272
	ds_read_b128 v[226:229], v207 offset:55296
	ds_read_b128 v[230:233], v207 offset:56320
	global_load_lds_dwordx4 v[234:235], off
	s_add_i32 m0, s48, 0x2000
	s_add_u32 s28, s28, 0x160080
	v_lshl_add_u64 v[234:235], v[236:237], 0, s[50:51]
	s_addc_u32 s29, s29, 0
	s_add_i32 s48, s78, s13
	global_load_lds_dwordx4 v[234:235], off
	v_lshl_add_u64 v[234:235], s[28:29], 0, v[160:161]
	s_mov_b32 m0, s48
	s_nop 0
	global_load_lds_dwordx4 v[234:235], off
	v_lshl_add_u64 v[234:235], s[28:29], 0, v[162:163]
	s_add_i32 m0, s48, 0x2000
	s_nop 0
	global_load_lds_dwordx4 v[234:235], off
	v_lshl_add_u64 v[234:235], v[238:239], 0, s[50:51]
	s_mov_b32 m0, s56
	s_nop 0
	global_load_lds_dwordx4 v[234:235], off
	v_lshl_add_u64 v[234:235], v[240:241], 0, s[50:51]
	s_mov_b32 m0, s57
	s_nop 0
	global_load_lds_dwordx4 v[234:235], off
	s_waitcnt vmcnt(8)
	s_waitcnt lgkmcnt(0)
	s_barrier
	s_setprio 1
	s_waitcnt lgkmcnt(0)
	v_mfma_f32_16x16x32_bf16 v[60:63], v[80:83], v[180:183], v[60:63]
	v_mfma_f32_16x16x32_bf16 v[60:63], v[84:87], v[184:187], v[60:63]
	v_mfma_f32_16x16x32_bf16 v[56:59], v[100:103], v[184:187], v[56:59]
	v_mfma_f32_16x16x32_bf16 v[56:59], v[92:95], v[180:183], v[56:59]
	v_mfma_f32_16x16x32_bf16 v[40:43], v[92:95], v[210:213], v[40:43]
	v_mfma_f32_16x16x32_bf16 v[40:43], v[100:103], v[214:217], v[40:43]
	v_mfma_f32_16x16x32_bf16 v[44:47], v[84:87], v[214:217], v[44:47]
	v_mfma_f32_16x16x32_bf16 v[44:47], v[80:83], v[210:213], v[44:47]
	v_mfma_f32_16x16x32_bf16 v[28:31], v[80:83], v[218:221], v[28:31]
	v_mfma_f32_16x16x32_bf16 v[28:31], v[84:87], v[222:225], v[28:31]
	v_mfma_f32_16x16x32_bf16 v[24:27], v[100:103], v[222:225], v[24:27]
	v_mfma_f32_16x16x32_bf16 v[24:27], v[92:95], v[218:221], v[24:27]
	v_mfma_f32_16x16x32_bf16 v[8:11], v[92:95], v[226:229], v[8:11]
	v_mfma_f32_16x16x32_bf16 v[8:11], v[100:103], v[230:233], v[8:11]
	v_mfma_f32_16x16x32_bf16 v[12:15], v[84:87], v[230:233], v[12:15]
	v_mfma_f32_16x16x32_bf16 v[12:15], v[80:83], v[226:229], v[12:15]
	s_setprio 0
	s_setprio 1
	v_mfma_f32_16x16x32_bf16 v[52:55], v[144:147], v[180:183], v[52:55]
	v_mfma_f32_16x16x32_bf16 v[52:55], v[148:151], v[184:187], v[52:55]
	v_mfma_f32_16x16x32_bf16 v[48:51], v[156:159], v[184:187], v[48:51]
	v_mfma_f32_16x16x32_bf16 v[48:51], v[152:155], v[180:183], v[48:51]
	v_mfma_f32_16x16x32_bf16 v[32:35], v[152:155], v[210:213], v[32:35]
	v_mfma_f32_16x16x32_bf16 v[32:35], v[156:159], v[214:217], v[32:35]
	v_mfma_f32_16x16x32_bf16 v[36:39], v[148:151], v[214:217], v[36:39]
	v_mfma_f32_16x16x32_bf16 v[36:39], v[144:147], v[210:213], v[36:39]
	v_mfma_f32_16x16x32_bf16 v[20:23], v[144:147], v[218:221], v[20:23]
	v_mfma_f32_16x16x32_bf16 v[20:23], v[148:151], v[222:225], v[20:23]
	v_mfma_f32_16x16x32_bf16 v[16:19], v[156:159], v[222:225], v[16:19]
	v_mfma_f32_16x16x32_bf16 v[16:19], v[152:155], v[218:221], v[16:19]
	v_mfma_f32_16x16x32_bf16 v[0:3], v[152:155], v[226:229], v[0:3]
	v_mfma_f32_16x16x32_bf16 v[0:3], v[156:159], v[230:233], v[0:3]
	s_setprio 2
	s_barrier
	v_mfma_f32_16x16x32_bf16 v[4:7], v[148:151], v[230:233], v[4:7]
	v_mfma_f32_16x16x32_bf16 v[4:7], v[144:147], v[226:229], v[4:7]
	s_setprio 0
	s_add_i32 s76, s76, 2
	s_add_u32 s72, s72, 0x100
	s_addc_u32 s73, s73, 0
	s_add_u32 s34, s34, 0x100
	s_addc_u32 s35, s35, 0
	s_cmpk_gt_u32 s76, 0x55
	s_cbranch_scc0 .LBB0_177
	s_and_b64 vcc, exec, s[52:53]
	s_cbranch_vccz .LBB0_180
	s_barrier

; #define PG8_STAGE(bufoff, gbase, voff) do { _Pragma("unroll") for (int _i = 0; _i < 2; ++_i) \
;         __builtin_amdgcn_global_load_lds((const unsigned*)((const char*)(gbase) + (voff)[_i]), (PG8_LAS unsigned*)(lds + (bufoff) + ldsw + _i * 8192), 16, 0, 0); } while (0)
; #define PG8_LDA(dst, b, h) do { _Pragma("unroll") for (int m = 0; m < 4; ++m) _Pragma("unroll") for (int k = 0; k < 2; ++k) dst[m][k] = *(const PG8_LAS bf16x8*)(lds + PG8_SA(b, h) + aoff + m * 2048 + k * 1024); } while (0)
; #define PG8_LDB(dst, b, h) do { _Pragma("unroll") for (int n = 0; n < 2; ++n) _Pragma("unroll") for (int k = 0; k < 2; ++k) dst[n][k] = *(const PG8_LAS bf16x8*)(lds + PG8_SB(b, h) + boff + n * 2048 + k * 1024); } while (0)
; #define PG8_MMA(ai, bj, At, Bt) do { __builtin_amdgcn_s_setprio(1); _Pragma("unroll") for (int m = 0; m < 4; ++m) _Pragma("unroll") for (int n = 0; n < 2; ++n) _Pragma("unroll") for (int k = 0; k < 2; ++k) \
;         acc[ai][bj][m][n] = __builtin_amdgcn_mfma_f32_16x16x32_bf16(Bt[n][k], At[m][k], acc[ai][bj][m][n], 0, 0, 0); __builtin_amdgcn_s_setprio(0); } while (0)
; #define PG8_WAIT_V(n) asm volatile("s_waitcnt vmcnt(" #n ")" ::: "memory")
; #define PG8_WAIT_L(n) asm volatile("s_waitcnt lgkmcnt(" #n ")" ::: "memory")
; #define PG8_BAR __builtin_amdgcn_s_barrier()
; #define PG8_SCHED __builtin_amdgcn_sched_barrier(0)
; template <class Epi, class Sched, bool ALIGN_EPI = false, bool SP2 = false>
; __device__ __forceinline__ void gemm_phase(PG8_LAS unsigned char* lds, const Gemm g, const Sched& S, const Epi& E) {
;     ...
;             const bool last = (t == nt - 2);
;             const char* a1 = cA + (size_t)(t + 1) * kstep;
;             const char* a2 = last ? nA : cA + (size_t)(t + 2) * kstep; const char* b2 = last ? nB : cB + (size_t)(t + 2) * kstep;
;             const char* a3 = a2 + kstep; const char* b3 = b2 + kstep;
;             if (last && has_next) S.a_ready(nxt);
;             if constexpr (SP2) {
;             PG8_LDB(B0, 0, 0); PG8_LDB(B1, 0, 1); PG8_SCHED; PG8_LDA(At, 0, 0); PG8_STAGE(PG8_SA(1, 1), a1 + hstep, voffA);
;             PG8_WAIT_V(8); PG8_WAIT_L(0); PG8_BAR; PG8_MMA(0, 0, At, B0); PG8_MMA(0, 1, At, B1); PG8_BAR; PG8_SCHED;
;             PG8_LDA(At, 0, 1); PG8_STAGE(PG8_SB(0, 0), b2, voffB); PG8_STAGE(PG8_SB(0, 1), b2 + hstep, voffB); PG8_STAGE(PG8_SA(0, 0), a2, voffA);
.LBB0_231:
	ds_read_b128 v[142:145], v153
	ds_read_b128 v[146:149], v153 offset:1024
	ds_read_b128 v[174:177], v153 offset:2048
	ds_read_b128 v[178:181], v153 offset:3072
	ds_read_b128 v[182:185], v154
	ds_read_b128 v[206:209], v154 offset:1024
	ds_read_b128 v[210:213], v154 offset:2048
	ds_read_b128 v[214:217], v154 offset:3072
	s_add_u32 s28, s84, 0xfff80080
	s_addc_u32 s29, s85, -1
	s_cmp_eq_u32 s97, 28
	s_cselect_b32 s49, s34, s29
	s_cselect_b32 s48, s35, s28
	s_cselect_b32 s29, s75, s96
	s_cselect_b32 s28, s77, s95
	v_lshl_add_u64 v[158:159], s[84:85], 0, v[134:135]
	s_add_i32 m0, s56, 0xc000
	ds_read_b128 v[218:221], v155
	ds_read_b128 v[222:225], v155 offset:1024
	ds_read_b128 v[226:229], v155 offset:2048
	ds_read_b128 v[230:233], v155 offset:3072
	ds_read_b128 v[234:237], v155 offset:4096
	ds_read_b128 v[238:241], v155 offset:5120
	ds_read_b128 v[242:245], v155 offset:6144
	ds_read_b128 v[246:249], v155 offset:7168
	global_load_lds_dwordx4 v[158:159], off
	v_lshl_add_u64 v[158:159], s[84:85], 0, v[136:137]
	s_add_i32 m0, s56, 0xe000
	s_nop 0
	global_load_lds_dwordx4 v[158:159], off
	s_waitcnt vmcnt(8)
	s_waitcnt lgkmcnt(0)
	s_barrier
	s_setprio 1
	s_waitcnt lgkmcnt(0)
	v_mfma_f32_16x16x32_bf16 v[124:127], v[142:145], v[218:221], v[124:127]
	v_mfma_f32_16x16x32_bf16 v[124:127], v[146:149], v[222:225], v[124:127]
	v_mfma_f32_16x16x32_bf16 v[120:123], v[178:181], v[222:225], v[120:123]
	v_mfma_f32_16x16x32_bf16 v[120:123], v[174:177], v[218:221], v[120:123]
	v_mfma_f32_16x16x32_bf16 v[104:107], v[174:177], v[226:229], v[104:107]
	v_mfma_f32_16x16x32_bf16 v[104:107], v[178:181], v[230:233], v[104:107]
	v_mfma_f32_16x16x32_bf16 v[108:111], v[146:149], v[230:233], v[108:111]
	v_mfma_f32_16x16x32_bf16 v[108:111], v[142:145], v[226:229], v[108:111]
	v_mfma_f32_16x16x32_bf16 v[92:95], v[142:145], v[234:237], v[92:95]
	v_mfma_f32_16x16x32_bf16 v[92:95], v[146:149], v[238:241], v[92:95]
	v_mfma_f32_16x16x32_bf16 v[88:91], v[178:181], v[238:241], v[88:91]
	v_mfma_f32_16x16x32_bf16 v[88:91], v[174:177], v[234:237], v[88:91]
	v_mfma_f32_16x16x32_bf16 v[72:75], v[174:177], v[242:245], v[72:75]
	v_mfma_f32_16x16x32_bf16 v[72:75], v[178:181], v[246:249], v[72:75]
	v_mfma_f32_16x16x32_bf16 v[76:79], v[146:149], v[246:249], v[76:79]
	v_mfma_f32_16x16x32_bf16 v[76:79], v[142:145], v[242:245], v[76:79]
	s_setprio 0
	s_setprio 1
	v_mfma_f32_16x16x32_bf16 v[116:119], v[182:185], v[218:221], v[116:119]
	v_mfma_f32_16x16x32_bf16 v[116:119], v[206:209], v[222:225], v[116:119]
	v_mfma_f32_16x16x32_bf16 v[112:115], v[214:217], v[222:225], v[112:115]
	v_mfma_f32_16x16x32_bf16 v[112:115], v[210:213], v[218:221], v[112:115]
	v_mfma_f32_16x16x32_bf16 v[96:99], v[210:213], v[226:229], v[96:99]
	v_mfma_f32_16x16x32_bf16 v[96:99], v[214:217], v[230:233], v[96:99]
	v_mfma_f32_16x16x32_bf16 v[100:103], v[206:209], v[230:233], v[100:103]
	v_mfma_f32_16x16x32_bf16 v[100:103], v[182:185], v[226:229], v[100:103]
	v_mfma_f32_16x16x32_bf16 v[84:87], v[182:185], v[234:237], v[84:87]
	v_mfma_f32_16x16x32_bf16 v[84:87], v[206:209], v[238:241], v[84:87]
	v_mfma_f32_16x16x32_bf16 v[80:83], v[214:217], v[238:241], v[80:83]
	v_mfma_f32_16x16x32_bf16 v[80:83], v[210:213], v[234:237], v[80:83]
	v_mfma_f32_16x16x32_bf16 v[64:67], v[210:213], v[242:245], v[64:67]
	v_mfma_f32_16x16x32_bf16 v[64:67], v[214:217], v[246:249], v[64:67]
	s_setprio 2
	s_barrier
	v_mfma_f32_16x16x32_bf16 v[68:71], v[206:209], v[246:249], v[68:71]
	v_mfma_f32_16x16x32_bf16 v[68:71], v[182:185], v[242:245], v[68:71]
	s_setprio 0
	s_add_i32 vcc_lo, s83, s13
	v_lshl_add_u64 v[158:159], s[28:29], 0, v[166:167]
	s_mov_b32 m0, vcc_lo
	ds_read_b128 v[218:221], v155 offset:16384
	ds_read_b128 v[222:225], v155 offset:17408
	ds_read_b128 v[226:229], v155 offset:18432
	ds_read_b128 v[230:233], v155 offset:19456
	ds_read_b128 v[234:237], v155 offset:20480
	ds_read_b128 v[238:241], v155 offset:21504
	ds_read_b128 v[242:245], v155 offset:22528
	ds_read_b128 v[246:249], v155 offset:23552
	global_load_lds_dwordx4 v[158:159], off
	s_add_i32 m0, vcc_lo, 0x2000
	s_add_u32 vcc_lo, s28, 0x80000
	v_lshl_add_u64 v[186:187], s[28:29], 0, v[170:171]
	s_addc_u32 vcc_hi, s29, 0
	s_add_i32 s44, s90, s13
	global_load_lds_dwordx4 v[186:187], off
	v_lshl_add_u64 v[250:251], vcc, 0, v[166:167]
	s_mov_b32 m0, s44
	v_lshl_add_u64 v[252:253], s[48:49], 0, v[168:169]
	global_load_lds_dwordx4 v[250:251], off
	v_lshl_add_u64 v[250:251], vcc, 0, v[170:171]
	s_add_i32 m0, s44, 0x2000
	s_nop 0
	global_load_lds_dwordx4 v[250:251], off
	v_lshl_add_u64 v[250:251], s[48:49], 0, v[164:165]
	s_mov_b32 m0, s56
	s_nop 0
	global_load_lds_dwordx4 v[250:251], off
	s_mov_b32 m0, s57
	s_nop 0
	global_load_lds_dwordx4 v[252:253], off
	s_waitcnt vmcnt(8)
	s_waitcnt lgkmcnt(0)
	s_barrier
; #define PG8_STAGE(bufoff, gbase, voff) do { _Pragma("unroll") for (int _i = 0; _i < 2; ++_i) \
;         __builtin_amdgcn_global_load_lds((const unsigned*)((const char*)(gbase) + (voff)[_i]), (PG8_LAS unsigned*)(lds + (bufoff) + ldsw + _i * 8192), 16, 0, 0); } while (0)
; #define PG8_LDA(dst, b, h) do { _Pragma("unroll") for (int m = 0; m < 4; ++m) _Pragma("unroll") for (int k = 0; k < 2; ++k) dst[m][k] = *(const PG8_LAS bf16x8*)(lds + PG8_SA(b, h) + aoff + m * 2048 + k * 1024); } while (0)
; #define PG8_LDB(dst, b, h) do { _Pragma("unroll") for (int n = 0; n < 2; ++n) _Pragma("unroll") for (int k = 0; k < 2; ++k) dst[n][k] = *(const PG8_LAS bf16x8*)(lds + PG8_SB(b, h) + boff + n * 2048 + k * 1024); } while (0)
; #define PG8_MMA(ai, bj, At, Bt) do { __builtin_amdgcn_s_setprio(1); _Pragma("unroll") for (int m = 0; m < 4; ++m) _Pragma("unroll") for (int n = 0; n < 2; ++n) _Pragma("unroll") for (int k = 0; k < 2; ++k) \
;         acc[ai][bj][m][n] = __builtin_amdgcn_mfma_f32_16x16x32_bf16(Bt[n][k], At[m][k], acc[ai][bj][m][n], 0, 0, 0); __builtin_amdgcn_s_setprio(0); } while (0)
; #define PG8_WAIT_V(n) asm volatile("s_waitcnt vmcnt(" #n ")" ::: "memory")
; #define PG8_WAIT_L(n) asm volatile("s_waitcnt lgkmcnt(" #n ")" ::: "memory")
; #define PG8_BAR __builtin_amdgcn_s_barrier()
; #define PG8_SCHED __builtin_amdgcn_sched_barrier(0)
; template <class Epi, class Sched, bool ALIGN_EPI = false, bool SP2 = false>
; __device__ __forceinline__ void gemm_phase(PG8_LAS unsigned char* lds, const Gemm g, const Sched& S, const Epi& E) {
;     ...
;             PG8_WAIT_V(8); PG8_WAIT_L(0); PG8_BAR; PG8_MMA(1, 0, At, B0); PG8_MMA(1, 1, At, B1); PG8_BAR; PG8_SCHED;
;             PG8_LDB(B0, 1, 0); PG8_LDB(B1, 1, 1); PG8_SCHED; PG8_LDA(At, 1, 0); PG8_STAGE(PG8_SA(0, 1), a2 + hstep, voffA);
;             PG8_WAIT_V(8); PG8_WAIT_L(0); PG8_BAR; PG8_MMA(0, 0, At, B0); PG8_MMA(0, 1, At, B1); PG8_BAR; PG8_SCHED;
	s_setprio 1
	s_waitcnt lgkmcnt(0)
	v_mfma_f32_16x16x32_bf16 v[60:63], v[142:145], v[218:221], v[60:63]
	v_mfma_f32_16x16x32_bf16 v[60:63], v[146:149], v[222:225], v[60:63]
	v_mfma_f32_16x16x32_bf16 v[56:59], v[178:181], v[222:225], v[56:59]
	v_mfma_f32_16x16x32_bf16 v[56:59], v[174:177], v[218:221], v[56:59]
	v_mfma_f32_16x16x32_bf16 v[40:43], v[174:177], v[226:229], v[40:43]
	v_mfma_f32_16x16x32_bf16 v[40:43], v[178:181], v[230:233], v[40:43]
	v_mfma_f32_16x16x32_bf16 v[44:47], v[146:149], v[230:233], v[44:47]
	v_mfma_f32_16x16x32_bf16 v[44:47], v[142:145], v[226:229], v[44:47]
	v_mfma_f32_16x16x32_bf16 v[28:31], v[142:145], v[234:237], v[28:31]
	v_mfma_f32_16x16x32_bf16 v[28:31], v[146:149], v[238:241], v[28:31]
	v_mfma_f32_16x16x32_bf16 v[24:27], v[178:181], v[238:241], v[24:27]
	v_mfma_f32_16x16x32_bf16 v[24:27], v[174:177], v[234:237], v[24:27]
	v_mfma_f32_16x16x32_bf16 v[8:11], v[174:177], v[242:245], v[8:11]
	v_mfma_f32_16x16x32_bf16 v[8:11], v[178:181], v[246:249], v[8:11]
	v_mfma_f32_16x16x32_bf16 v[12:15], v[146:149], v[246:249], v[12:15]
	v_mfma_f32_16x16x32_bf16 v[12:15], v[142:145], v[242:245], v[12:15]
	s_setprio 0
	s_setprio 1
	v_mfma_f32_16x16x32_bf16 v[52:55], v[182:185], v[218:221], v[52:55]
	v_mfma_f32_16x16x32_bf16 v[52:55], v[206:209], v[222:225], v[52:55]
	v_mfma_f32_16x16x32_bf16 v[48:51], v[214:217], v[222:225], v[48:51]
	v_mfma_f32_16x16x32_bf16 v[48:51], v[210:213], v[218:221], v[48:51]
	v_mfma_f32_16x16x32_bf16 v[32:35], v[210:213], v[226:229], v[32:35]
	v_mfma_f32_16x16x32_bf16 v[32:35], v[214:217], v[230:233], v[32:35]
	v_mfma_f32_16x16x32_bf16 v[36:39], v[206:209], v[230:233], v[36:39]
	v_mfma_f32_16x16x32_bf16 v[36:39], v[182:185], v[226:229], v[36:39]
	v_mfma_f32_16x16x32_bf16 v[20:23], v[182:185], v[234:237], v[20:23]
	v_mfma_f32_16x16x32_bf16 v[20:23], v[206:209], v[238:241], v[20:23]
	v_mfma_f32_16x16x32_bf16 v[16:19], v[214:217], v[238:241], v[16:19]
	v_mfma_f32_16x16x32_bf16 v[16:19], v[210:213], v[234:237], v[16:19]
	v_mfma_f32_16x16x32_bf16 v[0:3], v[210:213], v[242:245], v[0:3]
	v_mfma_f32_16x16x32_bf16 v[0:3], v[214:217], v[246:249], v[0:3]
	s_setprio 2
	s_barrier
	v_mfma_f32_16x16x32_bf16 v[4:7], v[206:209], v[246:249], v[4:7]
	v_mfma_f32_16x16x32_bf16 v[4:7], v[182:185], v[242:245], v[4:7]
	s_setprio 0
	s_add_i32 s44, 0, 0x18000
	v_add_u32_e32 v161, s44, v151
	s_add_i32 s45, 0, 0x1c000
	ds_read_b128 v[142:145], v161
	ds_read_b128 v[146:149], v161 offset:1024
	ds_read_b128 v[174:177], v161 offset:2048
	ds_read_b128 v[178:181], v161 offset:3072
	v_add_u32_e32 v161, s45, v151
	ds_read_b128 v[182:185], v161
	ds_read_b128 v[206:209], v161 offset:1024
	ds_read_b128 v[210:213], v161 offset:2048
	ds_read_b128 v[214:217], v161 offset:3072
	s_add_u32 s48, s48, 0x80000
	s_addc_u32 s49, s49, 0
	s_mov_b32 m0, s60
	v_lshl_add_u64 v[200:201], s[48:49], 0, v[164:165]
	ds_read_b128 v[218:221], v155 offset:32768
	ds_read_b128 v[222:225], v155 offset:33792
	ds_read_b128 v[226:229], v155 offset:34816
	ds_read_b128 v[230:233], v155 offset:35840
	ds_read_b128 v[234:237], v155 offset:36864
	ds_read_b128 v[238:241], v155 offset:37888
	ds_read_b128 v[242:245], v155 offset:38912
	ds_read_b128 v[246:249], v155 offset:39936
	global_load_lds_dwordx4 v[200:201], off
	v_lshl_add_u64 v[200:201], s[48:49], 0, v[168:169]
	s_mov_b32 m0, s61
	s_nop 0
	global_load_lds_dwordx4 v[200:201], off
	s_waitcnt vmcnt(8)
	s_waitcnt lgkmcnt(0)
	s_barrier
	s_setprio 1
	s_waitcnt lgkmcnt(0)
	v_mfma_f32_16x16x32_bf16 v[124:127], v[142:145], v[218:221], v[124:127]
	v_mfma_f32_16x16x32_bf16 v[124:127], v[146:149], v[222:225], v[124:127]
	v_mfma_f32_16x16x32_bf16 v[120:123], v[178:181], v[222:225], v[120:123]
	v_mfma_f32_16x16x32_bf16 v[120:123], v[174:177], v[218:221], v[120:123]
	v_mfma_f32_16x16x32_bf16 v[104:107], v[174:177], v[226:229], v[104:107]
	v_mfma_f32_16x16x32_bf16 v[104:107], v[178:181], v[230:233], v[104:107]
	v_mfma_f32_16x16x32_bf16 v[108:111], v[146:149], v[230:233], v[108:111]
	v_mfma_f32_16x16x32_bf16 v[108:111], v[142:145], v[226:229], v[108:111]
	v_mfma_f32_16x16x32_bf16 v[92:95], v[142:145], v[234:237], v[92:95]
	v_mfma_f32_16x16x32_bf16 v[92:95], v[146:149], v[238:241], v[92:95]
	v_mfma_f32_16x16x32_bf16 v[88:91], v[178:181], v[238:241], v[88:91]
	v_mfma_f32_16x16x32_bf16 v[88:91], v[174:177], v[234:237], v[88:91]
	v_mfma_f32_16x16x32_bf16 v[72:75], v[174:177], v[242:245], v[72:75]
	v_mfma_f32_16x16x32_bf16 v[72:75], v[178:181], v[246:249], v[72:75]
	v_mfma_f32_16x16x32_bf16 v[76:79], v[146:149], v[246:249], v[76:79]
	v_mfma_f32_16x16x32_bf16 v[76:79], v[142:145], v[242:245], v[76:79]
	s_setprio 0
	s_setprio 1
	v_mfma_f32_16x16x32_bf16 v[116:119], v[182:185], v[218:221], v[116:119]
	v_mfma_f32_16x16x32_bf16 v[116:119], v[206:209], v[222:225], v[116:119]
	v_mfma_f32_16x16x32_bf16 v[112:115], v[214:217], v[222:225], v[112:115]
	v_mfma_f32_16x16x32_bf16 v[112:115], v[210:213], v[218:221], v[112:115]
	v_mfma_f32_16x16x32_bf16 v[96:99], v[210:213], v[226:229], v[96:99]
	v_mfma_f32_16x16x32_bf16 v[96:99], v[214:217], v[230:233], v[96:99]
	v_mfma_f32_16x16x32_bf16 v[100:103], v[206:209], v[230:233], v[100:103]
	v_mfma_f32_16x16x32_bf16 v[100:103], v[182:185], v[226:229], v[100:103]
	v_mfma_f32_16x16x32_bf16 v[84:87], v[182:185], v[234:237], v[84:87]
	v_mfma_f32_16x16x32_bf16 v[84:87], v[206:209], v[238:241], v[84:87]
	v_mfma_f32_16x16x32_bf16 v[80:83], v[214:217], v[238:241], v[80:83]
	v_mfma_f32_16x16x32_bf16 v[80:83], v[210:213], v[234:237], v[80:83]
	v_mfma_f32_16x16x32_bf16 v[64:67], v[210:213], v[242:245], v[64:67]
	v_mfma_f32_16x16x32_bf16 v[64:67], v[214:217], v[246:249], v[64:67]
	s_setprio 2
	s_barrier
; #define PG8_STAGE(bufoff, gbase, voff) do { _Pragma("unroll") for (int _i = 0; _i < 2; ++_i) \
;         __builtin_amdgcn_global_load_lds((const unsigned*)((const char*)(gbase) + (voff)[_i]), (PG8_LAS unsigned*)(lds + (bufoff) + ldsw + _i * 8192), 16, 0, 0); } while (0)
; #define PG8_LDA(dst, b, h) do { _Pragma("unroll") for (int m = 0; m < 4; ++m) _Pragma("unroll") for (int k = 0; k < 2; ++k) dst[m][k] = *(const PG8_LAS bf16x8*)(lds + PG8_SA(b, h) + aoff + m * 2048 + k * 1024); } while (0)
; #define PG8_MMA(ai, bj, At, Bt) do { __builtin_amdgcn_s_setprio(1); _Pragma("unroll") for (int m = 0; m < 4; ++m) _Pragma("unroll") for (int n = 0; n < 2; ++n) _Pragma("unroll") for (int k = 0; k < 2; ++k) \
;         acc[ai][bj][m][n] = __builtin_amdgcn_mfma_f32_16x16x32_bf16(Bt[n][k], At[m][k], acc[ai][bj][m][n], 0, 0, 0); __builtin_amdgcn_s_setprio(0); } while (0)
; #define PG8_WAIT_V(n) asm volatile("s_waitcnt vmcnt(" #n ")" ::: "memory")
; #define PG8_WAIT_L(n) asm volatile("s_waitcnt lgkmcnt(" #n ")" ::: "memory")
; #define PG8_BAR __builtin_amdgcn_s_barrier()
; #define PG8_SCHED __builtin_amdgcn_sched_barrier(0)
; template <class Epi, class Sched, bool ALIGN_EPI = false, bool SP2 = false>
; __device__ __forceinline__ void gemm_phase(PG8_LAS unsigned char* lds, const Gemm g, const Sched& S, const Epi& E) {
;     ...
;             PG8_LDA(At, 1, 1); PG8_STAGE(PG8_SB(1, 0), b3, voffB); PG8_STAGE(PG8_SB(1, 1), b3 + hstep, voffB); PG8_STAGE(PG8_SA(1, 0), a3, voffA);
;             PG8_WAIT_V(8); PG8_WAIT_L(0); PG8_BAR; PG8_MMA(1, 0, At, B0); PG8_MMA(1, 1, At, B1); PG8_BAR; PG8_SCHED;
;     ...
;         if constexpr (ALIGN_EPI) { if (wr == 0) PG8_BAR; }
;         if constexpr (!Epi::AFTER_DRAIN) { E(acc, cur, wr, wc, fr, fq); S.done(cur); }
;         if (!has_next) break;
	v_mfma_f32_16x16x32_bf16 v[68:71], v[206:209], v[246:249], v[68:71]
	v_mfma_f32_16x16x32_bf16 v[68:71], v[182:185], v[242:245], v[68:71]
	s_setprio 0
	s_add_i32 s44, s44, s13
	v_lshl_add_u64 v[158:159], v[158:159], 0, s[52:53]
	s_mov_b32 m0, s44
	ds_read_b128 v[218:221], v155 offset:49152
	ds_read_b128 v[222:225], v155 offset:50176
	ds_read_b128 v[226:229], v155 offset:51200
	ds_read_b128 v[230:233], v155 offset:52224
	ds_read_b128 v[234:237], v155 offset:53248
	ds_read_b128 v[238:241], v155 offset:54272
	ds_read_b128 v[242:245], v155 offset:55296
	ds_read_b128 v[246:249], v155 offset:56320
	global_load_lds_dwordx4 v[158:159], off
	s_add_i32 m0, s44, 0x2000
	s_add_u32 s28, s28, 0x80080
	v_lshl_add_u64 v[158:159], v[186:187], 0, s[52:53]
	s_addc_u32 s29, s29, 0
	s_add_i32 s44, s45, s13
	global_load_lds_dwordx4 v[158:159], off
	v_lshl_add_u64 v[158:159], s[28:29], 0, v[166:167]
	s_mov_b32 m0, s44
	s_nop 0
	global_load_lds_dwordx4 v[158:159], off
	v_lshl_add_u64 v[158:159], s[28:29], 0, v[170:171]
	s_add_i32 m0, s44, 0x2000
	s_nop 0
	global_load_lds_dwordx4 v[158:159], off
	v_lshl_add_u64 v[158:159], v[250:251], 0, s[52:53]
	s_mov_b32 m0, s62
	s_nop 0
	global_load_lds_dwordx4 v[158:159], off
	v_lshl_add_u64 v[158:159], v[252:253], 0, s[52:53]
	s_mov_b32 m0, s63
	s_nop 0
	global_load_lds_dwordx4 v[158:159], off
	s_waitcnt vmcnt(8)
	s_waitcnt lgkmcnt(0)
	s_barrier
	s_setprio 1
	s_waitcnt lgkmcnt(0)
	v_mfma_f32_16x16x32_bf16 v[60:63], v[142:145], v[218:221], v[60:63]
	v_mfma_f32_16x16x32_bf16 v[60:63], v[146:149], v[222:225], v[60:63]
	v_mfma_f32_16x16x32_bf16 v[56:59], v[178:181], v[222:225], v[56:59]
	v_mfma_f32_16x16x32_bf16 v[56:59], v[174:177], v[218:221], v[56:59]
	v_mfma_f32_16x16x32_bf16 v[40:43], v[174:177], v[226:229], v[40:43]
	v_mfma_f32_16x16x32_bf16 v[40:43], v[178:181], v[230:233], v[40:43]
	v_mfma_f32_16x16x32_bf16 v[44:47], v[146:149], v[230:233], v[44:47]
	v_mfma_f32_16x16x32_bf16 v[44:47], v[142:145], v[226:229], v[44:47]
	v_mfma_f32_16x16x32_bf16 v[28:31], v[142:145], v[234:237], v[28:31]
	v_mfma_f32_16x16x32_bf16 v[28:31], v[146:149], v[238:241], v[28:31]
	v_mfma_f32_16x16x32_bf16 v[24:27], v[178:181], v[238:241], v[24:27]
	v_mfma_f32_16x16x32_bf16 v[24:27], v[174:177], v[234:237], v[24:27]
	v_mfma_f32_16x16x32_bf16 v[8:11], v[174:177], v[242:245], v[8:11]
	v_mfma_f32_16x16x32_bf16 v[8:11], v[178:181], v[246:249], v[8:11]
	v_mfma_f32_16x16x32_bf16 v[12:15], v[146:149], v[246:249], v[12:15]
	v_mfma_f32_16x16x32_bf16 v[12:15], v[142:145], v[242:245], v[12:15]
	s_setprio 0
	s_setprio 1
	v_mfma_f32_16x16x32_bf16 v[52:55], v[182:185], v[218:221], v[52:55]
	v_mfma_f32_16x16x32_bf16 v[52:55], v[206:209], v[222:225], v[52:55]
	v_mfma_f32_16x16x32_bf16 v[48:51], v[214:217], v[222:225], v[48:51]
	v_mfma_f32_16x16x32_bf16 v[48:51], v[210:213], v[218:221], v[48:51]
	v_mfma_f32_16x16x32_bf16 v[32:35], v[210:213], v[226:229], v[32:35]
	v_mfma_f32_16x16x32_bf16 v[32:35], v[214:217], v[230:233], v[32:35]
	v_mfma_f32_16x16x32_bf16 v[36:39], v[206:209], v[230:233], v[36:39]
	v_mfma_f32_16x16x32_bf16 v[36:39], v[182:185], v[226:229], v[36:39]
	v_mfma_f32_16x16x32_bf16 v[20:23], v[182:185], v[234:237], v[20:23]
	v_mfma_f32_16x16x32_bf16 v[20:23], v[206:209], v[238:241], v[20:23]
	v_mfma_f32_16x16x32_bf16 v[16:19], v[214:217], v[238:241], v[16:19]
	v_mfma_f32_16x16x32_bf16 v[16:19], v[210:213], v[234:237], v[16:19]
	v_mfma_f32_16x16x32_bf16 v[0:3], v[210:213], v[242:245], v[0:3]
	v_mfma_f32_16x16x32_bf16 v[0:3], v[214:217], v[246:249], v[0:3]
	s_setprio 2
	s_barrier
	v_mfma_f32_16x16x32_bf16 v[4:7], v[206:209], v[246:249], v[4:7]
	v_mfma_f32_16x16x32_bf16 v[4:7], v[182:185], v[242:245], v[4:7]
	s_setprio 0
	s_add_i32 s97, s97, 2
	s_add_u32 s84, s84, 0x100
	s_addc_u32 s85, s85, 0
	s_add_u32 s95, s95, 0x100
	s_addc_u32 s96, s96, 0
	s_cmp_gt_u32 s97, 29
	s_cbranch_scc0 .LBB0_231
	s_and_b64 vcc, exec, s[72:73]
	s_cbranch_vccz .LBB0_236
	s_barrier
	v_lshl_add_u32 v142, s82, 8, v150
	s_cmp_gt_i32 s94, 7
	s_mov_b64 s[28:29], -1
	s_cbranch_scc1 .LBB0_237

; #define PG8_STAGE(bufoff, gbase, voff) do { _Pragma("unroll") for (int _i = 0; _i < 2; ++_i) \
;         __builtin_amdgcn_global_load_lds((const unsigned*)((const char*)(gbase) + (voff)[_i]), (PG8_LAS unsigned*)(lds + (bufoff) + ldsw + _i * 8192), 16, 0, 0); } while (0)
; #define PG8_LDA(dst, b, h) do { _Pragma("unroll") for (int m = 0; m < 4; ++m) _Pragma("unroll") for (int k = 0; k < 2; ++k) dst[m][k] = *(const PG8_LAS bf16x8*)(lds + PG8_SA(b, h) + aoff + m * 2048 + k * 1024); } while (0)
; #define PG8_LDB(dst, b, h) do { _Pragma("unroll") for (int n = 0; n < 2; ++n) _Pragma("unroll") for (int k = 0; k < 2; ++k) dst[n][k] = *(const PG8_LAS bf16x8*)(lds + PG8_SB(b, h) + boff + n * 2048 + k * 1024); } while (0)
; #define PG8_MMA(ai, bj, At, Bt) do { __builtin_amdgcn_s_setprio(1); _Pragma("unroll") for (int m = 0; m < 4; ++m) _Pragma("unroll") for (int n = 0; n < 2; ++n) _Pragma("unroll") for (int k = 0; k < 2; ++k) \
;         acc[ai][bj][m][n] = __builtin_amdgcn_mfma_f32_16x16x32_bf16(Bt[n][k], At[m][k], acc[ai][bj][m][n], 0, 0, 0); __builtin_amdgcn_s_setprio(0); } while (0)
; #define PG8_WAIT_V(n) asm volatile("s_waitcnt vmcnt(" #n ")" ::: "memory")
; #define PG8_WAIT_L(n) asm volatile("s_waitcnt lgkmcnt(" #n ")" ::: "memory")
; #define PG8_BAR __builtin_amdgcn_s_barrier()
; #define PG8_SCHED __builtin_amdgcn_sched_barrier(0)
; template <class Epi, class Sched, bool ALIGN_EPI = false, bool SP2 = false>
; __device__ __forceinline__ void gemm_phase(PG8_LAS unsigned char* lds, const Gemm g, const Sched& S, const Epi& E) {
;     ...
;             const bool last = (t == nt - 2);
;             const char* a1 = cA + (size_t)(t + 1) * kstep;
;             const char* a2 = last ? nA : cA + (size_t)(t + 2) * kstep; const char* b2 = last ? nB : cB + (size_t)(t + 2) * kstep;
;             const char* a3 = a2 + kstep; const char* b3 = b2 + kstep;
;             if (last && has_next) S.a_ready(nxt);
;             if constexpr (SP2) {
;             PG8_LDB(B0, 0, 0); PG8_LDB(B1, 0, 1); PG8_SCHED; PG8_LDA(At, 0, 0); PG8_STAGE(PG8_SA(1, 1), a1 + hstep, voffA);
;             PG8_WAIT_V(8); PG8_WAIT_L(0); PG8_BAR; PG8_MMA(0, 0, At, B0); PG8_MMA(0, 1, At, B1); PG8_BAR; PG8_SCHED;
;             PG8_LDA(At, 0, 1); PG8_STAGE(PG8_SB(0, 0), b2, voffB); PG8_STAGE(PG8_SB(0, 1), b2 + hstep, voffB); PG8_STAGE(PG8_SA(0, 0), a2, voffA);
.LBB0_362:
	ds_read_b128 v[80:83], v171
	ds_read_b128 v[84:87], v171 offset:1024
	ds_read_b128 v[92:95], v171 offset:2048
	ds_read_b128 v[100:103], v171 offset:3072
	ds_read_b128 v[144:147], v186
	ds_read_b128 v[148:151], v186 offset:1024
	ds_read_b128 v[152:155], v186 offset:2048
	ds_read_b128 v[156:159], v186 offset:3072
	s_add_u32 s28, s74, 0xfff80080
	s_addc_u32 s29, s75, -1
	s_cmp_eq_u32 s77, 28
	s_cselect_b32 s49, s23, s29
	s_cselect_b32 s48, s34, s28
	s_cselect_b32 s29, s21, s76
	s_cselect_b32 s28, s35, s73
	v_lshl_add_u64 v[200:201], s[74:75], 0, v[172:173]
	s_add_i32 m0, s38, 0xc000
	ds_read_b128 v[178:181], v187
	ds_read_b128 v[182:185], v187 offset:1024
	ds_read_b128 v[206:209], v187 offset:2048
	ds_read_b128 v[210:213], v187 offset:3072
	ds_read_b128 v[214:217], v187 offset:4096
	ds_read_b128 v[218:221], v187 offset:5120
	ds_read_b128 v[222:225], v187 offset:6144
	ds_read_b128 v[226:229], v187 offset:7168
	global_load_lds_dwordx4 v[200:201], off
	v_lshl_add_u64 v[200:201], s[74:75], 0, v[174:175]
	s_add_i32 m0, s38, 0xe000
	s_nop 0
	global_load_lds_dwordx4 v[200:201], off
	s_waitcnt vmcnt(8)
	s_waitcnt lgkmcnt(0)
	s_barrier
	s_setprio 1
	s_waitcnt lgkmcnt(0)
	v_mfma_f32_16x16x32_bf16 v[140:143], v[80:83], v[178:181], v[140:143]
	v_mfma_f32_16x16x32_bf16 v[140:143], v[84:87], v[182:185], v[140:143]
	v_mfma_f32_16x16x32_bf16 v[136:139], v[100:103], v[182:185], v[136:139]
	v_mfma_f32_16x16x32_bf16 v[136:139], v[92:95], v[178:181], v[136:139]
	v_mfma_f32_16x16x32_bf16 v[120:123], v[92:95], v[206:209], v[120:123]
	v_mfma_f32_16x16x32_bf16 v[120:123], v[100:103], v[210:213], v[120:123]
	v_mfma_f32_16x16x32_bf16 v[124:127], v[84:87], v[210:213], v[124:127]
	v_mfma_f32_16x16x32_bf16 v[124:127], v[80:83], v[206:209], v[124:127]
	v_mfma_f32_16x16x32_bf16 v[108:111], v[80:83], v[214:217], v[108:111]
	v_mfma_f32_16x16x32_bf16 v[108:111], v[84:87], v[218:221], v[108:111]
	v_mfma_f32_16x16x32_bf16 v[104:107], v[100:103], v[218:221], v[104:107]
	v_mfma_f32_16x16x32_bf16 v[104:107], v[92:95], v[214:217], v[104:107]
	v_mfma_f32_16x16x32_bf16 v[72:75], v[92:95], v[222:225], v[72:75]
	v_mfma_f32_16x16x32_bf16 v[72:75], v[100:103], v[226:229], v[72:75]
	v_mfma_f32_16x16x32_bf16 v[76:79], v[84:87], v[226:229], v[76:79]
	v_mfma_f32_16x16x32_bf16 v[76:79], v[80:83], v[222:225], v[76:79]
	s_setprio 0
	s_setprio 1
	v_mfma_f32_16x16x32_bf16 v[132:135], v[144:147], v[178:181], v[132:135]
	v_mfma_f32_16x16x32_bf16 v[132:135], v[148:151], v[182:185], v[132:135]
	v_mfma_f32_16x16x32_bf16 v[128:131], v[156:159], v[182:185], v[128:131]
	v_mfma_f32_16x16x32_bf16 v[128:131], v[152:155], v[178:181], v[128:131]
	v_mfma_f32_16x16x32_bf16 v[112:115], v[152:155], v[206:209], v[112:115]
	v_mfma_f32_16x16x32_bf16 v[112:115], v[156:159], v[210:213], v[112:115]
	v_mfma_f32_16x16x32_bf16 v[116:119], v[148:151], v[210:213], v[116:119]
	v_mfma_f32_16x16x32_bf16 v[116:119], v[144:147], v[206:209], v[116:119]
	v_mfma_f32_16x16x32_bf16 v[96:99], v[144:147], v[214:217], v[96:99]
	v_mfma_f32_16x16x32_bf16 v[96:99], v[148:151], v[218:221], v[96:99]
	v_mfma_f32_16x16x32_bf16 v[88:91], v[156:159], v[218:221], v[88:91]
	v_mfma_f32_16x16x32_bf16 v[88:91], v[152:155], v[214:217], v[88:91]
	v_mfma_f32_16x16x32_bf16 v[64:67], v[152:155], v[222:225], v[64:67]
	v_mfma_f32_16x16x32_bf16 v[64:67], v[156:159], v[226:229], v[64:67]
	s_setprio 2
	s_barrier
	v_mfma_f32_16x16x32_bf16 v[68:71], v[148:151], v[226:229], v[68:71]
	v_mfma_f32_16x16x32_bf16 v[68:71], v[144:147], v[222:225], v[68:71]
	s_setprio 0
	s_add_i32 s44, s62, s13
	v_lshl_add_u64 v[200:201], s[28:29], 0, v[164:165]
	s_mov_b32 m0, s44
	ds_read_b128 v[178:181], v187 offset:16384
	ds_read_b128 v[182:185], v187 offset:17408
	ds_read_b128 v[206:209], v187 offset:18432
	ds_read_b128 v[210:213], v187 offset:19456
	ds_read_b128 v[214:217], v187 offset:20480
	ds_read_b128 v[218:221], v187 offset:21504
	ds_read_b128 v[222:225], v187 offset:22528
	ds_read_b128 v[226:229], v187 offset:23552
	global_load_lds_dwordx4 v[200:201], off
	s_add_i32 m0, s44, 0x2000
	s_add_u32 s78, s28, 0x80000
	v_lshl_add_u64 v[230:231], s[28:29], 0, v[168:169]
	s_addc_u32 s79, s29, 0
	s_add_i32 s44, s63, s13
	global_load_lds_dwordx4 v[230:231], off
	v_lshl_add_u64 v[232:233], s[78:79], 0, v[164:165]
	s_mov_b32 m0, s44
	v_lshl_add_u64 v[234:235], s[48:49], 0, v[168:169]
	global_load_lds_dwordx4 v[232:233], off
	v_lshl_add_u64 v[232:233], s[78:79], 0, v[168:169]
	s_add_i32 m0, s44, 0x2000
	s_nop 0
	global_load_lds_dwordx4 v[232:233], off
	v_lshl_add_u64 v[232:233], s[48:49], 0, v[164:165]
	s_mov_b32 m0, s38
	s_nop 0
	global_load_lds_dwordx4 v[232:233], off
	s_mov_b32 m0, s39
	s_nop 0
	global_load_lds_dwordx4 v[234:235], off
	s_waitcnt vmcnt(8)
	s_waitcnt lgkmcnt(0)
	s_barrier
; #define PG8_STAGE(bufoff, gbase, voff) do { _Pragma("unroll") for (int _i = 0; _i < 2; ++_i) \
;         __builtin_amdgcn_global_load_lds((const unsigned*)((const char*)(gbase) + (voff)[_i]), (PG8_LAS unsigned*)(lds + (bufoff) + ldsw + _i * 8192), 16, 0, 0); } while (0)
; #define PG8_LDA(dst, b, h) do { _Pragma("unroll") for (int m = 0; m < 4; ++m) _Pragma("unroll") for (int k = 0; k < 2; ++k) dst[m][k] = *(const PG8_LAS bf16x8*)(lds + PG8_SA(b, h) + aoff + m * 2048 + k * 1024); } while (0)
; #define PG8_LDB(dst, b, h) do { _Pragma("unroll") for (int n = 0; n < 2; ++n) _Pragma("unroll") for (int k = 0; k < 2; ++k) dst[n][k] = *(const PG8_LAS bf16x8*)(lds + PG8_SB(b, h) + boff + n * 2048 + k * 1024); } while (0)
; #define PG8_MMA(ai, bj, At, Bt) do { __builtin_amdgcn_s_setprio(1); _Pragma("unroll") for (int m = 0; m < 4; ++m) _Pragma("unroll") for (int n = 0; n < 2; ++n) _Pragma("unroll") for (int k = 0; k < 2; ++k) \
;         acc[ai][bj][m][n] = __builtin_amdgcn_mfma_f32_16x16x32_bf16(Bt[n][k], At[m][k], acc[ai][bj][m][n], 0, 0, 0); __builtin_amdgcn_s_setprio(0); } while (0)
; #define PG8_WAIT_V(n) asm volatile("s_waitcnt vmcnt(" #n ")" ::: "memory")
; #define PG8_WAIT_L(n) asm volatile("s_waitcnt lgkmcnt(" #n ")" ::: "memory")
; #define PG8_BAR __builtin_amdgcn_s_barrier()
; #define PG8_SCHED __builtin_amdgcn_sched_barrier(0)
; template <class Epi, class Sched, bool ALIGN_EPI = false, bool SP2 = false>
; __device__ __forceinline__ void gemm_phase(PG8_LAS unsigned char* lds, const Gemm g, const Sched& S, const Epi& E) {
;     ...
;             PG8_WAIT_V(8); PG8_WAIT_L(0); PG8_BAR; PG8_MMA(1, 0, At, B0); PG8_MMA(1, 1, At, B1); PG8_BAR; PG8_SCHED;
;             PG8_LDB(B0, 1, 0); PG8_LDB(B1, 1, 1); PG8_SCHED; PG8_LDA(At, 1, 0); PG8_STAGE(PG8_SA(0, 1), a2 + hstep, voffA);
;             PG8_WAIT_V(8); PG8_WAIT_L(0); PG8_BAR; PG8_MMA(0, 0, At, B0); PG8_MMA(0, 1, At, B1); PG8_BAR; PG8_SCHED;
	s_setprio 1
	s_waitcnt lgkmcnt(0)
	v_mfma_f32_16x16x32_bf16 v[60:63], v[80:83], v[178:181], v[60:63]
	v_mfma_f32_16x16x32_bf16 v[60:63], v[84:87], v[182:185], v[60:63]
	v_mfma_f32_16x16x32_bf16 v[56:59], v[100:103], v[182:185], v[56:59]
	v_mfma_f32_16x16x32_bf16 v[56:59], v[92:95], v[178:181], v[56:59]
	v_mfma_f32_16x16x32_bf16 v[40:43], v[92:95], v[206:209], v[40:43]
	v_mfma_f32_16x16x32_bf16 v[40:43], v[100:103], v[210:213], v[40:43]
	v_mfma_f32_16x16x32_bf16 v[44:47], v[84:87], v[210:213], v[44:47]
	v_mfma_f32_16x16x32_bf16 v[44:47], v[80:83], v[206:209], v[44:47]
	v_mfma_f32_16x16x32_bf16 v[28:31], v[80:83], v[214:217], v[28:31]
	v_mfma_f32_16x16x32_bf16 v[28:31], v[84:87], v[218:221], v[28:31]
	v_mfma_f32_16x16x32_bf16 v[24:27], v[100:103], v[218:221], v[24:27]
	v_mfma_f32_16x16x32_bf16 v[24:27], v[92:95], v[214:217], v[24:27]
	v_mfma_f32_16x16x32_bf16 v[8:11], v[92:95], v[222:225], v[8:11]
	v_mfma_f32_16x16x32_bf16 v[8:11], v[100:103], v[226:229], v[8:11]
	v_mfma_f32_16x16x32_bf16 v[12:15], v[84:87], v[226:229], v[12:15]
	v_mfma_f32_16x16x32_bf16 v[12:15], v[80:83], v[222:225], v[12:15]
	s_setprio 0
	s_setprio 1
	v_mfma_f32_16x16x32_bf16 v[52:55], v[144:147], v[178:181], v[52:55]
	v_mfma_f32_16x16x32_bf16 v[52:55], v[148:151], v[182:185], v[52:55]
	v_mfma_f32_16x16x32_bf16 v[48:51], v[156:159], v[182:185], v[48:51]
	v_mfma_f32_16x16x32_bf16 v[48:51], v[152:155], v[178:181], v[48:51]
	v_mfma_f32_16x16x32_bf16 v[32:35], v[152:155], v[206:209], v[32:35]
	v_mfma_f32_16x16x32_bf16 v[32:35], v[156:159], v[210:213], v[32:35]
	v_mfma_f32_16x16x32_bf16 v[36:39], v[148:151], v[210:213], v[36:39]
	v_mfma_f32_16x16x32_bf16 v[36:39], v[144:147], v[206:209], v[36:39]
	v_mfma_f32_16x16x32_bf16 v[20:23], v[144:147], v[214:217], v[20:23]
	v_mfma_f32_16x16x32_bf16 v[20:23], v[148:151], v[218:221], v[20:23]
	v_mfma_f32_16x16x32_bf16 v[16:19], v[156:159], v[218:221], v[16:19]
	v_mfma_f32_16x16x32_bf16 v[16:19], v[152:155], v[214:217], v[16:19]
	v_mfma_f32_16x16x32_bf16 v[0:3], v[152:155], v[222:225], v[0:3]
	v_mfma_f32_16x16x32_bf16 v[0:3], v[156:159], v[226:229], v[0:3]
	s_setprio 2
	s_barrier
	v_mfma_f32_16x16x32_bf16 v[4:7], v[148:151], v[226:229], v[4:7]
	v_mfma_f32_16x16x32_bf16 v[4:7], v[144:147], v[222:225], v[4:7]
	s_setprio 0
	s_add_i32 s44, 0, 0x18000
	s_add_i32 s45, 0, 0x1c000
	v_add_u32_e32 v100, s44, v163
	v_add_u32_e32 v156, s45, v163
	ds_read_b128 v[80:83], v100
	ds_read_b128 v[84:87], v100 offset:1024
	ds_read_b128 v[92:95], v100 offset:2048
	ds_read_b128 v[100:103], v100 offset:3072
	ds_read_b128 v[144:147], v156
	ds_read_b128 v[148:151], v156 offset:1024
	ds_read_b128 v[152:155], v156 offset:2048
	ds_read_b128 v[156:159], v156 offset:3072
	s_add_u32 s48, s48, 0x80000
	s_addc_u32 s49, s49, 0
	s_mov_b32 m0, s40
	v_lshl_add_u64 v[236:237], s[48:49], 0, v[164:165]
	ds_read_b128 v[178:181], v187 offset:32768
	ds_read_b128 v[182:185], v187 offset:33792
	ds_read_b128 v[206:209], v187 offset:34816
	ds_read_b128 v[210:213], v187 offset:35840
	ds_read_b128 v[214:217], v187 offset:36864
	ds_read_b128 v[218:221], v187 offset:37888
	ds_read_b128 v[222:225], v187 offset:38912
	ds_read_b128 v[226:229], v187 offset:39936
	global_load_lds_dwordx4 v[236:237], off
	v_lshl_add_u64 v[236:237], s[48:49], 0, v[168:169]
	s_mov_b32 m0, s41
	s_nop 0
	global_load_lds_dwordx4 v[236:237], off
	s_waitcnt vmcnt(8)
	s_waitcnt lgkmcnt(0)
	s_barrier
	s_setprio 1
	s_waitcnt lgkmcnt(0)
	v_mfma_f32_16x16x32_bf16 v[140:143], v[80:83], v[178:181], v[140:143]
	v_mfma_f32_16x16x32_bf16 v[140:143], v[84:87], v[182:185], v[140:143]
	v_mfma_f32_16x16x32_bf16 v[136:139], v[100:103], v[182:185], v[136:139]
	v_mfma_f32_16x16x32_bf16 v[136:139], v[92:95], v[178:181], v[136:139]
	v_mfma_f32_16x16x32_bf16 v[120:123], v[92:95], v[206:209], v[120:123]
	v_mfma_f32_16x16x32_bf16 v[120:123], v[100:103], v[210:213], v[120:123]
	v_mfma_f32_16x16x32_bf16 v[124:127], v[84:87], v[210:213], v[124:127]
	v_mfma_f32_16x16x32_bf16 v[124:127], v[80:83], v[206:209], v[124:127]
	v_mfma_f32_16x16x32_bf16 v[108:111], v[80:83], v[214:217], v[108:111]
	v_mfma_f32_16x16x32_bf16 v[108:111], v[84:87], v[218:221], v[108:111]
	v_mfma_f32_16x16x32_bf16 v[104:107], v[100:103], v[218:221], v[104:107]
	v_mfma_f32_16x16x32_bf16 v[104:107], v[92:95], v[214:217], v[104:107]
	v_mfma_f32_16x16x32_bf16 v[72:75], v[92:95], v[222:225], v[72:75]
	v_mfma_f32_16x16x32_bf16 v[72:75], v[100:103], v[226:229], v[72:75]
	v_mfma_f32_16x16x32_bf16 v[76:79], v[84:87], v[226:229], v[76:79]
	v_mfma_f32_16x16x32_bf16 v[76:79], v[80:83], v[222:225], v[76:79]
	s_setprio 0
	s_setprio 1
	v_mfma_f32_16x16x32_bf16 v[132:135], v[144:147], v[178:181], v[132:135]
	v_mfma_f32_16x16x32_bf16 v[132:135], v[148:151], v[182:185], v[132:135]
	v_mfma_f32_16x16x32_bf16 v[128:131], v[156:159], v[182:185], v[128:131]
	v_mfma_f32_16x16x32_bf16 v[128:131], v[152:155], v[178:181], v[128:131]
	v_mfma_f32_16x16x32_bf16 v[112:115], v[152:155], v[206:209], v[112:115]
	v_mfma_f32_16x16x32_bf16 v[112:115], v[156:159], v[210:213], v[112:115]
	v_mfma_f32_16x16x32_bf16 v[116:119], v[148:151], v[210:213], v[116:119]
	v_mfma_f32_16x16x32_bf16 v[116:119], v[144:147], v[206:209], v[116:119]
	v_mfma_f32_16x16x32_bf16 v[96:99], v[144:147], v[214:217], v[96:99]
	v_mfma_f32_16x16x32_bf16 v[96:99], v[148:151], v[218:221], v[96:99]
	v_mfma_f32_16x16x32_bf16 v[88:91], v[156:159], v[218:221], v[88:91]
	v_mfma_f32_16x16x32_bf16 v[88:91], v[152:155], v[214:217], v[88:91]
	v_mfma_f32_16x16x32_bf16 v[64:67], v[152:155], v[222:225], v[64:67]
	v_mfma_f32_16x16x32_bf16 v[64:67], v[156:159], v[226:229], v[64:67]
	s_setprio 2
	s_barrier
; #define PG8_STAGE(bufoff, gbase, voff) do { _Pragma("unroll") for (int _i = 0; _i < 2; ++_i) \
;         __builtin_amdgcn_global_load_lds((const unsigned*)((const char*)(gbase) + (voff)[_i]), (PG8_LAS unsigned*)(lds + (bufoff) + ldsw + _i * 8192), 16, 0, 0); } while (0)
; #define PG8_LDA(dst, b, h) do { _Pragma("unroll") for (int m = 0; m < 4; ++m) _Pragma("unroll") for (int k = 0; k < 2; ++k) dst[m][k] = *(const PG8_LAS bf16x8*)(lds + PG8_SA(b, h) + aoff + m * 2048 + k * 1024); } while (0)
; #define PG8_MMA(ai, bj, At, Bt) do { __builtin_amdgcn_s_setprio(1); _Pragma("unroll") for (int m = 0; m < 4; ++m) _Pragma("unroll") for (int n = 0; n < 2; ++n) _Pragma("unroll") for (int k = 0; k < 2; ++k) \
;         acc[ai][bj][m][n] = __builtin_amdgcn_mfma_f32_16x16x32_bf16(Bt[n][k], At[m][k], acc[ai][bj][m][n], 0, 0, 0); __builtin_amdgcn_s_setprio(0); } while (0)
; #define PG8_WAIT_V(n) asm volatile("s_waitcnt vmcnt(" #n ")" ::: "memory")
; #define PG8_WAIT_L(n) asm volatile("s_waitcnt lgkmcnt(" #n ")" ::: "memory")
; #define PG8_BAR __builtin_amdgcn_s_barrier()
; #define PG8_SCHED __builtin_amdgcn_sched_barrier(0)
; template <class Epi, class Sched, bool ALIGN_EPI = false, bool SP2 = false>
; __device__ __forceinline__ void gemm_phase(PG8_LAS unsigned char* lds, const Gemm g, const Sched& S, const Epi& E) {
;     ...
;             PG8_LDA(At, 1, 1); PG8_STAGE(PG8_SB(1, 0), b3, voffB); PG8_STAGE(PG8_SB(1, 1), b3 + hstep, voffB); PG8_STAGE(PG8_SA(1, 0), a3, voffA);
;             PG8_WAIT_V(8); PG8_WAIT_L(0); PG8_BAR; PG8_MMA(1, 0, At, B0); PG8_MMA(1, 1, At, B1); PG8_BAR; PG8_SCHED;
;     ...
;         if constexpr (ALIGN_EPI) { if (wr == 0) PG8_BAR; }
;         if constexpr (!Epi::AFTER_DRAIN) { E(acc, cur, wr, wc, fr, fq); S.done(cur); }
;         if (!has_next) break;
	v_mfma_f32_16x16x32_bf16 v[68:71], v[148:151], v[226:229], v[68:71]
	v_mfma_f32_16x16x32_bf16 v[68:71], v[144:147], v[222:225], v[68:71]
	s_setprio 0
	s_add_i32 s44, s44, s13
	v_lshl_add_u64 v[200:201], v[200:201], 0, s[16:17]
	s_mov_b32 m0, s44
	ds_read_b128 v[178:181], v187 offset:49152
	ds_read_b128 v[182:185], v187 offset:50176
	ds_read_b128 v[206:209], v187 offset:51200
	ds_read_b128 v[210:213], v187 offset:52224
	ds_read_b128 v[214:217], v187 offset:53248
	ds_read_b128 v[218:221], v187 offset:54272
	ds_read_b128 v[222:225], v187 offset:55296
	ds_read_b128 v[226:229], v187 offset:56320
	global_load_lds_dwordx4 v[200:201], off
	s_add_i32 m0, s44, 0x2000
	s_add_u32 s28, s28, 0x80080
	v_lshl_add_u64 v[200:201], v[230:231], 0, s[16:17]
	s_addc_u32 s29, s29, 0
	s_add_i32 s44, s45, s13
	global_load_lds_dwordx4 v[200:201], off
	v_lshl_add_u64 v[200:201], s[28:29], 0, v[164:165]
	s_mov_b32 m0, s44
	s_nop 0
	global_load_lds_dwordx4 v[200:201], off
	v_lshl_add_u64 v[200:201], s[28:29], 0, v[168:169]
	s_add_i32 m0, s44, 0x2000
	s_nop 0
	global_load_lds_dwordx4 v[200:201], off
	v_lshl_add_u64 v[200:201], v[232:233], 0, s[16:17]
	s_mov_b32 m0, s56
	s_nop 0
	global_load_lds_dwordx4 v[200:201], off
	v_lshl_add_u64 v[200:201], v[234:235], 0, s[16:17]
	s_mov_b32 m0, s57
	s_nop 0
	global_load_lds_dwordx4 v[200:201], off
	s_waitcnt vmcnt(8)
	s_waitcnt lgkmcnt(0)
	s_barrier
	s_setprio 1
	s_waitcnt lgkmcnt(0)
	v_mfma_f32_16x16x32_bf16 v[60:63], v[80:83], v[178:181], v[60:63]
	v_mfma_f32_16x16x32_bf16 v[60:63], v[84:87], v[182:185], v[60:63]
	v_mfma_f32_16x16x32_bf16 v[56:59], v[100:103], v[182:185], v[56:59]
	v_mfma_f32_16x16x32_bf16 v[56:59], v[92:95], v[178:181], v[56:59]
	v_mfma_f32_16x16x32_bf16 v[40:43], v[92:95], v[206:209], v[40:43]
	v_mfma_f32_16x16x32_bf16 v[40:43], v[100:103], v[210:213], v[40:43]
	v_mfma_f32_16x16x32_bf16 v[44:47], v[84:87], v[210:213], v[44:47]
	v_mfma_f32_16x16x32_bf16 v[44:47], v[80:83], v[206:209], v[44:47]
	v_mfma_f32_16x16x32_bf16 v[28:31], v[80:83], v[214:217], v[28:31]
	v_mfma_f32_16x16x32_bf16 v[28:31], v[84:87], v[218:221], v[28:31]
	v_mfma_f32_16x16x32_bf16 v[24:27], v[100:103], v[218:221], v[24:27]
	v_mfma_f32_16x16x32_bf16 v[24:27], v[92:95], v[214:217], v[24:27]
	v_mfma_f32_16x16x32_bf16 v[8:11], v[92:95], v[222:225], v[8:11]
	v_mfma_f32_16x16x32_bf16 v[8:11], v[100:103], v[226:229], v[8:11]
	v_mfma_f32_16x16x32_bf16 v[12:15], v[84:87], v[226:229], v[12:15]
	v_mfma_f32_16x16x32_bf16 v[12:15], v[80:83], v[222:225], v[12:15]
	s_setprio 0
	s_setprio 1
	v_mfma_f32_16x16x32_bf16 v[52:55], v[144:147], v[178:181], v[52:55]
	v_mfma_f32_16x16x32_bf16 v[52:55], v[148:151], v[182:185], v[52:55]
	v_mfma_f32_16x16x32_bf16 v[48:51], v[156:159], v[182:185], v[48:51]
	v_mfma_f32_16x16x32_bf16 v[48:51], v[152:155], v[178:181], v[48:51]
	v_mfma_f32_16x16x32_bf16 v[32:35], v[152:155], v[206:209], v[32:35]
	v_mfma_f32_16x16x32_bf16 v[32:35], v[156:159], v[210:213], v[32:35]
	v_mfma_f32_16x16x32_bf16 v[36:39], v[148:151], v[210:213], v[36:39]
	v_mfma_f32_16x16x32_bf16 v[36:39], v[144:147], v[206:209], v[36:39]
	v_mfma_f32_16x16x32_bf16 v[20:23], v[144:147], v[214:217], v[20:23]
	v_mfma_f32_16x16x32_bf16 v[20:23], v[148:151], v[218:221], v[20:23]
	v_mfma_f32_16x16x32_bf16 v[16:19], v[156:159], v[218:221], v[16:19]
	v_mfma_f32_16x16x32_bf16 v[16:19], v[152:155], v[214:217], v[16:19]
	v_mfma_f32_16x16x32_bf16 v[0:3], v[152:155], v[222:225], v[0:3]
	v_mfma_f32_16x16x32_bf16 v[0:3], v[156:159], v[226:229], v[0:3]
	s_setprio 2
	s_barrier
	v_mfma_f32_16x16x32_bf16 v[4:7], v[148:151], v[226:229], v[4:7]
	v_mfma_f32_16x16x32_bf16 v[4:7], v[144:147], v[222:225], v[4:7]
	s_setprio 0
	s_add_i32 s77, s77, 2
	s_add_u32 s74, s74, 0x100
	s_addc_u32 s75, s75, 0
	s_add_u32 s73, s73, 0x100
	s_addc_u32 s76, s76, 0
	s_cmp_gt_u32 s77, 29
	s_cbranch_scc0 .LBB0_362
	s_and_b64 vcc, exec, s[18:19]
	s_cbranch_vccz .LBB0_365
	s_barrier

; #define PG8_STAGE(bufoff, gbase, voff) do { _Pragma("unroll") for (int _i = 0; _i < 2; ++_i) \
;         __builtin_amdgcn_global_load_lds((const unsigned*)((const char*)(gbase) + (voff)[_i]), (PG8_LAS unsigned*)(lds + (bufoff) + ldsw + _i * 8192), 16, 0, 0); } while (0)
; #define PG8_LDA(dst, b, h) do { _Pragma("unroll") for (int m = 0; m < 4; ++m) _Pragma("unroll") for (int k = 0; k < 2; ++k) dst[m][k] = *(const PG8_LAS bf16x8*)(lds + PG8_SA(b, h) + aoff + m * 2048 + k * 1024); } while (0)
; #define PG8_LDB(dst, b, h) do { _Pragma("unroll") for (int n = 0; n < 2; ++n) _Pragma("unroll") for (int k = 0; k < 2; ++k) dst[n][k] = *(const PG8_LAS bf16x8*)(lds + PG8_SB(b, h) + boff + n * 2048 + k * 1024); } while (0)
; #define PG8_MMA(ai, bj, At, Bt) do { __builtin_amdgcn_s_setprio(1); _Pragma("unroll") for (int m = 0; m < 4; ++m) _Pragma("unroll") for (int n = 0; n < 2; ++n) _Pragma("unroll") for (int k = 0; k < 2; ++k) \
;         acc[ai][bj][m][n] = __builtin_amdgcn_mfma_f32_16x16x32_bf16(Bt[n][k], At[m][k], acc[ai][bj][m][n], 0, 0, 0); __builtin_amdgcn_s_setprio(0); } while (0)
; #define PG8_WAIT_V(n) asm volatile("s_waitcnt vmcnt(" #n ")" ::: "memory")
; #define PG8_WAIT_L(n) asm volatile("s_waitcnt lgkmcnt(" #n ")" ::: "memory")
; #define PG8_BAR __builtin_amdgcn_s_barrier()
; #define PG8_SCHED __builtin_amdgcn_sched_barrier(0)
; template <class Epi, class Sched, bool ALIGN_EPI = false, bool SP2 = false>
; __device__ __forceinline__ void gemm_phase(PG8_LAS unsigned char* lds, const Gemm g, const Sched& S, const Epi& E) {
;     ...
;             const bool last = (t == nt - 2);
;             const char* a1 = cA + (size_t)(t + 1) * kstep;
;             const char* a2 = last ? nA : cA + (size_t)(t + 2) * kstep; const char* b2 = last ? nB : cB + (size_t)(t + 2) * kstep;
;             const char* a3 = a2 + kstep; const char* b3 = b2 + kstep;
;             if (last && has_next) S.a_ready(nxt);
;             if constexpr (SP2) {
;             PG8_LDB(B0, 0, 0); PG8_LDB(B1, 0, 1); PG8_SCHED; PG8_LDA(At, 0, 0); PG8_STAGE(PG8_SA(1, 1), a1 + hstep, voffA);
;             PG8_WAIT_V(8); PG8_WAIT_L(0); PG8_BAR; PG8_MMA(0, 0, At, B0); PG8_MMA(0, 1, At, B1); PG8_BAR; PG8_SCHED;
;             PG8_LDA(At, 0, 1); PG8_STAGE(PG8_SB(0, 0), b2, voffB); PG8_STAGE(PG8_SB(0, 1), b2 + hstep, voffB); PG8_STAGE(PG8_SA(0, 0), a2, voffA);
.LBB0_416:
	ds_read_b128 v[136:139], v156
	ds_read_b128 v[140:143], v156 offset:1024
	ds_read_b128 v[172:175], v156 offset:2048
	ds_read_b128 v[176:179], v156 offset:3072
	ds_read_b128 v[180:183], v157
	ds_read_b128 v[184:187], v157 offset:1024
	ds_read_b128 v[206:209], v157 offset:2048
	ds_read_b128 v[210:213], v157 offset:3072
	s_add_u32 s28, s68, 0xfff80080
	s_addc_u32 s29, s69, -1
	s_cmp_eq_u32 s79, 28
	s_cselect_b32 s49, s34, s29
	s_cselect_b32 s48, s35, s28
	s_cselect_b32 s29, s23, s78
	s_cselect_b32 s28, s63, s77
	v_lshl_add_u64 v[200:201], s[68:69], 0, v[128:129]
	s_add_i32 m0, s15, 0xc000
	ds_read_b128 v[214:217], v158
	ds_read_b128 v[218:221], v158 offset:1024
	ds_read_b128 v[222:225], v158 offset:2048
	ds_read_b128 v[226:229], v158 offset:3072
	ds_read_b128 v[230:233], v158 offset:4096
	ds_read_b128 v[234:237], v158 offset:5120
	ds_read_b128 v[238:241], v158 offset:6144
	ds_read_b128 v[242:245], v158 offset:7168
	global_load_lds_dwordx4 v[200:201], off
	v_lshl_add_u64 v[200:201], s[68:69], 0, v[130:131]
	s_add_i32 m0, s15, 0xe000
	s_nop 0
	global_load_lds_dwordx4 v[200:201], off
	s_waitcnt vmcnt(8)
	s_waitcnt lgkmcnt(0)
	s_barrier
	s_setprio 1
	s_waitcnt lgkmcnt(0)
	v_mfma_f32_16x16x32_bf16 v[124:127], v[136:139], v[214:217], v[124:127]
	v_mfma_f32_16x16x32_bf16 v[124:127], v[140:143], v[218:221], v[124:127]
	v_mfma_f32_16x16x32_bf16 v[120:123], v[176:179], v[218:221], v[120:123]
	v_mfma_f32_16x16x32_bf16 v[120:123], v[172:175], v[214:217], v[120:123]
	v_mfma_f32_16x16x32_bf16 v[104:107], v[172:175], v[222:225], v[104:107]
	v_mfma_f32_16x16x32_bf16 v[104:107], v[176:179], v[226:229], v[104:107]
	v_mfma_f32_16x16x32_bf16 v[108:111], v[140:143], v[226:229], v[108:111]
	v_mfma_f32_16x16x32_bf16 v[108:111], v[136:139], v[222:225], v[108:111]
	v_mfma_f32_16x16x32_bf16 v[96:99], v[136:139], v[230:233], v[96:99]
	v_mfma_f32_16x16x32_bf16 v[96:99], v[140:143], v[234:237], v[96:99]
	v_mfma_f32_16x16x32_bf16 v[88:91], v[176:179], v[234:237], v[88:91]
	v_mfma_f32_16x16x32_bf16 v[88:91], v[172:175], v[230:233], v[88:91]
	v_mfma_f32_16x16x32_bf16 v[72:75], v[172:175], v[238:241], v[72:75]
	v_mfma_f32_16x16x32_bf16 v[72:75], v[176:179], v[242:245], v[72:75]
	v_mfma_f32_16x16x32_bf16 v[80:83], v[140:143], v[242:245], v[80:83]
	v_mfma_f32_16x16x32_bf16 v[80:83], v[136:139], v[238:241], v[80:83]
	s_setprio 0
	s_setprio 1
	v_mfma_f32_16x16x32_bf16 v[116:119], v[180:183], v[214:217], v[116:119]
	v_mfma_f32_16x16x32_bf16 v[116:119], v[184:187], v[218:221], v[116:119]
	v_mfma_f32_16x16x32_bf16 v[112:115], v[210:213], v[218:221], v[112:115]
	v_mfma_f32_16x16x32_bf16 v[112:115], v[206:209], v[214:217], v[112:115]
	v_mfma_f32_16x16x32_bf16 v[92:95], v[206:209], v[222:225], v[92:95]
	v_mfma_f32_16x16x32_bf16 v[92:95], v[210:213], v[226:229], v[92:95]
	v_mfma_f32_16x16x32_bf16 v[100:103], v[184:187], v[226:229], v[100:103]
	v_mfma_f32_16x16x32_bf16 v[100:103], v[180:183], v[222:225], v[100:103]
	v_mfma_f32_16x16x32_bf16 v[84:87], v[180:183], v[230:233], v[84:87]
	v_mfma_f32_16x16x32_bf16 v[84:87], v[184:187], v[234:237], v[84:87]
	v_mfma_f32_16x16x32_bf16 v[76:79], v[210:213], v[234:237], v[76:79]
	v_mfma_f32_16x16x32_bf16 v[76:79], v[206:209], v[230:233], v[76:79]
	v_mfma_f32_16x16x32_bf16 v[64:67], v[206:209], v[238:241], v[64:67]
	v_mfma_f32_16x16x32_bf16 v[64:67], v[210:213], v[242:245], v[64:67]
	s_setprio 2
	s_barrier
	v_mfma_f32_16x16x32_bf16 v[68:71], v[184:187], v[242:245], v[68:71]
	v_mfma_f32_16x16x32_bf16 v[68:71], v[180:183], v[238:241], v[68:71]
	s_setprio 0
	s_add_i32 s44, s72, s39
	v_lshl_add_u64 v[200:201], s[28:29], 0, v[166:167]
	s_mov_b32 m0, s44
	ds_read_b128 v[214:217], v158 offset:16384
	ds_read_b128 v[218:221], v158 offset:17408
	ds_read_b128 v[222:225], v158 offset:18432
	ds_read_b128 v[226:229], v158 offset:19456
	ds_read_b128 v[230:233], v158 offset:20480
	ds_read_b128 v[234:237], v158 offset:21504
	ds_read_b128 v[238:241], v158 offset:22528
	ds_read_b128 v[242:245], v158 offset:23552
	global_load_lds_dwordx4 v[200:201], off
	s_add_i32 m0, s44, 0x2000
	s_add_u32 s80, s28, 0x80000
	v_lshl_add_u64 v[246:247], s[28:29], 0, v[170:171]
	s_addc_u32 s81, s29, 0
	s_add_i32 s44, s73, s39
	global_load_lds_dwordx4 v[246:247], off
	v_lshl_add_u64 v[248:249], s[80:81], 0, v[166:167]
	s_mov_b32 m0, s44
	v_lshl_add_u64 v[250:251], s[48:49], 0, v[168:169]
	global_load_lds_dwordx4 v[248:249], off
	v_lshl_add_u64 v[248:249], s[80:81], 0, v[170:171]
	s_add_i32 m0, s44, 0x2000
	s_nop 0
	global_load_lds_dwordx4 v[248:249], off
	v_lshl_add_u64 v[248:249], s[48:49], 0, v[164:165]
	s_mov_b32 m0, s15
	s_nop 0
	global_load_lds_dwordx4 v[248:249], off
	s_mov_b32 m0, s41
	s_nop 0
	global_load_lds_dwordx4 v[250:251], off
	s_waitcnt vmcnt(8)
	s_waitcnt lgkmcnt(0)
	s_barrier
; #define PG8_STAGE(bufoff, gbase, voff) do { _Pragma("unroll") for (int _i = 0; _i < 2; ++_i) \
;         __builtin_amdgcn_global_load_lds((const unsigned*)((const char*)(gbase) + (voff)[_i]), (PG8_LAS unsigned*)(lds + (bufoff) + ldsw + _i * 8192), 16, 0, 0); } while (0)
; #define PG8_LDA(dst, b, h) do { _Pragma("unroll") for (int m = 0; m < 4; ++m) _Pragma("unroll") for (int k = 0; k < 2; ++k) dst[m][k] = *(const PG8_LAS bf16x8*)(lds + PG8_SA(b, h) + aoff + m * 2048 + k * 1024); } while (0)
; #define PG8_LDB(dst, b, h) do { _Pragma("unroll") for (int n = 0; n < 2; ++n) _Pragma("unroll") for (int k = 0; k < 2; ++k) dst[n][k] = *(const PG8_LAS bf16x8*)(lds + PG8_SB(b, h) + boff + n * 2048 + k * 1024); } while (0)
; #define PG8_MMA(ai, bj, At, Bt) do { __builtin_amdgcn_s_setprio(1); _Pragma("unroll") for (int m = 0; m < 4; ++m) _Pragma("unroll") for (int n = 0; n < 2; ++n) _Pragma("unroll") for (int k = 0; k < 2; ++k) \
;         acc[ai][bj][m][n] = __builtin_amdgcn_mfma_f32_16x16x32_bf16(Bt[n][k], At[m][k], acc[ai][bj][m][n], 0, 0, 0); __builtin_amdgcn_s_setprio(0); } while (0)
; #define PG8_WAIT_V(n) asm volatile("s_waitcnt vmcnt(" #n ")" ::: "memory")
; #define PG8_WAIT_L(n) asm volatile("s_waitcnt lgkmcnt(" #n ")" ::: "memory")
; #define PG8_BAR __builtin_amdgcn_s_barrier()
; #define PG8_SCHED __builtin_amdgcn_sched_barrier(0)
; template <class Epi, class Sched, bool ALIGN_EPI = false, bool SP2 = false>
; __device__ __forceinline__ void gemm_phase(PG8_LAS unsigned char* lds, const Gemm g, const Sched& S, const Epi& E) {
;     ...
;             PG8_WAIT_V(8); PG8_WAIT_L(0); PG8_BAR; PG8_MMA(1, 0, At, B0); PG8_MMA(1, 1, At, B1); PG8_BAR; PG8_SCHED;
;             PG8_LDB(B0, 1, 0); PG8_LDB(B1, 1, 1); PG8_SCHED; PG8_LDA(At, 1, 0); PG8_STAGE(PG8_SA(0, 1), a2 + hstep, voffA);
;             PG8_WAIT_V(8); PG8_WAIT_L(0); PG8_BAR; PG8_MMA(0, 0, At, B0); PG8_MMA(0, 1, At, B1); PG8_BAR; PG8_SCHED;
	s_setprio 1
	s_waitcnt lgkmcnt(0)
	v_mfma_f32_16x16x32_bf16 v[60:63], v[136:139], v[214:217], v[60:63]
	v_mfma_f32_16x16x32_bf16 v[60:63], v[140:143], v[218:221], v[60:63]
	v_mfma_f32_16x16x32_bf16 v[56:59], v[176:179], v[218:221], v[56:59]
	v_mfma_f32_16x16x32_bf16 v[56:59], v[172:175], v[214:217], v[56:59]
	v_mfma_f32_16x16x32_bf16 v[40:43], v[172:175], v[222:225], v[40:43]
	v_mfma_f32_16x16x32_bf16 v[40:43], v[176:179], v[226:229], v[40:43]
	v_mfma_f32_16x16x32_bf16 v[48:51], v[140:143], v[226:229], v[48:51]
	v_mfma_f32_16x16x32_bf16 v[48:51], v[136:139], v[222:225], v[48:51]
	v_mfma_f32_16x16x32_bf16 v[32:35], v[136:139], v[230:233], v[32:35]
	v_mfma_f32_16x16x32_bf16 v[32:35], v[140:143], v[234:237], v[32:35]
	v_mfma_f32_16x16x32_bf16 v[24:27], v[176:179], v[234:237], v[24:27]
	v_mfma_f32_16x16x32_bf16 v[24:27], v[172:175], v[230:233], v[24:27]
	v_mfma_f32_16x16x32_bf16 v[8:11], v[172:175], v[238:241], v[8:11]
	v_mfma_f32_16x16x32_bf16 v[8:11], v[176:179], v[242:245], v[8:11]
	v_mfma_f32_16x16x32_bf16 v[12:15], v[140:143], v[242:245], v[12:15]
	v_mfma_f32_16x16x32_bf16 v[12:15], v[136:139], v[238:241], v[12:15]
	s_setprio 0
	s_setprio 1
	v_mfma_f32_16x16x32_bf16 v[52:55], v[180:183], v[214:217], v[52:55]
	v_mfma_f32_16x16x32_bf16 v[52:55], v[184:187], v[218:221], v[52:55]
	v_mfma_f32_16x16x32_bf16 v[44:47], v[210:213], v[218:221], v[44:47]
	v_mfma_f32_16x16x32_bf16 v[44:47], v[206:209], v[214:217], v[44:47]
	v_mfma_f32_16x16x32_bf16 v[28:31], v[206:209], v[222:225], v[28:31]
	v_mfma_f32_16x16x32_bf16 v[28:31], v[210:213], v[226:229], v[28:31]
	v_mfma_f32_16x16x32_bf16 v[36:39], v[184:187], v[226:229], v[36:39]
	v_mfma_f32_16x16x32_bf16 v[36:39], v[180:183], v[222:225], v[36:39]
	v_mfma_f32_16x16x32_bf16 v[20:23], v[180:183], v[230:233], v[20:23]
	v_mfma_f32_16x16x32_bf16 v[20:23], v[184:187], v[234:237], v[20:23]
	v_mfma_f32_16x16x32_bf16 v[16:19], v[210:213], v[234:237], v[16:19]
	v_mfma_f32_16x16x32_bf16 v[16:19], v[206:209], v[230:233], v[16:19]
	v_mfma_f32_16x16x32_bf16 v[0:3], v[206:209], v[238:241], v[0:3]
	v_mfma_f32_16x16x32_bf16 v[0:3], v[210:213], v[242:245], v[0:3]
	s_setprio 2
	s_barrier
	v_mfma_f32_16x16x32_bf16 v[4:7], v[184:187], v[242:245], v[4:7]
	v_mfma_f32_16x16x32_bf16 v[4:7], v[180:183], v[238:241], v[4:7]
	s_setprio 0
	s_add_i32 s44, 0, 0x18000
	v_add_u32_e32 v144, s44, v146
	s_add_i32 s45, 0, 0x1c000
	ds_read_b128 v[136:139], v144
	ds_read_b128 v[140:143], v144 offset:1024
	ds_read_b128 v[172:175], v144 offset:2048
	ds_read_b128 v[176:179], v144 offset:3072
	v_add_u32_e32 v144, s45, v146
	ds_read_b128 v[180:183], v144
	ds_read_b128 v[184:187], v144 offset:1024
	ds_read_b128 v[206:209], v144 offset:2048
	ds_read_b128 v[210:213], v144 offset:3072
	s_add_u32 s48, s48, 0x80000
	s_addc_u32 s49, s49, 0
	s_mov_b32 m0, s56
	v_lshl_add_u64 v[252:253], s[48:49], 0, v[164:165]
	ds_read_b128 v[214:217], v158 offset:32768
	ds_read_b128 v[218:221], v158 offset:33792
	ds_read_b128 v[222:225], v158 offset:34816
	ds_read_b128 v[226:229], v158 offset:35840
	ds_read_b128 v[230:233], v158 offset:36864
	ds_read_b128 v[234:237], v158 offset:37888
	ds_read_b128 v[238:241], v158 offset:38912
	ds_read_b128 v[242:245], v158 offset:39936
	global_load_lds_dwordx4 v[252:253], off
	v_lshl_add_u64 v[252:253], s[48:49], 0, v[168:169]
	s_mov_b32 m0, s57
	s_nop 0
	global_load_lds_dwordx4 v[252:253], off
	s_waitcnt vmcnt(8)
	s_waitcnt lgkmcnt(0)
	s_barrier
	s_setprio 1
	s_waitcnt lgkmcnt(0)
	v_mfma_f32_16x16x32_bf16 v[124:127], v[136:139], v[214:217], v[124:127]
	v_mfma_f32_16x16x32_bf16 v[124:127], v[140:143], v[218:221], v[124:127]
	v_mfma_f32_16x16x32_bf16 v[120:123], v[176:179], v[218:221], v[120:123]
	v_mfma_f32_16x16x32_bf16 v[120:123], v[172:175], v[214:217], v[120:123]
	v_mfma_f32_16x16x32_bf16 v[104:107], v[172:175], v[222:225], v[104:107]
	v_mfma_f32_16x16x32_bf16 v[104:107], v[176:179], v[226:229], v[104:107]
	v_mfma_f32_16x16x32_bf16 v[108:111], v[140:143], v[226:229], v[108:111]
	v_mfma_f32_16x16x32_bf16 v[108:111], v[136:139], v[222:225], v[108:111]
	v_mfma_f32_16x16x32_bf16 v[96:99], v[136:139], v[230:233], v[96:99]
	v_mfma_f32_16x16x32_bf16 v[96:99], v[140:143], v[234:237], v[96:99]
	v_mfma_f32_16x16x32_bf16 v[88:91], v[176:179], v[234:237], v[88:91]
	v_mfma_f32_16x16x32_bf16 v[88:91], v[172:175], v[230:233], v[88:91]
	v_mfma_f32_16x16x32_bf16 v[72:75], v[172:175], v[238:241], v[72:75]
	v_mfma_f32_16x16x32_bf16 v[72:75], v[176:179], v[242:245], v[72:75]
	v_mfma_f32_16x16x32_bf16 v[80:83], v[140:143], v[242:245], v[80:83]
	v_mfma_f32_16x16x32_bf16 v[80:83], v[136:139], v[238:241], v[80:83]
	s_setprio 0
	s_setprio 1
	v_mfma_f32_16x16x32_bf16 v[116:119], v[180:183], v[214:217], v[116:119]
	v_mfma_f32_16x16x32_bf16 v[116:119], v[184:187], v[218:221], v[116:119]
	v_mfma_f32_16x16x32_bf16 v[112:115], v[210:213], v[218:221], v[112:115]
	v_mfma_f32_16x16x32_bf16 v[112:115], v[206:209], v[214:217], v[112:115]
	v_mfma_f32_16x16x32_bf16 v[92:95], v[206:209], v[222:225], v[92:95]
	v_mfma_f32_16x16x32_bf16 v[92:95], v[210:213], v[226:229], v[92:95]
	v_mfma_f32_16x16x32_bf16 v[100:103], v[184:187], v[226:229], v[100:103]
	v_mfma_f32_16x16x32_bf16 v[100:103], v[180:183], v[222:225], v[100:103]
	v_mfma_f32_16x16x32_bf16 v[84:87], v[180:183], v[230:233], v[84:87]
	v_mfma_f32_16x16x32_bf16 v[84:87], v[184:187], v[234:237], v[84:87]
	v_mfma_f32_16x16x32_bf16 v[76:79], v[210:213], v[234:237], v[76:79]
	v_mfma_f32_16x16x32_bf16 v[76:79], v[206:209], v[230:233], v[76:79]
	v_mfma_f32_16x16x32_bf16 v[64:67], v[206:209], v[238:241], v[64:67]
	v_mfma_f32_16x16x32_bf16 v[64:67], v[210:213], v[242:245], v[64:67]
	s_setprio 2
	s_barrier
; #define PG8_STAGE(bufoff, gbase, voff) do { _Pragma("unroll") for (int _i = 0; _i < 2; ++_i) \
;         __builtin_amdgcn_global_load_lds((const unsigned*)((const char*)(gbase) + (voff)[_i]), (PG8_LAS unsigned*)(lds + (bufoff) + ldsw + _i * 8192), 16, 0, 0); } while (0)
; #define PG8_LDA(dst, b, h) do { _Pragma("unroll") for (int m = 0; m < 4; ++m) _Pragma("unroll") for (int k = 0; k < 2; ++k) dst[m][k] = *(const PG8_LAS bf16x8*)(lds + PG8_SA(b, h) + aoff + m * 2048 + k * 1024); } while (0)
; #define PG8_MMA(ai, bj, At, Bt) do { __builtin_amdgcn_s_setprio(1); _Pragma("unroll") for (int m = 0; m < 4; ++m) _Pragma("unroll") for (int n = 0; n < 2; ++n) _Pragma("unroll") for (int k = 0; k < 2; ++k) \
;         acc[ai][bj][m][n] = __builtin_amdgcn_mfma_f32_16x16x32_bf16(Bt[n][k], At[m][k], acc[ai][bj][m][n], 0, 0, 0); __builtin_amdgcn_s_setprio(0); } while (0)
; #define PG8_WAIT_V(n) asm volatile("s_waitcnt vmcnt(" #n ")" ::: "memory")
; #define PG8_WAIT_L(n) asm volatile("s_waitcnt lgkmcnt(" #n ")" ::: "memory")
; #define PG8_BAR __builtin_amdgcn_s_barrier()
; #define PG8_SCHED __builtin_amdgcn_sched_barrier(0)
; template <class Epi, class Sched, bool ALIGN_EPI = false, bool SP2 = false>
; __device__ __forceinline__ void gemm_phase(PG8_LAS unsigned char* lds, const Gemm g, const Sched& S, const Epi& E) {
;     ...
;             PG8_LDA(At, 1, 1); PG8_STAGE(PG8_SB(1, 0), b3, voffB); PG8_STAGE(PG8_SB(1, 1), b3 + hstep, voffB); PG8_STAGE(PG8_SA(1, 0), a3, voffA);
;             PG8_WAIT_V(8); PG8_WAIT_L(0); PG8_BAR; PG8_MMA(1, 0, At, B0); PG8_MMA(1, 1, At, B1); PG8_BAR; PG8_SCHED;
;     ...
;         if constexpr (ALIGN_EPI) { if (wr == 0) PG8_BAR; }
;         if constexpr (!Epi::AFTER_DRAIN) { E(acc, cur, wr, wc, fr, fq); S.done(cur); }
;         if (!has_next) break;
	v_mfma_f32_16x16x32_bf16 v[68:71], v[184:187], v[242:245], v[68:71]
	v_mfma_f32_16x16x32_bf16 v[68:71], v[180:183], v[238:241], v[68:71]
	s_setprio 0
	s_add_i32 s44, s44, s39
	v_lshl_add_u64 v[200:201], v[200:201], 0, s[18:19]
	s_mov_b32 m0, s44
	ds_read_b128 v[214:217], v158 offset:49152
	ds_read_b128 v[218:221], v158 offset:50176
	ds_read_b128 v[222:225], v158 offset:51200
	ds_read_b128 v[226:229], v158 offset:52224
	ds_read_b128 v[230:233], v158 offset:53248
	ds_read_b128 v[234:237], v158 offset:54272
	ds_read_b128 v[238:241], v158 offset:55296
	ds_read_b128 v[242:245], v158 offset:56320
	global_load_lds_dwordx4 v[200:201], off
	s_add_i32 m0, s44, 0x2000
	s_add_u32 s28, s28, 0x80080
	v_lshl_add_u64 v[200:201], v[246:247], 0, s[18:19]
	s_addc_u32 s29, s29, 0
	s_add_i32 s44, s45, s39
	global_load_lds_dwordx4 v[200:201], off
	v_lshl_add_u64 v[200:201], s[28:29], 0, v[166:167]
	s_mov_b32 m0, s44
	s_nop 0
	global_load_lds_dwordx4 v[200:201], off
	v_lshl_add_u64 v[200:201], s[28:29], 0, v[170:171]
	s_add_i32 m0, s44, 0x2000
	s_nop 0
	global_load_lds_dwordx4 v[200:201], off
	v_lshl_add_u64 v[200:201], v[248:249], 0, s[18:19]
	s_mov_b32 m0, s70
	s_nop 0
	global_load_lds_dwordx4 v[200:201], off
	v_lshl_add_u64 v[200:201], v[250:251], 0, s[18:19]
	s_mov_b32 m0, s71
	s_nop 0
	global_load_lds_dwordx4 v[200:201], off
	s_waitcnt vmcnt(8)
	s_waitcnt lgkmcnt(0)
	s_barrier
	s_setprio 1
	s_waitcnt lgkmcnt(0)
	v_mfma_f32_16x16x32_bf16 v[60:63], v[136:139], v[214:217], v[60:63]
	v_mfma_f32_16x16x32_bf16 v[60:63], v[140:143], v[218:221], v[60:63]
	v_mfma_f32_16x16x32_bf16 v[56:59], v[176:179], v[218:221], v[56:59]
	v_mfma_f32_16x16x32_bf16 v[56:59], v[172:175], v[214:217], v[56:59]
	v_mfma_f32_16x16x32_bf16 v[40:43], v[172:175], v[222:225], v[40:43]
	v_mfma_f32_16x16x32_bf16 v[40:43], v[176:179], v[226:229], v[40:43]
	v_mfma_f32_16x16x32_bf16 v[48:51], v[140:143], v[226:229], v[48:51]
	v_mfma_f32_16x16x32_bf16 v[48:51], v[136:139], v[222:225], v[48:51]
	v_mfma_f32_16x16x32_bf16 v[32:35], v[136:139], v[230:233], v[32:35]
	v_mfma_f32_16x16x32_bf16 v[32:35], v[140:143], v[234:237], v[32:35]
	v_mfma_f32_16x16x32_bf16 v[24:27], v[176:179], v[234:237], v[24:27]
	v_mfma_f32_16x16x32_bf16 v[24:27], v[172:175], v[230:233], v[24:27]
	v_mfma_f32_16x16x32_bf16 v[8:11], v[172:175], v[238:241], v[8:11]
	v_mfma_f32_16x16x32_bf16 v[8:11], v[176:179], v[242:245], v[8:11]
	v_mfma_f32_16x16x32_bf16 v[12:15], v[140:143], v[242:245], v[12:15]
	v_mfma_f32_16x16x32_bf16 v[12:15], v[136:139], v[238:241], v[12:15]
	s_setprio 0
	s_setprio 1
	v_mfma_f32_16x16x32_bf16 v[52:55], v[180:183], v[214:217], v[52:55]
	v_mfma_f32_16x16x32_bf16 v[52:55], v[184:187], v[218:221], v[52:55]
	v_mfma_f32_16x16x32_bf16 v[44:47], v[210:213], v[218:221], v[44:47]
	v_mfma_f32_16x16x32_bf16 v[44:47], v[206:209], v[214:217], v[44:47]
	v_mfma_f32_16x16x32_bf16 v[28:31], v[206:209], v[222:225], v[28:31]
	v_mfma_f32_16x16x32_bf16 v[28:31], v[210:213], v[226:229], v[28:31]
	v_mfma_f32_16x16x32_bf16 v[36:39], v[184:187], v[226:229], v[36:39]
	v_mfma_f32_16x16x32_bf16 v[36:39], v[180:183], v[222:225], v[36:39]
	v_mfma_f32_16x16x32_bf16 v[20:23], v[180:183], v[230:233], v[20:23]
	v_mfma_f32_16x16x32_bf16 v[20:23], v[184:187], v[234:237], v[20:23]
	v_mfma_f32_16x16x32_bf16 v[16:19], v[210:213], v[234:237], v[16:19]
	v_mfma_f32_16x16x32_bf16 v[16:19], v[206:209], v[230:233], v[16:19]
	v_mfma_f32_16x16x32_bf16 v[0:3], v[206:209], v[238:241], v[0:3]
	v_mfma_f32_16x16x32_bf16 v[0:3], v[210:213], v[242:245], v[0:3]
	s_setprio 2
	s_barrier
	v_mfma_f32_16x16x32_bf16 v[4:7], v[184:187], v[242:245], v[4:7]
	v_mfma_f32_16x16x32_bf16 v[4:7], v[180:183], v[238:241], v[4:7]
	s_setprio 0
	s_add_i32 s79, s79, 2
	s_add_u32 s68, s68, 0x100
	s_addc_u32 s69, s69, 0
	s_add_u32 s77, s77, 0x100
	s_addc_u32 s78, s78, 0
	s_cmp_gt_u32 s79, 29
	s_cbranch_scc0 .LBB0_416
	s_and_b64 vcc, exec, s[20:21]
	s_cbranch_vccz .LBB0_419
	s_barrier

; #define PG8_STAGE(bufoff, gbase, voff) do { _Pragma("unroll") for (int _i = 0; _i < 2; ++_i) \
;         __builtin_amdgcn_global_load_lds((const unsigned*)((const char*)(gbase) + (voff)[_i]), (PG8_LAS unsigned*)(lds + (bufoff) + ldsw + _i * 8192), 16, 0, 0); } while (0)
; #define PG8_LDA(dst, b, h) do { _Pragma("unroll") for (int m = 0; m < 4; ++m) _Pragma("unroll") for (int k = 0; k < 2; ++k) dst[m][k] = *(const PG8_LAS bf16x8*)(lds + PG8_SA(b, h) + aoff + m * 2048 + k * 1024); } while (0)
; #define PG8_LDB(dst, b, h) do { _Pragma("unroll") for (int n = 0; n < 2; ++n) _Pragma("unroll") for (int k = 0; k < 2; ++k) dst[n][k] = *(const PG8_LAS bf16x8*)(lds + PG8_SB(b, h) + boff + n * 2048 + k * 1024); } while (0)
; #define PG8_MMA(ai, bj, At, Bt) do { __builtin_amdgcn_s_setprio(1); _Pragma("unroll") for (int m = 0; m < 4; ++m) _Pragma("unroll") for (int n = 0; n < 2; ++n) _Pragma("unroll") for (int k = 0; k < 2; ++k) \
;         acc[ai][bj][m][n] = __builtin_amdgcn_mfma_f32_16x16x32_bf16(Bt[n][k], At[m][k], acc[ai][bj][m][n], 0, 0, 0); __builtin_amdgcn_s_setprio(0); } while (0)
; #define PG8_WAIT_V(n) asm volatile("s_waitcnt vmcnt(" #n ")" ::: "memory")
; #define PG8_WAIT_L(n) asm volatile("s_waitcnt lgkmcnt(" #n ")" ::: "memory")
; #define PG8_BAR __builtin_amdgcn_s_barrier()
; #define PG8_SCHED __builtin_amdgcn_sched_barrier(0)
; template <class Epi, class Sched, bool ALIGN_EPI = false, bool SP2 = false>
; __device__ __forceinline__ void gemm_phase(PG8_LAS unsigned char* lds, const Gemm g, const Sched& S, const Epi& E) {
;     ...
;             const bool last = (t == nt - 2);
;             const char* a1 = cA + (size_t)(t + 1) * kstep;
;             const char* a2 = last ? nA : cA + (size_t)(t + 2) * kstep; const char* b2 = last ? nB : cB + (size_t)(t + 2) * kstep;
;             const char* a3 = a2 + kstep; const char* b3 = b2 + kstep;
;             if (last && has_next) S.a_ready(nxt);
;             if constexpr (SP2) {
;             PG8_LDB(B0, 0, 0); PG8_LDB(B1, 0, 1); PG8_SCHED; PG8_LDA(At, 0, 0); PG8_STAGE(PG8_SA(1, 1), a1 + hstep, voffA);
;             PG8_WAIT_V(8); PG8_WAIT_L(0); PG8_BAR; PG8_MMA(0, 0, At, B0); PG8_MMA(0, 1, At, B1); PG8_BAR; PG8_SCHED;
;             PG8_LDA(At, 0, 1); PG8_STAGE(PG8_SB(0, 0), b2, voffB); PG8_STAGE(PG8_SB(0, 1), b2 + hstep, voffB); PG8_STAGE(PG8_SA(0, 0), a2, voffA);
.LBB0_482:
	ds_read_b128 v[76:79], v171
	ds_read_b128 v[84:87], v171 offset:1024
	ds_read_b128 v[92:95], v171 offset:2048
	ds_read_b128 v[96:99], v171 offset:3072
	ds_read_b128 v[144:147], v186
	ds_read_b128 v[148:151], v186 offset:1024
	ds_read_b128 v[152:155], v186 offset:2048
	ds_read_b128 v[156:159], v186 offset:3072
	s_add_u32 s28, s64, 0xffea0080
	s_addc_u32 s29, s65, -1
	s_cmpk_eq_i32 s77, 0x54
	s_cselect_b32 s49, s39, s29
	s_cselect_b32 s48, s38, s28
	s_cselect_b32 s29, s63, s35
	s_cselect_b32 s28, s62, s34
	v_lshl_add_u64 v[200:201], s[64:65], 0, v[172:173]
	s_add_i32 m0, s56, 0xc000
	ds_read_b128 v[178:181], v187
	ds_read_b128 v[182:185], v187 offset:1024
	ds_read_b128 v[206:209], v187 offset:2048
	ds_read_b128 v[210:213], v187 offset:3072
	ds_read_b128 v[214:217], v187 offset:4096
	ds_read_b128 v[218:221], v187 offset:5120
	ds_read_b128 v[222:225], v187 offset:6144
	ds_read_b128 v[226:229], v187 offset:7168
	global_load_lds_dwordx4 v[200:201], off
	v_lshl_add_u64 v[200:201], s[64:65], 0, v[174:175]
	s_add_i32 m0, s56, 0xe000
	s_nop 0
	global_load_lds_dwordx4 v[200:201], off
	s_waitcnt vmcnt(8)
	s_waitcnt lgkmcnt(0)
	s_barrier
	s_setprio 1
	s_waitcnt lgkmcnt(0)
	v_mfma_f32_16x16x32_bf16 v[140:143], v[76:79], v[178:181], v[140:143]
	v_mfma_f32_16x16x32_bf16 v[140:143], v[84:87], v[182:185], v[140:143]
	v_mfma_f32_16x16x32_bf16 v[136:139], v[96:99], v[182:185], v[136:139]
	v_mfma_f32_16x16x32_bf16 v[136:139], v[92:95], v[178:181], v[136:139]
	v_mfma_f32_16x16x32_bf16 v[120:123], v[92:95], v[206:209], v[120:123]
	v_mfma_f32_16x16x32_bf16 v[120:123], v[96:99], v[210:213], v[120:123]
	v_mfma_f32_16x16x32_bf16 v[124:127], v[84:87], v[210:213], v[124:127]
	v_mfma_f32_16x16x32_bf16 v[124:127], v[76:79], v[206:209], v[124:127]
	v_mfma_f32_16x16x32_bf16 v[108:111], v[76:79], v[214:217], v[108:111]
	v_mfma_f32_16x16x32_bf16 v[108:111], v[84:87], v[218:221], v[108:111]
	v_mfma_f32_16x16x32_bf16 v[104:107], v[96:99], v[218:221], v[104:107]
	v_mfma_f32_16x16x32_bf16 v[104:107], v[92:95], v[214:217], v[104:107]
	v_mfma_f32_16x16x32_bf16 v[72:75], v[92:95], v[222:225], v[72:75]
	v_mfma_f32_16x16x32_bf16 v[72:75], v[96:99], v[226:229], v[72:75]
	v_mfma_f32_16x16x32_bf16 v[80:83], v[84:87], v[226:229], v[80:83]
	v_mfma_f32_16x16x32_bf16 v[80:83], v[76:79], v[222:225], v[80:83]
	s_setprio 0
	s_setprio 1
	v_mfma_f32_16x16x32_bf16 v[132:135], v[144:147], v[178:181], v[132:135]
	v_mfma_f32_16x16x32_bf16 v[132:135], v[148:151], v[182:185], v[132:135]
	v_mfma_f32_16x16x32_bf16 v[128:131], v[156:159], v[182:185], v[128:131]
	v_mfma_f32_16x16x32_bf16 v[128:131], v[152:155], v[178:181], v[128:131]
	v_mfma_f32_16x16x32_bf16 v[112:115], v[152:155], v[206:209], v[112:115]
	v_mfma_f32_16x16x32_bf16 v[112:115], v[156:159], v[210:213], v[112:115]
	v_mfma_f32_16x16x32_bf16 v[116:119], v[148:151], v[210:213], v[116:119]
	v_mfma_f32_16x16x32_bf16 v[116:119], v[144:147], v[206:209], v[116:119]
	v_mfma_f32_16x16x32_bf16 v[100:103], v[144:147], v[214:217], v[100:103]
	v_mfma_f32_16x16x32_bf16 v[100:103], v[148:151], v[218:221], v[100:103]
	v_mfma_f32_16x16x32_bf16 v[88:91], v[156:159], v[218:221], v[88:91]
	v_mfma_f32_16x16x32_bf16 v[88:91], v[152:155], v[214:217], v[88:91]
	v_mfma_f32_16x16x32_bf16 v[64:67], v[152:155], v[222:225], v[64:67]
	v_mfma_f32_16x16x32_bf16 v[64:67], v[156:159], v[226:229], v[64:67]
	s_setprio 2
	s_barrier
	v_mfma_f32_16x16x32_bf16 v[68:71], v[148:151], v[226:229], v[68:71]
	v_mfma_f32_16x16x32_bf16 v[68:71], v[144:147], v[222:225], v[68:71]
	s_setprio 0
	s_add_i32 s44, s70, s41
	v_lshl_add_u64 v[200:201], s[28:29], 0, v[160:161]
	s_mov_b32 m0, s44
	ds_read_b128 v[178:181], v187 offset:16384
	ds_read_b128 v[182:185], v187 offset:17408
	ds_read_b128 v[206:209], v187 offset:18432
	ds_read_b128 v[210:213], v187 offset:19456
	ds_read_b128 v[214:217], v187 offset:20480
	ds_read_b128 v[218:221], v187 offset:21504
	ds_read_b128 v[222:225], v187 offset:22528
	ds_read_b128 v[226:229], v187 offset:23552
	global_load_lds_dwordx4 v[200:201], off
	s_add_i32 m0, s44, 0x2000
	s_add_u32 s78, s28, 0x160000
	v_lshl_add_u64 v[230:231], s[28:29], 0, v[162:163]
	s_addc_u32 s79, s29, 0
	s_add_i32 s44, s71, s41
	global_load_lds_dwordx4 v[230:231], off
	v_lshl_add_u64 v[232:233], s[78:79], 0, v[160:161]
	s_mov_b32 m0, s44
	v_lshl_add_u64 v[234:235], s[48:49], 0, v[162:163]
	global_load_lds_dwordx4 v[232:233], off
	v_lshl_add_u64 v[232:233], s[78:79], 0, v[162:163]
	s_add_i32 m0, s44, 0x2000
	s_nop 0
	global_load_lds_dwordx4 v[232:233], off
	v_lshl_add_u64 v[232:233], s[48:49], 0, v[160:161]
	s_mov_b32 m0, s56
	s_nop 0
	global_load_lds_dwordx4 v[232:233], off
	s_mov_b32 m0, s57
	s_nop 0
	global_load_lds_dwordx4 v[234:235], off
	s_waitcnt vmcnt(8)
	s_waitcnt lgkmcnt(0)
	s_barrier
; #define PG8_STAGE(bufoff, gbase, voff) do { _Pragma("unroll") for (int _i = 0; _i < 2; ++_i) \
;         __builtin_amdgcn_global_load_lds((const unsigned*)((const char*)(gbase) + (voff)[_i]), (PG8_LAS unsigned*)(lds + (bufoff) + ldsw + _i * 8192), 16, 0, 0); } while (0)
; #define PG8_LDA(dst, b, h) do { _Pragma("unroll") for (int m = 0; m < 4; ++m) _Pragma("unroll") for (int k = 0; k < 2; ++k) dst[m][k] = *(const PG8_LAS bf16x8*)(lds + PG8_SA(b, h) + aoff + m * 2048 + k * 1024); } while (0)
; #define PG8_LDB(dst, b, h) do { _Pragma("unroll") for (int n = 0; n < 2; ++n) _Pragma("unroll") for (int k = 0; k < 2; ++k) dst[n][k] = *(const PG8_LAS bf16x8*)(lds + PG8_SB(b, h) + boff + n * 2048 + k * 1024); } while (0)
; #define PG8_MMA(ai, bj, At, Bt) do { __builtin_amdgcn_s_setprio(1); _Pragma("unroll") for (int m = 0; m < 4; ++m) _Pragma("unroll") for (int n = 0; n < 2; ++n) _Pragma("unroll") for (int k = 0; k < 2; ++k) \
;         acc[ai][bj][m][n] = __builtin_amdgcn_mfma_f32_16x16x32_bf16(Bt[n][k], At[m][k], acc[ai][bj][m][n], 0, 0, 0); __builtin_amdgcn_s_setprio(0); } while (0)
; #define PG8_WAIT_V(n) asm volatile("s_waitcnt vmcnt(" #n ")" ::: "memory")
; #define PG8_WAIT_L(n) asm volatile("s_waitcnt lgkmcnt(" #n ")" ::: "memory")
; #define PG8_BAR __builtin_amdgcn_s_barrier()
; #define PG8_SCHED __builtin_amdgcn_sched_barrier(0)
; template <class Epi, class Sched, bool ALIGN_EPI = false, bool SP2 = false>
; __device__ __forceinline__ void gemm_phase(PG8_LAS unsigned char* lds, const Gemm g, const Sched& S, const Epi& E) {
;     ...
;             PG8_WAIT_V(8); PG8_WAIT_L(0); PG8_BAR; PG8_MMA(1, 0, At, B0); PG8_MMA(1, 1, At, B1); PG8_BAR; PG8_SCHED;
;             PG8_LDB(B0, 1, 0); PG8_LDB(B1, 1, 1); PG8_SCHED; PG8_LDA(At, 1, 0); PG8_STAGE(PG8_SA(0, 1), a2 + hstep, voffA);
;             PG8_WAIT_V(8); PG8_WAIT_L(0); PG8_BAR; PG8_MMA(0, 0, At, B0); PG8_MMA(0, 1, At, B1); PG8_BAR; PG8_SCHED;
	s_setprio 1
	s_waitcnt lgkmcnt(0)
	v_mfma_f32_16x16x32_bf16 v[60:63], v[76:79], v[178:181], v[60:63]
	v_mfma_f32_16x16x32_bf16 v[60:63], v[84:87], v[182:185], v[60:63]
	v_mfma_f32_16x16x32_bf16 v[56:59], v[96:99], v[182:185], v[56:59]
	v_mfma_f32_16x16x32_bf16 v[56:59], v[92:95], v[178:181], v[56:59]
	v_mfma_f32_16x16x32_bf16 v[40:43], v[92:95], v[206:209], v[40:43]
	v_mfma_f32_16x16x32_bf16 v[40:43], v[96:99], v[210:213], v[40:43]
	v_mfma_f32_16x16x32_bf16 v[44:47], v[84:87], v[210:213], v[44:47]
	v_mfma_f32_16x16x32_bf16 v[44:47], v[76:79], v[206:209], v[44:47]
	v_mfma_f32_16x16x32_bf16 v[28:31], v[76:79], v[214:217], v[28:31]
	v_mfma_f32_16x16x32_bf16 v[28:31], v[84:87], v[218:221], v[28:31]
	v_mfma_f32_16x16x32_bf16 v[24:27], v[96:99], v[218:221], v[24:27]
	v_mfma_f32_16x16x32_bf16 v[24:27], v[92:95], v[214:217], v[24:27]
	v_mfma_f32_16x16x32_bf16 v[8:11], v[92:95], v[222:225], v[8:11]
	v_mfma_f32_16x16x32_bf16 v[8:11], v[96:99], v[226:229], v[8:11]
	v_mfma_f32_16x16x32_bf16 v[12:15], v[84:87], v[226:229], v[12:15]
	v_mfma_f32_16x16x32_bf16 v[12:15], v[76:79], v[222:225], v[12:15]
	s_setprio 0
	s_setprio 1
	v_mfma_f32_16x16x32_bf16 v[52:55], v[144:147], v[178:181], v[52:55]
	v_mfma_f32_16x16x32_bf16 v[52:55], v[148:151], v[182:185], v[52:55]
	v_mfma_f32_16x16x32_bf16 v[48:51], v[156:159], v[182:185], v[48:51]
	v_mfma_f32_16x16x32_bf16 v[48:51], v[152:155], v[178:181], v[48:51]
	v_mfma_f32_16x16x32_bf16 v[32:35], v[152:155], v[206:209], v[32:35]
	v_mfma_f32_16x16x32_bf16 v[32:35], v[156:159], v[210:213], v[32:35]
	v_mfma_f32_16x16x32_bf16 v[36:39], v[148:151], v[210:213], v[36:39]
	v_mfma_f32_16x16x32_bf16 v[36:39], v[144:147], v[206:209], v[36:39]
	v_mfma_f32_16x16x32_bf16 v[20:23], v[144:147], v[214:217], v[20:23]
	v_mfma_f32_16x16x32_bf16 v[20:23], v[148:151], v[218:221], v[20:23]
	v_mfma_f32_16x16x32_bf16 v[16:19], v[156:159], v[218:221], v[16:19]
	v_mfma_f32_16x16x32_bf16 v[16:19], v[152:155], v[214:217], v[16:19]
	v_mfma_f32_16x16x32_bf16 v[0:3], v[152:155], v[222:225], v[0:3]
	v_mfma_f32_16x16x32_bf16 v[0:3], v[156:159], v[226:229], v[0:3]
	s_setprio 2
	s_barrier
	v_mfma_f32_16x16x32_bf16 v[4:7], v[148:151], v[226:229], v[4:7]
	v_mfma_f32_16x16x32_bf16 v[4:7], v[144:147], v[222:225], v[4:7]
	s_setprio 0
	s_add_i32 s44, 0, 0x18000
	s_add_i32 s45, 0, 0x1c000
	v_add_u32_e32 v96, s44, v167
	v_add_u32_e32 v156, s45, v167
	ds_read_b128 v[76:79], v96
	ds_read_b128 v[84:87], v96 offset:1024
	ds_read_b128 v[92:95], v96 offset:2048
	ds_read_b128 v[96:99], v96 offset:3072
	ds_read_b128 v[144:147], v156
	ds_read_b128 v[148:151], v156 offset:1024
	ds_read_b128 v[152:155], v156 offset:2048
	ds_read_b128 v[156:159], v156 offset:3072
	s_add_u32 s48, s48, 0x160000
	s_addc_u32 s49, s49, 0
	s_mov_b32 m0, s61
	v_lshl_add_u64 v[236:237], s[48:49], 0, v[160:161]
	ds_read_b128 v[178:181], v187 offset:32768
	ds_read_b128 v[182:185], v187 offset:33792
	ds_read_b128 v[206:209], v187 offset:34816
	ds_read_b128 v[210:213], v187 offset:35840
	ds_read_b128 v[214:217], v187 offset:36864
	ds_read_b128 v[218:221], v187 offset:37888
	ds_read_b128 v[222:225], v187 offset:38912
	ds_read_b128 v[226:229], v187 offset:39936
	global_load_lds_dwordx4 v[236:237], off
	v_lshl_add_u64 v[236:237], s[48:49], 0, v[162:163]
	s_mov_b32 m0, s66
	s_nop 0
	global_load_lds_dwordx4 v[236:237], off
	s_waitcnt vmcnt(8)
	s_waitcnt lgkmcnt(0)
	s_barrier
	s_setprio 1
	s_waitcnt lgkmcnt(0)
	v_mfma_f32_16x16x32_bf16 v[140:143], v[76:79], v[178:181], v[140:143]
	v_mfma_f32_16x16x32_bf16 v[140:143], v[84:87], v[182:185], v[140:143]
	v_mfma_f32_16x16x32_bf16 v[136:139], v[96:99], v[182:185], v[136:139]
	v_mfma_f32_16x16x32_bf16 v[136:139], v[92:95], v[178:181], v[136:139]
	v_mfma_f32_16x16x32_bf16 v[120:123], v[92:95], v[206:209], v[120:123]
	v_mfma_f32_16x16x32_bf16 v[120:123], v[96:99], v[210:213], v[120:123]
	v_mfma_f32_16x16x32_bf16 v[124:127], v[84:87], v[210:213], v[124:127]
	v_mfma_f32_16x16x32_bf16 v[124:127], v[76:79], v[206:209], v[124:127]
	v_mfma_f32_16x16x32_bf16 v[108:111], v[76:79], v[214:217], v[108:111]
	v_mfma_f32_16x16x32_bf16 v[108:111], v[84:87], v[218:221], v[108:111]
	v_mfma_f32_16x16x32_bf16 v[104:107], v[96:99], v[218:221], v[104:107]
	v_mfma_f32_16x16x32_bf16 v[104:107], v[92:95], v[214:217], v[104:107]
	v_mfma_f32_16x16x32_bf16 v[72:75], v[92:95], v[222:225], v[72:75]
	v_mfma_f32_16x16x32_bf16 v[72:75], v[96:99], v[226:229], v[72:75]
	v_mfma_f32_16x16x32_bf16 v[80:83], v[84:87], v[226:229], v[80:83]
	v_mfma_f32_16x16x32_bf16 v[80:83], v[76:79], v[222:225], v[80:83]
	s_setprio 0
	s_setprio 1
	v_mfma_f32_16x16x32_bf16 v[132:135], v[144:147], v[178:181], v[132:135]
	v_mfma_f32_16x16x32_bf16 v[132:135], v[148:151], v[182:185], v[132:135]
	v_mfma_f32_16x16x32_bf16 v[128:131], v[156:159], v[182:185], v[128:131]
	v_mfma_f32_16x16x32_bf16 v[128:131], v[152:155], v[178:181], v[128:131]
	v_mfma_f32_16x16x32_bf16 v[112:115], v[152:155], v[206:209], v[112:115]
	v_mfma_f32_16x16x32_bf16 v[112:115], v[156:159], v[210:213], v[112:115]
	v_mfma_f32_16x16x32_bf16 v[116:119], v[148:151], v[210:213], v[116:119]
	v_mfma_f32_16x16x32_bf16 v[116:119], v[144:147], v[206:209], v[116:119]
	v_mfma_f32_16x16x32_bf16 v[100:103], v[144:147], v[214:217], v[100:103]
	v_mfma_f32_16x16x32_bf16 v[100:103], v[148:151], v[218:221], v[100:103]
	v_mfma_f32_16x16x32_bf16 v[88:91], v[156:159], v[218:221], v[88:91]
	v_mfma_f32_16x16x32_bf16 v[88:91], v[152:155], v[214:217], v[88:91]
	v_mfma_f32_16x16x32_bf16 v[64:67], v[152:155], v[222:225], v[64:67]
	v_mfma_f32_16x16x32_bf16 v[64:67], v[156:159], v[226:229], v[64:67]
	s_setprio 2
	s_barrier
; #define PG8_STAGE(bufoff, gbase, voff) do { _Pragma("unroll") for (int _i = 0; _i < 2; ++_i) \
;         __builtin_amdgcn_global_load_lds((const unsigned*)((const char*)(gbase) + (voff)[_i]), (PG8_LAS unsigned*)(lds + (bufoff) + ldsw + _i * 8192), 16, 0, 0); } while (0)
; #define PG8_LDA(dst, b, h) do { _Pragma("unroll") for (int m = 0; m < 4; ++m) _Pragma("unroll") for (int k = 0; k < 2; ++k) dst[m][k] = *(const PG8_LAS bf16x8*)(lds + PG8_SA(b, h) + aoff + m * 2048 + k * 1024); } while (0)
; #define PG8_MMA(ai, bj, At, Bt) do { __builtin_amdgcn_s_setprio(1); _Pragma("unroll") for (int m = 0; m < 4; ++m) _Pragma("unroll") for (int n = 0; n < 2; ++n) _Pragma("unroll") for (int k = 0; k < 2; ++k) \
;         acc[ai][bj][m][n] = __builtin_amdgcn_mfma_f32_16x16x32_bf16(Bt[n][k], At[m][k], acc[ai][bj][m][n], 0, 0, 0); __builtin_amdgcn_s_setprio(0); } while (0)
; #define PG8_WAIT_V(n) asm volatile("s_waitcnt vmcnt(" #n ")" ::: "memory")
; #define PG8_WAIT_L(n) asm volatile("s_waitcnt lgkmcnt(" #n ")" ::: "memory")
; #define PG8_BAR __builtin_amdgcn_s_barrier()
; #define PG8_SCHED __builtin_amdgcn_sched_barrier(0)
; template <class Epi, class Sched, bool ALIGN_EPI = false, bool SP2 = false>
; __device__ __forceinline__ void gemm_phase(PG8_LAS unsigned char* lds, const Gemm g, const Sched& S, const Epi& E) {
;     ...
;             PG8_LDA(At, 1, 1); PG8_STAGE(PG8_SB(1, 0), b3, voffB); PG8_STAGE(PG8_SB(1, 1), b3 + hstep, voffB); PG8_STAGE(PG8_SA(1, 0), a3, voffA);
;             PG8_WAIT_V(8); PG8_WAIT_L(0); PG8_BAR; PG8_MMA(1, 0, At, B0); PG8_MMA(1, 1, At, B1); PG8_BAR; PG8_SCHED;
;     ...
;         if constexpr (ALIGN_EPI) { if (wr == 0) PG8_BAR; }
;         if constexpr (!Epi::AFTER_DRAIN) { E(acc, cur, wr, wc, fr, fq); S.done(cur); }
;         if (!has_next) break;
	v_mfma_f32_16x16x32_bf16 v[68:71], v[148:151], v[226:229], v[68:71]
	v_mfma_f32_16x16x32_bf16 v[68:71], v[144:147], v[222:225], v[68:71]
	s_setprio 0
	s_add_i32 s44, s44, s41
	v_lshl_add_u64 v[200:201], v[200:201], 0, s[20:21]
	s_mov_b32 m0, s44
	ds_read_b128 v[178:181], v187 offset:49152
	ds_read_b128 v[182:185], v187 offset:50176
	ds_read_b128 v[206:209], v187 offset:51200
	ds_read_b128 v[210:213], v187 offset:52224
	ds_read_b128 v[214:217], v187 offset:53248
	ds_read_b128 v[218:221], v187 offset:54272
	ds_read_b128 v[222:225], v187 offset:55296
	ds_read_b128 v[226:229], v187 offset:56320
	global_load_lds_dwordx4 v[200:201], off
	s_add_i32 m0, s44, 0x2000
	s_add_u32 s28, s28, 0x160080
	v_lshl_add_u64 v[200:201], v[230:231], 0, s[20:21]
	s_addc_u32 s29, s29, 0
	s_add_i32 s44, s45, s41
	global_load_lds_dwordx4 v[200:201], off
	v_lshl_add_u64 v[200:201], s[28:29], 0, v[160:161]
	s_mov_b32 m0, s44
	s_nop 0
	global_load_lds_dwordx4 v[200:201], off
	v_lshl_add_u64 v[200:201], s[28:29], 0, v[162:163]
	s_add_i32 m0, s44, 0x2000
	s_nop 0
	global_load_lds_dwordx4 v[200:201], off
	v_lshl_add_u64 v[200:201], v[232:233], 0, s[20:21]
	s_mov_b32 m0, s67
	s_nop 0
	global_load_lds_dwordx4 v[200:201], off
	v_lshl_add_u64 v[200:201], v[234:235], 0, s[20:21]
	s_mov_b32 m0, s68
	s_nop 0
	global_load_lds_dwordx4 v[200:201], off
	s_waitcnt vmcnt(8)
	s_waitcnt lgkmcnt(0)
	s_barrier
	s_setprio 1
	s_waitcnt lgkmcnt(0)
	v_mfma_f32_16x16x32_bf16 v[60:63], v[76:79], v[178:181], v[60:63]
	v_mfma_f32_16x16x32_bf16 v[60:63], v[84:87], v[182:185], v[60:63]
	v_mfma_f32_16x16x32_bf16 v[56:59], v[96:99], v[182:185], v[56:59]
	v_mfma_f32_16x16x32_bf16 v[56:59], v[92:95], v[178:181], v[56:59]
	v_mfma_f32_16x16x32_bf16 v[40:43], v[92:95], v[206:209], v[40:43]
	v_mfma_f32_16x16x32_bf16 v[40:43], v[96:99], v[210:213], v[40:43]
	v_mfma_f32_16x16x32_bf16 v[44:47], v[84:87], v[210:213], v[44:47]
	v_mfma_f32_16x16x32_bf16 v[44:47], v[76:79], v[206:209], v[44:47]
	v_mfma_f32_16x16x32_bf16 v[28:31], v[76:79], v[214:217], v[28:31]
	v_mfma_f32_16x16x32_bf16 v[28:31], v[84:87], v[218:221], v[28:31]
	v_mfma_f32_16x16x32_bf16 v[24:27], v[96:99], v[218:221], v[24:27]
	v_mfma_f32_16x16x32_bf16 v[24:27], v[92:95], v[214:217], v[24:27]
	v_mfma_f32_16x16x32_bf16 v[8:11], v[92:95], v[222:225], v[8:11]
	v_mfma_f32_16x16x32_bf16 v[8:11], v[96:99], v[226:229], v[8:11]
	v_mfma_f32_16x16x32_bf16 v[12:15], v[84:87], v[226:229], v[12:15]
	v_mfma_f32_16x16x32_bf16 v[12:15], v[76:79], v[222:225], v[12:15]
	s_setprio 0
	s_setprio 1
	v_mfma_f32_16x16x32_bf16 v[52:55], v[144:147], v[178:181], v[52:55]
	v_mfma_f32_16x16x32_bf16 v[52:55], v[148:151], v[182:185], v[52:55]
	v_mfma_f32_16x16x32_bf16 v[48:51], v[156:159], v[182:185], v[48:51]
	v_mfma_f32_16x16x32_bf16 v[48:51], v[152:155], v[178:181], v[48:51]
	v_mfma_f32_16x16x32_bf16 v[32:35], v[152:155], v[206:209], v[32:35]
	v_mfma_f32_16x16x32_bf16 v[32:35], v[156:159], v[210:213], v[32:35]
	v_mfma_f32_16x16x32_bf16 v[36:39], v[148:151], v[210:213], v[36:39]
	v_mfma_f32_16x16x32_bf16 v[36:39], v[144:147], v[206:209], v[36:39]
	v_mfma_f32_16x16x32_bf16 v[20:23], v[144:147], v[214:217], v[20:23]
	v_mfma_f32_16x16x32_bf16 v[20:23], v[148:151], v[218:221], v[20:23]
	v_mfma_f32_16x16x32_bf16 v[16:19], v[156:159], v[218:221], v[16:19]
	v_mfma_f32_16x16x32_bf16 v[16:19], v[152:155], v[214:217], v[16:19]
	v_mfma_f32_16x16x32_bf16 v[0:3], v[152:155], v[222:225], v[0:3]
	v_mfma_f32_16x16x32_bf16 v[0:3], v[156:159], v[226:229], v[0:3]
	s_setprio 2
	s_barrier
	v_mfma_f32_16x16x32_bf16 v[4:7], v[148:151], v[226:229], v[4:7]
	v_mfma_f32_16x16x32_bf16 v[4:7], v[144:147], v[222:225], v[4:7]
	s_setprio 0
	s_add_i32 s77, s77, 2
	s_add_u32 s64, s64, 0x100
	s_addc_u32 s65, s65, 0
	s_add_u32 s34, s34, 0x100
	s_addc_u32 s35, s35, 0
	s_cmpk_gt_u32 s77, 0x55
	s_cbranch_scc0 .LBB0_482
	s_and_b64 vcc, exec, s[22:23]
	s_cbranch_vccz .LBB0_485
	s_barrier

; #define PG8_STAGE(bufoff, gbase, voff) do { _Pragma("unroll") for (int _i = 0; _i < 2; ++_i) \
;         __builtin_amdgcn_global_load_lds((const unsigned*)((const char*)(gbase) + (voff)[_i]), (PG8_LAS unsigned*)(lds + (bufoff) + ldsw + _i * 8192), 16, 0, 0); } while (0)
; #define PG8_LDA(dst, b, h) do { _Pragma("unroll") for (int m = 0; m < 4; ++m) _Pragma("unroll") for (int k = 0; k < 2; ++k) dst[m][k] = *(const PG8_LAS bf16x8*)(lds + PG8_SA(b, h) + aoff + m * 2048 + k * 1024); } while (0)
; #define PG8_LDB(dst, b, h) do { _Pragma("unroll") for (int n = 0; n < 2; ++n) _Pragma("unroll") for (int k = 0; k < 2; ++k) dst[n][k] = *(const PG8_LAS bf16x8*)(lds + PG8_SB(b, h) + boff + n * 2048 + k * 1024); } while (0)
; #define PG8_MMA(ai, bj, At, Bt) do { __builtin_amdgcn_s_setprio(1); _Pragma("unroll") for (int m = 0; m < 4; ++m) _Pragma("unroll") for (int n = 0; n < 2; ++n) _Pragma("unroll") for (int k = 0; k < 2; ++k) \
;         acc[ai][bj][m][n] = __builtin_amdgcn_mfma_f32_16x16x32_bf16(Bt[n][k], At[m][k], acc[ai][bj][m][n], 0, 0, 0); __builtin_amdgcn_s_setprio(0); } while (0)
; #define PG8_WAIT_V(n) asm volatile("s_waitcnt vmcnt(" #n ")" ::: "memory")
; #define PG8_WAIT_L(n) asm volatile("s_waitcnt lgkmcnt(" #n ")" ::: "memory")
; #define PG8_BAR __builtin_amdgcn_s_barrier()
; #define PG8_SCHED __builtin_amdgcn_sched_barrier(0)
; template <class Epi, class Sched, bool ALIGN_EPI = false, bool SP2 = false>
; __device__ __forceinline__ void gemm_phase(PG8_LAS unsigned char* lds, const Gemm g, const Sched& S, const Epi& E) {
;     ...
;             const bool last = (t == nt - 2);
;             const char* a1 = cA + (size_t)(t + 1) * kstep;
;             const char* a2 = last ? nA : cA + (size_t)(t + 2) * kstep; const char* b2 = last ? nB : cB + (size_t)(t + 2) * kstep;
;             const char* a3 = a2 + kstep; const char* b3 = b2 + kstep;
;             if (last && has_next) S.a_ready(nxt);
;             if constexpr (SP2) {
;             PG8_LDB(B0, 0, 0); PG8_LDB(B1, 0, 1); PG8_SCHED; PG8_LDA(At, 0, 0); PG8_STAGE(PG8_SA(1, 1), a1 + hstep, voffA);
;             PG8_WAIT_V(8); PG8_WAIT_L(0); PG8_BAR; PG8_MMA(0, 0, At, B0); PG8_MMA(0, 1, At, B1); PG8_BAR; PG8_SCHED;
;             PG8_LDA(At, 0, 1); PG8_STAGE(PG8_SB(0, 0), b2, voffB); PG8_STAGE(PG8_SB(0, 1), b2 + hstep, voffB); PG8_STAGE(PG8_SA(0, 0), a2, voffA);
.LBB0_536:
	ds_read_b128 v[136:139], v156
	ds_read_b128 v[140:143], v156 offset:1024
	ds_read_b128 v[172:175], v156 offset:2048
	ds_read_b128 v[176:179], v156 offset:3072
	ds_read_b128 v[180:183], v157
	ds_read_b128 v[184:187], v157 offset:1024
	ds_read_b128 v[206:209], v157 offset:2048
	ds_read_b128 v[210:213], v157 offset:3072
	s_add_u32 s28, s66, 0xfff80080
	s_addc_u32 s29, s67, -1
	s_cmp_eq_u32 s79, 28
	s_cselect_b32 s49, s34, s29
	s_cselect_b32 s48, s35, s28
	s_cselect_b32 s29, s23, s78
	s_cselect_b32 s28, s39, s77
	v_lshl_add_u64 v[200:201], s[66:67], 0, v[128:129]
	s_add_i32 m0, s11, 0xc000
	ds_read_b128 v[214:217], v158
	ds_read_b128 v[218:221], v158 offset:1024
	ds_read_b128 v[222:225], v158 offset:2048
	ds_read_b128 v[226:229], v158 offset:3072
	ds_read_b128 v[230:233], v158 offset:4096
	ds_read_b128 v[234:237], v158 offset:5120
	ds_read_b128 v[238:241], v158 offset:6144
	ds_read_b128 v[242:245], v158 offset:7168
	global_load_lds_dwordx4 v[200:201], off
	v_lshl_add_u64 v[200:201], s[66:67], 0, v[130:131]
	s_add_i32 m0, s11, 0xe000
	s_nop 0
	global_load_lds_dwordx4 v[200:201], off
	s_waitcnt vmcnt(8)
	s_waitcnt lgkmcnt(0)
	s_barrier
	s_setprio 1
	s_waitcnt lgkmcnt(0)
	v_mfma_f32_16x16x32_bf16 v[124:127], v[136:139], v[214:217], v[124:127]
	v_mfma_f32_16x16x32_bf16 v[124:127], v[140:143], v[218:221], v[124:127]
	v_mfma_f32_16x16x32_bf16 v[120:123], v[176:179], v[218:221], v[120:123]
	v_mfma_f32_16x16x32_bf16 v[120:123], v[172:175], v[214:217], v[120:123]
	v_mfma_f32_16x16x32_bf16 v[104:107], v[172:175], v[222:225], v[104:107]
	v_mfma_f32_16x16x32_bf16 v[104:107], v[176:179], v[226:229], v[104:107]
	v_mfma_f32_16x16x32_bf16 v[108:111], v[140:143], v[226:229], v[108:111]
	v_mfma_f32_16x16x32_bf16 v[108:111], v[136:139], v[222:225], v[108:111]
	v_mfma_f32_16x16x32_bf16 v[96:99], v[136:139], v[230:233], v[96:99]
	v_mfma_f32_16x16x32_bf16 v[96:99], v[140:143], v[234:237], v[96:99]
	v_mfma_f32_16x16x32_bf16 v[88:91], v[176:179], v[234:237], v[88:91]
	v_mfma_f32_16x16x32_bf16 v[88:91], v[172:175], v[230:233], v[88:91]
	v_mfma_f32_16x16x32_bf16 v[72:75], v[172:175], v[238:241], v[72:75]
	v_mfma_f32_16x16x32_bf16 v[72:75], v[176:179], v[242:245], v[72:75]
	v_mfma_f32_16x16x32_bf16 v[80:83], v[140:143], v[242:245], v[80:83]
	v_mfma_f32_16x16x32_bf16 v[80:83], v[136:139], v[238:241], v[80:83]
	s_setprio 0
	s_setprio 1
	v_mfma_f32_16x16x32_bf16 v[116:119], v[180:183], v[214:217], v[116:119]
	v_mfma_f32_16x16x32_bf16 v[116:119], v[184:187], v[218:221], v[116:119]
	v_mfma_f32_16x16x32_bf16 v[112:115], v[210:213], v[218:221], v[112:115]
	v_mfma_f32_16x16x32_bf16 v[112:115], v[206:209], v[214:217], v[112:115]
	v_mfma_f32_16x16x32_bf16 v[92:95], v[206:209], v[222:225], v[92:95]
	v_mfma_f32_16x16x32_bf16 v[92:95], v[210:213], v[226:229], v[92:95]
	v_mfma_f32_16x16x32_bf16 v[100:103], v[184:187], v[226:229], v[100:103]
	v_mfma_f32_16x16x32_bf16 v[100:103], v[180:183], v[222:225], v[100:103]
	v_mfma_f32_16x16x32_bf16 v[84:87], v[180:183], v[230:233], v[84:87]
	v_mfma_f32_16x16x32_bf16 v[84:87], v[184:187], v[234:237], v[84:87]
	v_mfma_f32_16x16x32_bf16 v[76:79], v[210:213], v[234:237], v[76:79]
	v_mfma_f32_16x16x32_bf16 v[76:79], v[206:209], v[230:233], v[76:79]
	v_mfma_f32_16x16x32_bf16 v[64:67], v[206:209], v[238:241], v[64:67]
	v_mfma_f32_16x16x32_bf16 v[64:67], v[210:213], v[242:245], v[64:67]
	s_setprio 2
	s_barrier
	v_mfma_f32_16x16x32_bf16 v[68:71], v[184:187], v[242:245], v[68:71]
	v_mfma_f32_16x16x32_bf16 v[68:71], v[180:183], v[238:241], v[68:71]
	s_setprio 0
	s_add_i32 s44, s72, s41
	v_lshl_add_u64 v[200:201], s[28:29], 0, v[166:167]
	s_mov_b32 m0, s44
	ds_read_b128 v[214:217], v158 offset:16384
	ds_read_b128 v[218:221], v158 offset:17408
	ds_read_b128 v[222:225], v158 offset:18432
	ds_read_b128 v[226:229], v158 offset:19456
	ds_read_b128 v[230:233], v158 offset:20480
	ds_read_b128 v[234:237], v158 offset:21504
	ds_read_b128 v[238:241], v158 offset:22528
	ds_read_b128 v[242:245], v158 offset:23552
	global_load_lds_dwordx4 v[200:201], off
	s_add_i32 m0, s44, 0x2000
	s_add_u32 s80, s28, 0x80000
	v_lshl_add_u64 v[246:247], s[28:29], 0, v[170:171]
	s_addc_u32 s81, s29, 0
	s_add_i32 s44, s73, s41
	global_load_lds_dwordx4 v[246:247], off
	v_lshl_add_u64 v[248:249], s[80:81], 0, v[166:167]
	s_mov_b32 m0, s44
	v_lshl_add_u64 v[250:251], s[48:49], 0, v[168:169]
	global_load_lds_dwordx4 v[248:249], off
	v_lshl_add_u64 v[248:249], s[80:81], 0, v[170:171]
	s_add_i32 m0, s44, 0x2000
	s_nop 0
	global_load_lds_dwordx4 v[248:249], off
	v_lshl_add_u64 v[248:249], s[48:49], 0, v[164:165]
	s_mov_b32 m0, s11
	s_nop 0
	global_load_lds_dwordx4 v[248:249], off
	s_mov_b32 m0, s57
	s_nop 0
	global_load_lds_dwordx4 v[250:251], off
	s_waitcnt vmcnt(8)
	s_waitcnt lgkmcnt(0)
	s_barrier
; #define PG8_STAGE(bufoff, gbase, voff) do { _Pragma("unroll") for (int _i = 0; _i < 2; ++_i) \
;         __builtin_amdgcn_global_load_lds((const unsigned*)((const char*)(gbase) + (voff)[_i]), (PG8_LAS unsigned*)(lds + (bufoff) + ldsw + _i * 8192), 16, 0, 0); } while (0)
; #define PG8_LDA(dst, b, h) do { _Pragma("unroll") for (int m = 0; m < 4; ++m) _Pragma("unroll") for (int k = 0; k < 2; ++k) dst[m][k] = *(const PG8_LAS bf16x8*)(lds + PG8_SA(b, h) + aoff + m * 2048 + k * 1024); } while (0)
; #define PG8_LDB(dst, b, h) do { _Pragma("unroll") for (int n = 0; n < 2; ++n) _Pragma("unroll") for (int k = 0; k < 2; ++k) dst[n][k] = *(const PG8_LAS bf16x8*)(lds + PG8_SB(b, h) + boff + n * 2048 + k * 1024); } while (0)
; #define PG8_MMA(ai, bj, At, Bt) do { __builtin_amdgcn_s_setprio(1); _Pragma("unroll") for (int m = 0; m < 4; ++m) _Pragma("unroll") for (int n = 0; n < 2; ++n) _Pragma("unroll") for (int k = 0; k < 2; ++k) \
;         acc[ai][bj][m][n] = __builtin_amdgcn_mfma_f32_16x16x32_bf16(Bt[n][k], At[m][k], acc[ai][bj][m][n], 0, 0, 0); __builtin_amdgcn_s_setprio(0); } while (0)
; #define PG8_WAIT_V(n) asm volatile("s_waitcnt vmcnt(" #n ")" ::: "memory")
; #define PG8_WAIT_L(n) asm volatile("s_waitcnt lgkmcnt(" #n ")" ::: "memory")
; #define PG8_BAR __builtin_amdgcn_s_barrier()
; #define PG8_SCHED __builtin_amdgcn_sched_barrier(0)
; template <class Epi, class Sched, bool ALIGN_EPI = false, bool SP2 = false>
; __device__ __forceinline__ void gemm_phase(PG8_LAS unsigned char* lds, const Gemm g, const Sched& S, const Epi& E) {
;     ...
;             PG8_WAIT_V(8); PG8_WAIT_L(0); PG8_BAR; PG8_MMA(1, 0, At, B0); PG8_MMA(1, 1, At, B1); PG8_BAR; PG8_SCHED;
;             PG8_LDB(B0, 1, 0); PG8_LDB(B1, 1, 1); PG8_SCHED; PG8_LDA(At, 1, 0); PG8_STAGE(PG8_SA(0, 1), a2 + hstep, voffA);
;             PG8_WAIT_V(8); PG8_WAIT_L(0); PG8_BAR; PG8_MMA(0, 0, At, B0); PG8_MMA(0, 1, At, B1); PG8_BAR; PG8_SCHED;
	s_setprio 1
	s_waitcnt lgkmcnt(0)
	v_mfma_f32_16x16x32_bf16 v[60:63], v[136:139], v[214:217], v[60:63]
	v_mfma_f32_16x16x32_bf16 v[60:63], v[140:143], v[218:221], v[60:63]
	v_mfma_f32_16x16x32_bf16 v[56:59], v[176:179], v[218:221], v[56:59]
	v_mfma_f32_16x16x32_bf16 v[56:59], v[172:175], v[214:217], v[56:59]
	v_mfma_f32_16x16x32_bf16 v[40:43], v[172:175], v[222:225], v[40:43]
	v_mfma_f32_16x16x32_bf16 v[40:43], v[176:179], v[226:229], v[40:43]
	v_mfma_f32_16x16x32_bf16 v[48:51], v[140:143], v[226:229], v[48:51]
	v_mfma_f32_16x16x32_bf16 v[48:51], v[136:139], v[222:225], v[48:51]
	v_mfma_f32_16x16x32_bf16 v[32:35], v[136:139], v[230:233], v[32:35]
	v_mfma_f32_16x16x32_bf16 v[32:35], v[140:143], v[234:237], v[32:35]
	v_mfma_f32_16x16x32_bf16 v[24:27], v[176:179], v[234:237], v[24:27]
	v_mfma_f32_16x16x32_bf16 v[24:27], v[172:175], v[230:233], v[24:27]
	v_mfma_f32_16x16x32_bf16 v[8:11], v[172:175], v[238:241], v[8:11]
	v_mfma_f32_16x16x32_bf16 v[8:11], v[176:179], v[242:245], v[8:11]
	v_mfma_f32_16x16x32_bf16 v[12:15], v[140:143], v[242:245], v[12:15]
	v_mfma_f32_16x16x32_bf16 v[12:15], v[136:139], v[238:241], v[12:15]
	s_setprio 0
	s_setprio 1
	v_mfma_f32_16x16x32_bf16 v[52:55], v[180:183], v[214:217], v[52:55]
	v_mfma_f32_16x16x32_bf16 v[52:55], v[184:187], v[218:221], v[52:55]
	v_mfma_f32_16x16x32_bf16 v[44:47], v[210:213], v[218:221], v[44:47]
	v_mfma_f32_16x16x32_bf16 v[44:47], v[206:209], v[214:217], v[44:47]
	v_mfma_f32_16x16x32_bf16 v[28:31], v[206:209], v[222:225], v[28:31]
	v_mfma_f32_16x16x32_bf16 v[28:31], v[210:213], v[226:229], v[28:31]
	v_mfma_f32_16x16x32_bf16 v[36:39], v[184:187], v[226:229], v[36:39]
	v_mfma_f32_16x16x32_bf16 v[36:39], v[180:183], v[222:225], v[36:39]
	v_mfma_f32_16x16x32_bf16 v[20:23], v[180:183], v[230:233], v[20:23]
	v_mfma_f32_16x16x32_bf16 v[20:23], v[184:187], v[234:237], v[20:23]
	v_mfma_f32_16x16x32_bf16 v[16:19], v[210:213], v[234:237], v[16:19]
	v_mfma_f32_16x16x32_bf16 v[16:19], v[206:209], v[230:233], v[16:19]
	v_mfma_f32_16x16x32_bf16 v[0:3], v[206:209], v[238:241], v[0:3]
	v_mfma_f32_16x16x32_bf16 v[0:3], v[210:213], v[242:245], v[0:3]
	s_setprio 2
	s_barrier
	v_mfma_f32_16x16x32_bf16 v[4:7], v[184:187], v[242:245], v[4:7]
	v_mfma_f32_16x16x32_bf16 v[4:7], v[180:183], v[238:241], v[4:7]
	s_setprio 0
	s_add_i32 s44, 0, 0x18000
	v_add_u32_e32 v144, s44, v146
	s_add_i32 s45, 0, 0x1c000
	ds_read_b128 v[136:139], v144
	ds_read_b128 v[140:143], v144 offset:1024
	ds_read_b128 v[172:175], v144 offset:2048
	ds_read_b128 v[176:179], v144 offset:3072
	v_add_u32_e32 v144, s45, v146
	ds_read_b128 v[180:183], v144
	ds_read_b128 v[184:187], v144 offset:1024
	ds_read_b128 v[206:209], v144 offset:2048
	ds_read_b128 v[210:213], v144 offset:3072
	s_add_u32 s48, s48, 0x80000
	s_addc_u32 s49, s49, 0
	s_mov_b32 m0, s61
	v_lshl_add_u64 v[252:253], s[48:49], 0, v[164:165]
	ds_read_b128 v[214:217], v158 offset:32768
	ds_read_b128 v[218:221], v158 offset:33792
	ds_read_b128 v[222:225], v158 offset:34816
	ds_read_b128 v[226:229], v158 offset:35840
	ds_read_b128 v[230:233], v158 offset:36864
	ds_read_b128 v[234:237], v158 offset:37888
	ds_read_b128 v[238:241], v158 offset:38912
	ds_read_b128 v[242:245], v158 offset:39936
	global_load_lds_dwordx4 v[252:253], off
	v_lshl_add_u64 v[252:253], s[48:49], 0, v[168:169]
	s_mov_b32 m0, s68
	s_nop 0
	global_load_lds_dwordx4 v[252:253], off
	s_waitcnt vmcnt(8)
	s_waitcnt lgkmcnt(0)
	s_barrier
	s_setprio 1
	s_waitcnt lgkmcnt(0)
	v_mfma_f32_16x16x32_bf16 v[124:127], v[136:139], v[214:217], v[124:127]
	v_mfma_f32_16x16x32_bf16 v[124:127], v[140:143], v[218:221], v[124:127]
	v_mfma_f32_16x16x32_bf16 v[120:123], v[176:179], v[218:221], v[120:123]
	v_mfma_f32_16x16x32_bf16 v[120:123], v[172:175], v[214:217], v[120:123]
	v_mfma_f32_16x16x32_bf16 v[104:107], v[172:175], v[222:225], v[104:107]
	v_mfma_f32_16x16x32_bf16 v[104:107], v[176:179], v[226:229], v[104:107]
	v_mfma_f32_16x16x32_bf16 v[108:111], v[140:143], v[226:229], v[108:111]
	v_mfma_f32_16x16x32_bf16 v[108:111], v[136:139], v[222:225], v[108:111]
	v_mfma_f32_16x16x32_bf16 v[96:99], v[136:139], v[230:233], v[96:99]
	v_mfma_f32_16x16x32_bf16 v[96:99], v[140:143], v[234:237], v[96:99]
	v_mfma_f32_16x16x32_bf16 v[88:91], v[176:179], v[234:237], v[88:91]
	v_mfma_f32_16x16x32_bf16 v[88:91], v[172:175], v[230:233], v[88:91]
	v_mfma_f32_16x16x32_bf16 v[72:75], v[172:175], v[238:241], v[72:75]
	v_mfma_f32_16x16x32_bf16 v[72:75], v[176:179], v[242:245], v[72:75]
	v_mfma_f32_16x16x32_bf16 v[80:83], v[140:143], v[242:245], v[80:83]
	v_mfma_f32_16x16x32_bf16 v[80:83], v[136:139], v[238:241], v[80:83]
	s_setprio 0
	s_setprio 1
	v_mfma_f32_16x16x32_bf16 v[116:119], v[180:183], v[214:217], v[116:119]
	v_mfma_f32_16x16x32_bf16 v[116:119], v[184:187], v[218:221], v[116:119]
	v_mfma_f32_16x16x32_bf16 v[112:115], v[210:213], v[218:221], v[112:115]
	v_mfma_f32_16x16x32_bf16 v[112:115], v[206:209], v[214:217], v[112:115]
	v_mfma_f32_16x16x32_bf16 v[92:95], v[206:209], v[222:225], v[92:95]
	v_mfma_f32_16x16x32_bf16 v[92:95], v[210:213], v[226:229], v[92:95]
	v_mfma_f32_16x16x32_bf16 v[100:103], v[184:187], v[226:229], v[100:103]
	v_mfma_f32_16x16x32_bf16 v[100:103], v[180:183], v[222:225], v[100:103]
	v_mfma_f32_16x16x32_bf16 v[84:87], v[180:183], v[230:233], v[84:87]
	v_mfma_f32_16x16x32_bf16 v[84:87], v[184:187], v[234:237], v[84:87]
	v_mfma_f32_16x16x32_bf16 v[76:79], v[210:213], v[234:237], v[76:79]
	v_mfma_f32_16x16x32_bf16 v[76:79], v[206:209], v[230:233], v[76:79]
	v_mfma_f32_16x16x32_bf16 v[64:67], v[206:209], v[238:241], v[64:67]
	v_mfma_f32_16x16x32_bf16 v[64:67], v[210:213], v[242:245], v[64:67]
	s_setprio 2
	s_barrier
; #define PG8_STAGE(bufoff, gbase, voff) do { _Pragma("unroll") for (int _i = 0; _i < 2; ++_i) \
;         __builtin_amdgcn_global_load_lds((const unsigned*)((const char*)(gbase) + (voff)[_i]), (PG8_LAS unsigned*)(lds + (bufoff) + ldsw + _i * 8192), 16, 0, 0); } while (0)
; #define PG8_LDA(dst, b, h) do { _Pragma("unroll") for (int m = 0; m < 4; ++m) _Pragma("unroll") for (int k = 0; k < 2; ++k) dst[m][k] = *(const PG8_LAS bf16x8*)(lds + PG8_SA(b, h) + aoff + m * 2048 + k * 1024); } while (0)
; #define PG8_MMA(ai, bj, At, Bt) do { __builtin_amdgcn_s_setprio(1); _Pragma("unroll") for (int m = 0; m < 4; ++m) _Pragma("unroll") for (int n = 0; n < 2; ++n) _Pragma("unroll") for (int k = 0; k < 2; ++k) \
;         acc[ai][bj][m][n] = __builtin_amdgcn_mfma_f32_16x16x32_bf16(Bt[n][k], At[m][k], acc[ai][bj][m][n], 0, 0, 0); __builtin_amdgcn_s_setprio(0); } while (0)
; #define PG8_WAIT_V(n) asm volatile("s_waitcnt vmcnt(" #n ")" ::: "memory")
; #define PG8_WAIT_L(n) asm volatile("s_waitcnt lgkmcnt(" #n ")" ::: "memory")
; #define PG8_BAR __builtin_amdgcn_s_barrier()
; #define PG8_SCHED __builtin_amdgcn_sched_barrier(0)
; template <class Epi, class Sched, bool ALIGN_EPI = false, bool SP2 = false>
; __device__ __forceinline__ void gemm_phase(PG8_LAS unsigned char* lds, const Gemm g, const Sched& S, const Epi& E) {
;     ...
;             PG8_LDA(At, 1, 1); PG8_STAGE(PG8_SB(1, 0), b3, voffB); PG8_STAGE(PG8_SB(1, 1), b3 + hstep, voffB); PG8_STAGE(PG8_SA(1, 0), a3, voffA);
;             PG8_WAIT_V(8); PG8_WAIT_L(0); PG8_BAR; PG8_MMA(1, 0, At, B0); PG8_MMA(1, 1, At, B1); PG8_BAR; PG8_SCHED;
;     ...
;         if constexpr (ALIGN_EPI) { if (wr == 0) PG8_BAR; }
;         if constexpr (!Epi::AFTER_DRAIN) { E(acc, cur, wr, wc, fr, fq); S.done(cur); }
;         if (!has_next) break;
	v_mfma_f32_16x16x32_bf16 v[68:71], v[184:187], v[242:245], v[68:71]
	v_mfma_f32_16x16x32_bf16 v[68:71], v[180:183], v[238:241], v[68:71]
	s_setprio 0
	s_add_i32 s44, s44, s41
	v_lshl_add_u64 v[200:201], v[200:201], 0, s[18:19]
	s_mov_b32 m0, s44
	ds_read_b128 v[214:217], v158 offset:49152
	ds_read_b128 v[218:221], v158 offset:50176
	ds_read_b128 v[222:225], v158 offset:51200
	ds_read_b128 v[226:229], v158 offset:52224
	ds_read_b128 v[230:233], v158 offset:53248
	ds_read_b128 v[234:237], v158 offset:54272
	ds_read_b128 v[238:241], v158 offset:55296
	ds_read_b128 v[242:245], v158 offset:56320
	global_load_lds_dwordx4 v[200:201], off
	s_add_i32 m0, s44, 0x2000
	s_add_u32 s28, s28, 0x80080
	v_lshl_add_u64 v[200:201], v[246:247], 0, s[18:19]
	s_addc_u32 s29, s29, 0
	s_add_i32 s44, s45, s41
	global_load_lds_dwordx4 v[200:201], off
	v_lshl_add_u64 v[200:201], s[28:29], 0, v[166:167]
	s_mov_b32 m0, s44
	s_nop 0
	global_load_lds_dwordx4 v[200:201], off
	v_lshl_add_u64 v[200:201], s[28:29], 0, v[170:171]
	s_add_i32 m0, s44, 0x2000
	s_nop 0
	global_load_lds_dwordx4 v[200:201], off
	v_lshl_add_u64 v[200:201], v[248:249], 0, s[18:19]
	s_mov_b32 m0, s70
	s_nop 0
	global_load_lds_dwordx4 v[200:201], off
	v_lshl_add_u64 v[200:201], v[250:251], 0, s[18:19]
	s_mov_b32 m0, s71
	s_nop 0
	global_load_lds_dwordx4 v[200:201], off
	s_waitcnt vmcnt(8)
	s_waitcnt lgkmcnt(0)
	s_barrier
	s_setprio 1
	s_waitcnt lgkmcnt(0)
	v_mfma_f32_16x16x32_bf16 v[60:63], v[136:139], v[214:217], v[60:63]
	v_mfma_f32_16x16x32_bf16 v[60:63], v[140:143], v[218:221], v[60:63]
	v_mfma_f32_16x16x32_bf16 v[56:59], v[176:179], v[218:221], v[56:59]
	v_mfma_f32_16x16x32_bf16 v[56:59], v[172:175], v[214:217], v[56:59]
	v_mfma_f32_16x16x32_bf16 v[40:43], v[172:175], v[222:225], v[40:43]
	v_mfma_f32_16x16x32_bf16 v[40:43], v[176:179], v[226:229], v[40:43]
	v_mfma_f32_16x16x32_bf16 v[48:51], v[140:143], v[226:229], v[48:51]
	v_mfma_f32_16x16x32_bf16 v[48:51], v[136:139], v[222:225], v[48:51]
	v_mfma_f32_16x16x32_bf16 v[32:35], v[136:139], v[230:233], v[32:35]
	v_mfma_f32_16x16x32_bf16 v[32:35], v[140:143], v[234:237], v[32:35]
	v_mfma_f32_16x16x32_bf16 v[24:27], v[176:179], v[234:237], v[24:27]
	v_mfma_f32_16x16x32_bf16 v[24:27], v[172:175], v[230:233], v[24:27]
	v_mfma_f32_16x16x32_bf16 v[8:11], v[172:175], v[238:241], v[8:11]
	v_mfma_f32_16x16x32_bf16 v[8:11], v[176:179], v[242:245], v[8:11]
	v_mfma_f32_16x16x32_bf16 v[12:15], v[140:143], v[242:245], v[12:15]
	v_mfma_f32_16x16x32_bf16 v[12:15], v[136:139], v[238:241], v[12:15]
	s_setprio 0
	s_setprio 1
	v_mfma_f32_16x16x32_bf16 v[52:55], v[180:183], v[214:217], v[52:55]
	v_mfma_f32_16x16x32_bf16 v[52:55], v[184:187], v[218:221], v[52:55]
	v_mfma_f32_16x16x32_bf16 v[44:47], v[210:213], v[218:221], v[44:47]
	v_mfma_f32_16x16x32_bf16 v[44:47], v[206:209], v[214:217], v[44:47]
	v_mfma_f32_16x16x32_bf16 v[28:31], v[206:209], v[222:225], v[28:31]
	v_mfma_f32_16x16x32_bf16 v[28:31], v[210:213], v[226:229], v[28:31]
	v_mfma_f32_16x16x32_bf16 v[36:39], v[184:187], v[226:229], v[36:39]
	v_mfma_f32_16x16x32_bf16 v[36:39], v[180:183], v[222:225], v[36:39]
	v_mfma_f32_16x16x32_bf16 v[20:23], v[180:183], v[230:233], v[20:23]
	v_mfma_f32_16x16x32_bf16 v[20:23], v[184:187], v[234:237], v[20:23]
	v_mfma_f32_16x16x32_bf16 v[16:19], v[210:213], v[234:237], v[16:19]
	v_mfma_f32_16x16x32_bf16 v[16:19], v[206:209], v[230:233], v[16:19]
	v_mfma_f32_16x16x32_bf16 v[0:3], v[206:209], v[238:241], v[0:3]
	v_mfma_f32_16x16x32_bf16 v[0:3], v[210:213], v[242:245], v[0:3]
	s_setprio 2
	s_barrier
	v_mfma_f32_16x16x32_bf16 v[4:7], v[184:187], v[242:245], v[4:7]
	v_mfma_f32_16x16x32_bf16 v[4:7], v[180:183], v[238:241], v[4:7]
	s_setprio 0
	s_add_i32 s79, s79, 2
	s_add_u32 s66, s66, 0x100
	s_addc_u32 s67, s67, 0
	s_add_u32 s77, s77, 0x100
	s_addc_u32 s78, s78, 0
	s_cmp_gt_u32 s79, 29
	s_cbranch_scc0 .LBB0_536
	s_and_b64 vcc, exec, s[20:21]
	s_cbranch_vccz .LBB0_539
	s_barrier

; #define PG8_STAGE(bufoff, gbase, voff) do { _Pragma("unroll") for (int _i = 0; _i < 2; ++_i) \
;         __builtin_amdgcn_global_load_lds((const unsigned*)((const char*)(gbase) + (voff)[_i]), (PG8_LAS unsigned*)(lds + (bufoff) + ldsw + _i * 8192), 16, 0, 0); } while (0)
; #define PG8_LDA(dst, b, h) do { _Pragma("unroll") for (int m = 0; m < 4; ++m) _Pragma("unroll") for (int k = 0; k < 2; ++k) dst[m][k] = *(const PG8_LAS bf16x8*)(lds + PG8_SA(b, h) + aoff + m * 2048 + k * 1024); } while (0)
; #define PG8_LDB(dst, b, h) do { _Pragma("unroll") for (int n = 0; n < 2; ++n) _Pragma("unroll") for (int k = 0; k < 2; ++k) dst[n][k] = *(const PG8_LAS bf16x8*)(lds + PG8_SB(b, h) + boff + n * 2048 + k * 1024); } while (0)
; #define PG8_MMA(ai, bj, At, Bt) do { __builtin_amdgcn_s_setprio(1); _Pragma("unroll") for (int m = 0; m < 4; ++m) _Pragma("unroll") for (int n = 0; n < 2; ++n) _Pragma("unroll") for (int k = 0; k < 2; ++k) \
;         acc[ai][bj][m][n] = __builtin_amdgcn_mfma_f32_16x16x32_bf16(Bt[n][k], At[m][k], acc[ai][bj][m][n], 0, 0, 0); __builtin_amdgcn_s_setprio(0); } while (0)
; #define PG8_WAIT_V(n) asm volatile("s_waitcnt vmcnt(" #n ")" ::: "memory")
; #define PG8_WAIT_L(n) asm volatile("s_waitcnt lgkmcnt(" #n ")" ::: "memory")
; #define PG8_BAR __builtin_amdgcn_s_barrier()
; #define PG8_SCHED __builtin_amdgcn_sched_barrier(0)
; template <class Epi, class Sched, bool ALIGN_EPI = false, bool SP2 = false>
; __device__ __forceinline__ void gemm_phase(PG8_LAS unsigned char* lds, const Gemm g, const Sched& S, const Epi& E) {
;     ...
;             const bool last = (t == nt - 2);
;             const char* a1 = cA + (size_t)(t + 1) * kstep;
;             const char* a2 = last ? nA : cA + (size_t)(t + 2) * kstep; const char* b2 = last ? nB : cB + (size_t)(t + 2) * kstep;
;             const char* a3 = a2 + kstep; const char* b3 = b2 + kstep;
;             if (last && has_next) S.a_ready(nxt);
;             if constexpr (SP2) {
;             PG8_LDB(B0, 0, 0); PG8_LDB(B1, 0, 1); PG8_SCHED; PG8_LDA(At, 0, 0); PG8_STAGE(PG8_SA(1, 1), a1 + hstep, voffA);
;             PG8_WAIT_V(8); PG8_WAIT_L(0); PG8_BAR; PG8_MMA(0, 0, At, B0); PG8_MMA(0, 1, At, B1); PG8_BAR; PG8_SCHED;
;             PG8_LDA(At, 0, 1); PG8_STAGE(PG8_SB(0, 0), b2, voffB); PG8_STAGE(PG8_SB(0, 1), b2 + hstep, voffB); PG8_STAGE(PG8_SA(0, 0), a2, voffA);
.LBB0_602:
	ds_read_b128 v[76:79], v171
	ds_read_b128 v[84:87], v171 offset:1024
	ds_read_b128 v[92:95], v171 offset:2048
	ds_read_b128 v[96:99], v171 offset:3072
	ds_read_b128 v[144:147], v186
	ds_read_b128 v[148:151], v186 offset:1024
	ds_read_b128 v[152:155], v186 offset:2048
	ds_read_b128 v[156:159], v186 offset:3072
	s_add_u32 s28, s62, 0xffea0080
	s_addc_u32 s29, s63, -1
	s_cmpk_eq_i32 s77, 0x54
	s_cselect_b32 s49, s39, s29
	s_cselect_b32 s48, s38, s28
	s_cselect_b32 s29, s41, s35
	s_cselect_b32 s28, s40, s34
	v_lshl_add_u64 v[200:201], s[62:63], 0, v[172:173]
	s_add_i32 m0, s61, 0xc000
	ds_read_b128 v[178:181], v187
	ds_read_b128 v[182:185], v187 offset:1024
	ds_read_b128 v[206:209], v187 offset:2048
	ds_read_b128 v[210:213], v187 offset:3072
	ds_read_b128 v[214:217], v187 offset:4096
	ds_read_b128 v[218:221], v187 offset:5120
	ds_read_b128 v[222:225], v187 offset:6144
	ds_read_b128 v[226:229], v187 offset:7168
	global_load_lds_dwordx4 v[200:201], off
	v_lshl_add_u64 v[200:201], s[62:63], 0, v[174:175]
	s_add_i32 m0, s61, 0xe000
	s_nop 0
	global_load_lds_dwordx4 v[200:201], off
	s_waitcnt vmcnt(8)
	s_waitcnt lgkmcnt(0)
	s_barrier
	s_setprio 1
	s_waitcnt lgkmcnt(0)
	v_mfma_f32_16x16x32_bf16 v[140:143], v[76:79], v[178:181], v[140:143]
	v_mfma_f32_16x16x32_bf16 v[140:143], v[84:87], v[182:185], v[140:143]
	v_mfma_f32_16x16x32_bf16 v[136:139], v[96:99], v[182:185], v[136:139]
	v_mfma_f32_16x16x32_bf16 v[136:139], v[92:95], v[178:181], v[136:139]
	v_mfma_f32_16x16x32_bf16 v[120:123], v[92:95], v[206:209], v[120:123]
	v_mfma_f32_16x16x32_bf16 v[120:123], v[96:99], v[210:213], v[120:123]
	v_mfma_f32_16x16x32_bf16 v[124:127], v[84:87], v[210:213], v[124:127]
	v_mfma_f32_16x16x32_bf16 v[124:127], v[76:79], v[206:209], v[124:127]
	v_mfma_f32_16x16x32_bf16 v[108:111], v[76:79], v[214:217], v[108:111]
	v_mfma_f32_16x16x32_bf16 v[108:111], v[84:87], v[218:221], v[108:111]
	v_mfma_f32_16x16x32_bf16 v[104:107], v[96:99], v[218:221], v[104:107]
	v_mfma_f32_16x16x32_bf16 v[104:107], v[92:95], v[214:217], v[104:107]
	v_mfma_f32_16x16x32_bf16 v[72:75], v[92:95], v[222:225], v[72:75]
	v_mfma_f32_16x16x32_bf16 v[72:75], v[96:99], v[226:229], v[72:75]
	v_mfma_f32_16x16x32_bf16 v[80:83], v[84:87], v[226:229], v[80:83]
	v_mfma_f32_16x16x32_bf16 v[80:83], v[76:79], v[222:225], v[80:83]
	s_setprio 0
	s_setprio 1
	v_mfma_f32_16x16x32_bf16 v[132:135], v[144:147], v[178:181], v[132:135]
	v_mfma_f32_16x16x32_bf16 v[132:135], v[148:151], v[182:185], v[132:135]
	v_mfma_f32_16x16x32_bf16 v[128:131], v[156:159], v[182:185], v[128:131]
	v_mfma_f32_16x16x32_bf16 v[128:131], v[152:155], v[178:181], v[128:131]
	v_mfma_f32_16x16x32_bf16 v[112:115], v[152:155], v[206:209], v[112:115]
	v_mfma_f32_16x16x32_bf16 v[112:115], v[156:159], v[210:213], v[112:115]
	v_mfma_f32_16x16x32_bf16 v[116:119], v[148:151], v[210:213], v[116:119]
	v_mfma_f32_16x16x32_bf16 v[116:119], v[144:147], v[206:209], v[116:119]
	v_mfma_f32_16x16x32_bf16 v[100:103], v[144:147], v[214:217], v[100:103]
	v_mfma_f32_16x16x32_bf16 v[100:103], v[148:151], v[218:221], v[100:103]
	v_mfma_f32_16x16x32_bf16 v[88:91], v[156:159], v[218:221], v[88:91]
	v_mfma_f32_16x16x32_bf16 v[88:91], v[152:155], v[214:217], v[88:91]
	v_mfma_f32_16x16x32_bf16 v[64:67], v[152:155], v[222:225], v[64:67]
	v_mfma_f32_16x16x32_bf16 v[64:67], v[156:159], v[226:229], v[64:67]
	s_setprio 2
	s_barrier
	v_mfma_f32_16x16x32_bf16 v[68:71], v[148:151], v[226:229], v[68:71]
	v_mfma_f32_16x16x32_bf16 v[68:71], v[144:147], v[222:225], v[68:71]
	s_setprio 0
	s_add_i32 s44, s70, s57
	v_lshl_add_u64 v[200:201], s[28:29], 0, v[160:161]
	s_mov_b32 m0, s44
	ds_read_b128 v[178:181], v187 offset:16384
	ds_read_b128 v[182:185], v187 offset:17408
	ds_read_b128 v[206:209], v187 offset:18432
	ds_read_b128 v[210:213], v187 offset:19456
	ds_read_b128 v[214:217], v187 offset:20480
	ds_read_b128 v[218:221], v187 offset:21504
	ds_read_b128 v[222:225], v187 offset:22528
	ds_read_b128 v[226:229], v187 offset:23552
	global_load_lds_dwordx4 v[200:201], off
	s_add_i32 m0, s44, 0x2000
	s_add_u32 s78, s28, 0x160000
	v_lshl_add_u64 v[230:231], s[28:29], 0, v[162:163]
	s_addc_u32 s79, s29, 0
	s_add_i32 s44, s71, s57
	global_load_lds_dwordx4 v[230:231], off
	v_lshl_add_u64 v[232:233], s[78:79], 0, v[160:161]
	s_mov_b32 m0, s44
	v_lshl_add_u64 v[234:235], s[48:49], 0, v[162:163]
	global_load_lds_dwordx4 v[232:233], off
	v_lshl_add_u64 v[232:233], s[78:79], 0, v[162:163]
	s_add_i32 m0, s44, 0x2000
	s_nop 0
	global_load_lds_dwordx4 v[232:233], off
	v_lshl_add_u64 v[232:233], s[48:49], 0, v[160:161]
	s_mov_b32 m0, s61
	s_nop 0
	global_load_lds_dwordx4 v[232:233], off
	s_mov_b32 m0, s64
	s_nop 0
	global_load_lds_dwordx4 v[234:235], off
	s_waitcnt vmcnt(8)
	s_waitcnt lgkmcnt(0)
	s_barrier
; #define PG8_STAGE(bufoff, gbase, voff) do { _Pragma("unroll") for (int _i = 0; _i < 2; ++_i) \
;         __builtin_amdgcn_global_load_lds((const unsigned*)((const char*)(gbase) + (voff)[_i]), (PG8_LAS unsigned*)(lds + (bufoff) + ldsw + _i * 8192), 16, 0, 0); } while (0)
; #define PG8_LDA(dst, b, h) do { _Pragma("unroll") for (int m = 0; m < 4; ++m) _Pragma("unroll") for (int k = 0; k < 2; ++k) dst[m][k] = *(const PG8_LAS bf16x8*)(lds + PG8_SA(b, h) + aoff + m * 2048 + k * 1024); } while (0)
; #define PG8_LDB(dst, b, h) do { _Pragma("unroll") for (int n = 0; n < 2; ++n) _Pragma("unroll") for (int k = 0; k < 2; ++k) dst[n][k] = *(const PG8_LAS bf16x8*)(lds + PG8_SB(b, h) + boff + n * 2048 + k * 1024); } while (0)
; #define PG8_MMA(ai, bj, At, Bt) do { __builtin_amdgcn_s_setprio(1); _Pragma("unroll") for (int m = 0; m < 4; ++m) _Pragma("unroll") for (int n = 0; n < 2; ++n) _Pragma("unroll") for (int k = 0; k < 2; ++k) \
;         acc[ai][bj][m][n] = __builtin_amdgcn_mfma_f32_16x16x32_bf16(Bt[n][k], At[m][k], acc[ai][bj][m][n], 0, 0, 0); __builtin_amdgcn_s_setprio(0); } while (0)
; #define PG8_WAIT_V(n) asm volatile("s_waitcnt vmcnt(" #n ")" ::: "memory")
; #define PG8_WAIT_L(n) asm volatile("s_waitcnt lgkmcnt(" #n ")" ::: "memory")
; #define PG8_BAR __builtin_amdgcn_s_barrier()
; #define PG8_SCHED __builtin_amdgcn_sched_barrier(0)
; template <class Epi, class Sched, bool ALIGN_EPI = false, bool SP2 = false>
; __device__ __forceinline__ void gemm_phase(PG8_LAS unsigned char* lds, const Gemm g, const Sched& S, const Epi& E) {
;     ...
;             PG8_WAIT_V(8); PG8_WAIT_L(0); PG8_BAR; PG8_MMA(1, 0, At, B0); PG8_MMA(1, 1, At, B1); PG8_BAR; PG8_SCHED;
;             PG8_LDB(B0, 1, 0); PG8_LDB(B1, 1, 1); PG8_SCHED; PG8_LDA(At, 1, 0); PG8_STAGE(PG8_SA(0, 1), a2 + hstep, voffA);
;             PG8_WAIT_V(8); PG8_WAIT_L(0); PG8_BAR; PG8_MMA(0, 0, At, B0); PG8_MMA(0, 1, At, B1); PG8_BAR; PG8_SCHED;
	s_setprio 1
	s_waitcnt lgkmcnt(0)
	v_mfma_f32_16x16x32_bf16 v[60:63], v[76:79], v[178:181], v[60:63]
	v_mfma_f32_16x16x32_bf16 v[60:63], v[84:87], v[182:185], v[60:63]
	v_mfma_f32_16x16x32_bf16 v[56:59], v[96:99], v[182:185], v[56:59]
	v_mfma_f32_16x16x32_bf16 v[56:59], v[92:95], v[178:181], v[56:59]
	v_mfma_f32_16x16x32_bf16 v[40:43], v[92:95], v[206:209], v[40:43]
	v_mfma_f32_16x16x32_bf16 v[40:43], v[96:99], v[210:213], v[40:43]
	v_mfma_f32_16x16x32_bf16 v[44:47], v[84:87], v[210:213], v[44:47]
	v_mfma_f32_16x16x32_bf16 v[44:47], v[76:79], v[206:209], v[44:47]
	v_mfma_f32_16x16x32_bf16 v[28:31], v[76:79], v[214:217], v[28:31]
	v_mfma_f32_16x16x32_bf16 v[28:31], v[84:87], v[218:221], v[28:31]
	v_mfma_f32_16x16x32_bf16 v[24:27], v[96:99], v[218:221], v[24:27]
	v_mfma_f32_16x16x32_bf16 v[24:27], v[92:95], v[214:217], v[24:27]
	v_mfma_f32_16x16x32_bf16 v[8:11], v[92:95], v[222:225], v[8:11]
	v_mfma_f32_16x16x32_bf16 v[8:11], v[96:99], v[226:229], v[8:11]
	v_mfma_f32_16x16x32_bf16 v[12:15], v[84:87], v[226:229], v[12:15]
	v_mfma_f32_16x16x32_bf16 v[12:15], v[76:79], v[222:225], v[12:15]
	s_setprio 0
	s_setprio 1
	v_mfma_f32_16x16x32_bf16 v[52:55], v[144:147], v[178:181], v[52:55]
	v_mfma_f32_16x16x32_bf16 v[52:55], v[148:151], v[182:185], v[52:55]
	v_mfma_f32_16x16x32_bf16 v[48:51], v[156:159], v[182:185], v[48:51]
	v_mfma_f32_16x16x32_bf16 v[48:51], v[152:155], v[178:181], v[48:51]
	v_mfma_f32_16x16x32_bf16 v[32:35], v[152:155], v[206:209], v[32:35]
	v_mfma_f32_16x16x32_bf16 v[32:35], v[156:159], v[210:213], v[32:35]
	v_mfma_f32_16x16x32_bf16 v[36:39], v[148:151], v[210:213], v[36:39]
	v_mfma_f32_16x16x32_bf16 v[36:39], v[144:147], v[206:209], v[36:39]
	v_mfma_f32_16x16x32_bf16 v[20:23], v[144:147], v[214:217], v[20:23]
	v_mfma_f32_16x16x32_bf16 v[20:23], v[148:151], v[218:221], v[20:23]
	v_mfma_f32_16x16x32_bf16 v[16:19], v[156:159], v[218:221], v[16:19]
	v_mfma_f32_16x16x32_bf16 v[16:19], v[152:155], v[214:217], v[16:19]
	v_mfma_f32_16x16x32_bf16 v[0:3], v[152:155], v[222:225], v[0:3]
	v_mfma_f32_16x16x32_bf16 v[0:3], v[156:159], v[226:229], v[0:3]
	s_setprio 2
	s_barrier
	v_mfma_f32_16x16x32_bf16 v[4:7], v[148:151], v[226:229], v[4:7]
	v_mfma_f32_16x16x32_bf16 v[4:7], v[144:147], v[222:225], v[4:7]
	s_setprio 0
	s_add_i32 s44, 0, 0x18000
	s_add_i32 s45, 0, 0x1c000
	v_add_u32_e32 v96, s44, v167
	v_add_u32_e32 v156, s45, v167
	ds_read_b128 v[76:79], v96
	ds_read_b128 v[84:87], v96 offset:1024
	ds_read_b128 v[92:95], v96 offset:2048
	ds_read_b128 v[96:99], v96 offset:3072
	ds_read_b128 v[144:147], v156
	ds_read_b128 v[148:151], v156 offset:1024
	ds_read_b128 v[152:155], v156 offset:2048
	ds_read_b128 v[156:159], v156 offset:3072
	s_add_u32 s48, s48, 0x160000
	s_addc_u32 s49, s49, 0
	s_mov_b32 m0, s65
	v_lshl_add_u64 v[236:237], s[48:49], 0, v[160:161]
	ds_read_b128 v[178:181], v187 offset:32768
	ds_read_b128 v[182:185], v187 offset:33792
	ds_read_b128 v[206:209], v187 offset:34816
	ds_read_b128 v[210:213], v187 offset:35840
	ds_read_b128 v[214:217], v187 offset:36864
	ds_read_b128 v[218:221], v187 offset:37888
	ds_read_b128 v[222:225], v187 offset:38912
	ds_read_b128 v[226:229], v187 offset:39936
	global_load_lds_dwordx4 v[236:237], off
	v_lshl_add_u64 v[236:237], s[48:49], 0, v[162:163]
	s_mov_b32 m0, s66
	s_nop 0
	global_load_lds_dwordx4 v[236:237], off
	s_waitcnt vmcnt(8)
	s_waitcnt lgkmcnt(0)
	s_barrier
	s_setprio 1
	s_waitcnt lgkmcnt(0)
	v_mfma_f32_16x16x32_bf16 v[140:143], v[76:79], v[178:181], v[140:143]
	v_mfma_f32_16x16x32_bf16 v[140:143], v[84:87], v[182:185], v[140:143]
	v_mfma_f32_16x16x32_bf16 v[136:139], v[96:99], v[182:185], v[136:139]
	v_mfma_f32_16x16x32_bf16 v[136:139], v[92:95], v[178:181], v[136:139]
	v_mfma_f32_16x16x32_bf16 v[120:123], v[92:95], v[206:209], v[120:123]
	v_mfma_f32_16x16x32_bf16 v[120:123], v[96:99], v[210:213], v[120:123]
	v_mfma_f32_16x16x32_bf16 v[124:127], v[84:87], v[210:213], v[124:127]
	v_mfma_f32_16x16x32_bf16 v[124:127], v[76:79], v[206:209], v[124:127]
	v_mfma_f32_16x16x32_bf16 v[108:111], v[76:79], v[214:217], v[108:111]
	v_mfma_f32_16x16x32_bf16 v[108:111], v[84:87], v[218:221], v[108:111]
	v_mfma_f32_16x16x32_bf16 v[104:107], v[96:99], v[218:221], v[104:107]
	v_mfma_f32_16x16x32_bf16 v[104:107], v[92:95], v[214:217], v[104:107]
	v_mfma_f32_16x16x32_bf16 v[72:75], v[92:95], v[222:225], v[72:75]
	v_mfma_f32_16x16x32_bf16 v[72:75], v[96:99], v[226:229], v[72:75]
	v_mfma_f32_16x16x32_bf16 v[80:83], v[84:87], v[226:229], v[80:83]
	v_mfma_f32_16x16x32_bf16 v[80:83], v[76:79], v[222:225], v[80:83]
	s_setprio 0
	s_setprio 1
	v_mfma_f32_16x16x32_bf16 v[132:135], v[144:147], v[178:181], v[132:135]
	v_mfma_f32_16x16x32_bf16 v[132:135], v[148:151], v[182:185], v[132:135]
	v_mfma_f32_16x16x32_bf16 v[128:131], v[156:159], v[182:185], v[128:131]
	v_mfma_f32_16x16x32_bf16 v[128:131], v[152:155], v[178:181], v[128:131]
	v_mfma_f32_16x16x32_bf16 v[112:115], v[152:155], v[206:209], v[112:115]
	v_mfma_f32_16x16x32_bf16 v[112:115], v[156:159], v[210:213], v[112:115]
	v_mfma_f32_16x16x32_bf16 v[116:119], v[148:151], v[210:213], v[116:119]
	v_mfma_f32_16x16x32_bf16 v[116:119], v[144:147], v[206:209], v[116:119]
	v_mfma_f32_16x16x32_bf16 v[100:103], v[144:147], v[214:217], v[100:103]
	v_mfma_f32_16x16x32_bf16 v[100:103], v[148:151], v[218:221], v[100:103]
	v_mfma_f32_16x16x32_bf16 v[88:91], v[156:159], v[218:221], v[88:91]
	v_mfma_f32_16x16x32_bf16 v[88:91], v[152:155], v[214:217], v[88:91]
	v_mfma_f32_16x16x32_bf16 v[64:67], v[152:155], v[222:225], v[64:67]
	v_mfma_f32_16x16x32_bf16 v[64:67], v[156:159], v[226:229], v[64:67]
	s_setprio 2
	s_barrier
; #define PG8_STAGE(bufoff, gbase, voff) do { _Pragma("unroll") for (int _i = 0; _i < 2; ++_i) \
;         __builtin_amdgcn_global_load_lds((const unsigned*)((const char*)(gbase) + (voff)[_i]), (PG8_LAS unsigned*)(lds + (bufoff) + ldsw + _i * 8192), 16, 0, 0); } while (0)
; #define PG8_LDA(dst, b, h) do { _Pragma("unroll") for (int m = 0; m < 4; ++m) _Pragma("unroll") for (int k = 0; k < 2; ++k) dst[m][k] = *(const PG8_LAS bf16x8*)(lds + PG8_SA(b, h) + aoff + m * 2048 + k * 1024); } while (0)
; #define PG8_MMA(ai, bj, At, Bt) do { __builtin_amdgcn_s_setprio(1); _Pragma("unroll") for (int m = 0; m < 4; ++m) _Pragma("unroll") for (int n = 0; n < 2; ++n) _Pragma("unroll") for (int k = 0; k < 2; ++k) \
;         acc[ai][bj][m][n] = __builtin_amdgcn_mfma_f32_16x16x32_bf16(Bt[n][k], At[m][k], acc[ai][bj][m][n], 0, 0, 0); __builtin_amdgcn_s_setprio(0); } while (0)
; #define PG8_WAIT_V(n) asm volatile("s_waitcnt vmcnt(" #n ")" ::: "memory")
; #define PG8_WAIT_L(n) asm volatile("s_waitcnt lgkmcnt(" #n ")" ::: "memory")
; #define PG8_BAR __builtin_amdgcn_s_barrier()
; #define PG8_SCHED __builtin_amdgcn_sched_barrier(0)
; template <class Epi, class Sched, bool ALIGN_EPI = false, bool SP2 = false>
; __device__ __forceinline__ void gemm_phase(PG8_LAS unsigned char* lds, const Gemm g, const Sched& S, const Epi& E) {
;     ...
;             PG8_LDA(At, 1, 1); PG8_STAGE(PG8_SB(1, 0), b3, voffB); PG8_STAGE(PG8_SB(1, 1), b3 + hstep, voffB); PG8_STAGE(PG8_SA(1, 0), a3, voffA);
;             PG8_WAIT_V(8); PG8_WAIT_L(0); PG8_BAR; PG8_MMA(1, 0, At, B0); PG8_MMA(1, 1, At, B1); PG8_BAR; PG8_SCHED;
;     ...
;         if constexpr (ALIGN_EPI) { if (wr == 0) PG8_BAR; }
;         if constexpr (!Epi::AFTER_DRAIN) { E(acc, cur, wr, wc, fr, fq); S.done(cur); }
;         if (!has_next) break;
	v_mfma_f32_16x16x32_bf16 v[68:71], v[148:151], v[226:229], v[68:71]
	v_mfma_f32_16x16x32_bf16 v[68:71], v[144:147], v[222:225], v[68:71]
	s_setprio 0
	s_add_i32 s44, s44, s57
	v_lshl_add_u64 v[200:201], v[200:201], 0, s[20:21]
	s_mov_b32 m0, s44
	ds_read_b128 v[178:181], v187 offset:49152
	ds_read_b128 v[182:185], v187 offset:50176
	ds_read_b128 v[206:209], v187 offset:51200
	ds_read_b128 v[210:213], v187 offset:52224
	ds_read_b128 v[214:217], v187 offset:53248
	ds_read_b128 v[218:221], v187 offset:54272
	ds_read_b128 v[222:225], v187 offset:55296
	ds_read_b128 v[226:229], v187 offset:56320
	global_load_lds_dwordx4 v[200:201], off
	s_add_i32 m0, s44, 0x2000
	s_add_u32 s28, s28, 0x160080
	v_lshl_add_u64 v[200:201], v[230:231], 0, s[20:21]
	s_addc_u32 s29, s29, 0
	s_add_i32 s44, s45, s57
	global_load_lds_dwordx4 v[200:201], off
	v_lshl_add_u64 v[200:201], s[28:29], 0, v[160:161]
	s_mov_b32 m0, s44
	s_nop 0
	global_load_lds_dwordx4 v[200:201], off
	v_lshl_add_u64 v[200:201], s[28:29], 0, v[162:163]
	s_add_i32 m0, s44, 0x2000
	s_nop 0
	global_load_lds_dwordx4 v[200:201], off
	v_lshl_add_u64 v[200:201], v[232:233], 0, s[20:21]
	s_mov_b32 m0, s67
	s_nop 0
	global_load_lds_dwordx4 v[200:201], off
	v_lshl_add_u64 v[200:201], v[234:235], 0, s[20:21]
	s_mov_b32 m0, s68
	s_nop 0
	global_load_lds_dwordx4 v[200:201], off
	s_waitcnt vmcnt(8)
	s_waitcnt lgkmcnt(0)
	s_barrier
	s_setprio 1
	s_waitcnt lgkmcnt(0)
	v_mfma_f32_16x16x32_bf16 v[60:63], v[76:79], v[178:181], v[60:63]
	v_mfma_f32_16x16x32_bf16 v[60:63], v[84:87], v[182:185], v[60:63]
	v_mfma_f32_16x16x32_bf16 v[56:59], v[96:99], v[182:185], v[56:59]
	v_mfma_f32_16x16x32_bf16 v[56:59], v[92:95], v[178:181], v[56:59]
	v_mfma_f32_16x16x32_bf16 v[40:43], v[92:95], v[206:209], v[40:43]
	v_mfma_f32_16x16x32_bf16 v[40:43], v[96:99], v[210:213], v[40:43]
	v_mfma_f32_16x16x32_bf16 v[44:47], v[84:87], v[210:213], v[44:47]
	v_mfma_f32_16x16x32_bf16 v[44:47], v[76:79], v[206:209], v[44:47]
	v_mfma_f32_16x16x32_bf16 v[28:31], v[76:79], v[214:217], v[28:31]
	v_mfma_f32_16x16x32_bf16 v[28:31], v[84:87], v[218:221], v[28:31]
	v_mfma_f32_16x16x32_bf16 v[24:27], v[96:99], v[218:221], v[24:27]
	v_mfma_f32_16x16x32_bf16 v[24:27], v[92:95], v[214:217], v[24:27]
	v_mfma_f32_16x16x32_bf16 v[8:11], v[92:95], v[222:225], v[8:11]
	v_mfma_f32_16x16x32_bf16 v[8:11], v[96:99], v[226:229], v[8:11]
	v_mfma_f32_16x16x32_bf16 v[12:15], v[84:87], v[226:229], v[12:15]
	v_mfma_f32_16x16x32_bf16 v[12:15], v[76:79], v[222:225], v[12:15]
	s_setprio 0
	s_setprio 1
	v_mfma_f32_16x16x32_bf16 v[52:55], v[144:147], v[178:181], v[52:55]
	v_mfma_f32_16x16x32_bf16 v[52:55], v[148:151], v[182:185], v[52:55]
	v_mfma_f32_16x16x32_bf16 v[48:51], v[156:159], v[182:185], v[48:51]
	v_mfma_f32_16x16x32_bf16 v[48:51], v[152:155], v[178:181], v[48:51]
	v_mfma_f32_16x16x32_bf16 v[32:35], v[152:155], v[206:209], v[32:35]
	v_mfma_f32_16x16x32_bf16 v[32:35], v[156:159], v[210:213], v[32:35]
	v_mfma_f32_16x16x32_bf16 v[36:39], v[148:151], v[210:213], v[36:39]
	v_mfma_f32_16x16x32_bf16 v[36:39], v[144:147], v[206:209], v[36:39]
	v_mfma_f32_16x16x32_bf16 v[20:23], v[144:147], v[214:217], v[20:23]
	v_mfma_f32_16x16x32_bf16 v[20:23], v[148:151], v[218:221], v[20:23]
	v_mfma_f32_16x16x32_bf16 v[16:19], v[156:159], v[218:221], v[16:19]
	v_mfma_f32_16x16x32_bf16 v[16:19], v[152:155], v[214:217], v[16:19]
	v_mfma_f32_16x16x32_bf16 v[0:3], v[152:155], v[222:225], v[0:3]
	v_mfma_f32_16x16x32_bf16 v[0:3], v[156:159], v[226:229], v[0:3]
	s_setprio 2
	s_barrier
	v_mfma_f32_16x16x32_bf16 v[4:7], v[148:151], v[226:229], v[4:7]
	v_mfma_f32_16x16x32_bf16 v[4:7], v[144:147], v[222:225], v[4:7]
	s_setprio 0
	s_add_i32 s77, s77, 2
	s_add_u32 s62, s62, 0x100
	s_addc_u32 s63, s63, 0
	s_add_u32 s34, s34, 0x100
	s_addc_u32 s35, s35, 0
	s_cmpk_gt_u32 s77, 0x55
	s_cbranch_scc0 .LBB0_602
	s_and_b64 vcc, exec, s[22:23]
	s_cbranch_vccz .LBB0_605
	s_barrier

; #define PG8_STAGE(bufoff, gbase, voff) do { _Pragma("unroll") for (int _i = 0; _i < 2; ++_i) \
;         __builtin_amdgcn_global_load_lds((const unsigned*)((const char*)(gbase) + (voff)[_i]), (PG8_LAS unsigned*)(lds + (bufoff) + ldsw + _i * 8192), 16, 0, 0); } while (0)
; #define PG8_LDA(dst, b, h) do { _Pragma("unroll") for (int m = 0; m < 4; ++m) _Pragma("unroll") for (int k = 0; k < 2; ++k) dst[m][k] = *(const PG8_LAS bf16x8*)(lds + PG8_SA(b, h) + aoff + m * 2048 + k * 1024); } while (0)
; #define PG8_LDB(dst, b, h) do { _Pragma("unroll") for (int n = 0; n < 2; ++n) _Pragma("unroll") for (int k = 0; k < 2; ++k) dst[n][k] = *(const PG8_LAS bf16x8*)(lds + PG8_SB(b, h) + boff + n * 2048 + k * 1024); } while (0)
; #define PG8_MMA(ai, bj, At, Bt) do { __builtin_amdgcn_s_setprio(1); _Pragma("unroll") for (int m = 0; m < 4; ++m) _Pragma("unroll") for (int n = 0; n < 2; ++n) _Pragma("unroll") for (int k = 0; k < 2; ++k) \
;         acc[ai][bj][m][n] = __builtin_amdgcn_mfma_f32_16x16x32_bf16(Bt[n][k], At[m][k], acc[ai][bj][m][n], 0, 0, 0); __builtin_amdgcn_s_setprio(0); } while (0)
; #define PG8_WAIT_V(n) asm volatile("s_waitcnt vmcnt(" #n ")" ::: "memory")
; #define PG8_WAIT_L(n) asm volatile("s_waitcnt lgkmcnt(" #n ")" ::: "memory")
; #define PG8_BAR __builtin_amdgcn_s_barrier()
; #define PG8_SCHED __builtin_amdgcn_sched_barrier(0)
; template <class Epi, class Sched, bool ALIGN_EPI = false, bool SP2 = false>
; __device__ __forceinline__ void gemm_phase(PG8_LAS unsigned char* lds, const Gemm g, const Sched& S, const Epi& E) {
;     ...
;             const bool last = (t == nt - 2);
;             const char* a1 = cA + (size_t)(t + 1) * kstep;
;             const char* a2 = last ? nA : cA + (size_t)(t + 2) * kstep; const char* b2 = last ? nB : cB + (size_t)(t + 2) * kstep;
;             const char* a3 = a2 + kstep; const char* b3 = b2 + kstep;
;             if (last && has_next) S.a_ready(nxt);
;             if constexpr (SP2) {
;             PG8_LDB(B0, 0, 0); PG8_LDB(B1, 0, 1); PG8_SCHED; PG8_LDA(At, 0, 0); PG8_STAGE(PG8_SA(1, 1), a1 + hstep, voffA);
;             PG8_WAIT_V(8); PG8_WAIT_L(0); PG8_BAR; PG8_MMA(0, 0, At, B0); PG8_MMA(0, 1, At, B1); PG8_BAR; PG8_SCHED;
;             PG8_LDA(At, 0, 1); PG8_STAGE(PG8_SB(0, 0), b2, voffB); PG8_STAGE(PG8_SB(0, 1), b2 + hstep, voffB); PG8_STAGE(PG8_SA(0, 0), a2, voffA);
.LBB0_719:
	ds_read_b128 v[88:91], v208
	ds_read_b128 v[96:99], v208 offset:1024
	ds_read_b128 v[136:139], v208 offset:2048
	ds_read_b128 v[140:143], v208 offset:3072
	ds_read_b128 v[144:147], v209
	ds_read_b128 v[148:151], v209 offset:1024
	ds_read_b128 v[152:155], v209 offset:2048
	ds_read_b128 v[156:159], v209 offset:3072
	s_add_u32 s44, s62, 0xfff80080
	s_addc_u32 s45, s63, -1
	s_cmp_eq_u32 s76, 28
	s_cselect_b32 s59, s29, s45
	s_cselect_b32 s58, s34, s44
	s_cselect_b32 s57, s23, s75
	s_cselect_b32 s56, s35, s74
	v_lshl_add_u64 v[200:201], s[62:63], 0, v[172:173]
	s_add_i32 m0, s49, 0xc000
	ds_read_b128 v[178:181], v210
	ds_read_b128 v[182:185], v210 offset:1024
	ds_read_b128 v[186:189], v210 offset:2048
	ds_read_b128 v[212:215], v210 offset:3072
	ds_read_b128 v[216:219], v210 offset:4096
	ds_read_b128 v[220:223], v210 offset:5120
	ds_read_b128 v[224:227], v210 offset:6144
	ds_read_b128 v[228:231], v210 offset:7168
	global_load_lds_dwordx4 v[200:201], off
	v_lshl_add_u64 v[200:201], s[62:63], 0, v[174:175]
	s_add_i32 m0, s49, 0xe000
	s_nop 0
	global_load_lds_dwordx4 v[200:201], off
	s_waitcnt vmcnt(8)
	s_waitcnt lgkmcnt(0)
	s_barrier
	s_setprio 1
	s_waitcnt lgkmcnt(0)
	v_mfma_f32_16x16x32_bf16 v[128:131], v[88:91], v[178:181], v[128:131]
	v_mfma_f32_16x16x32_bf16 v[128:131], v[96:99], v[182:185], v[128:131]
	v_mfma_f32_16x16x32_bf16 v[120:123], v[140:143], v[182:185], v[120:123]
	v_mfma_f32_16x16x32_bf16 v[120:123], v[136:139], v[178:181], v[120:123]
	v_mfma_f32_16x16x32_bf16 v[108:111], v[136:139], v[186:189], v[108:111]
	v_mfma_f32_16x16x32_bf16 v[108:111], v[140:143], v[212:215], v[108:111]
	v_mfma_f32_16x16x32_bf16 v[116:119], v[96:99], v[212:215], v[116:119]
	v_mfma_f32_16x16x32_bf16 v[116:119], v[88:91], v[186:189], v[116:119]
	v_mfma_f32_16x16x32_bf16 v[100:103], v[88:91], v[216:219], v[100:103]
	v_mfma_f32_16x16x32_bf16 v[100:103], v[96:99], v[220:223], v[100:103]
	v_mfma_f32_16x16x32_bf16 v[84:87], v[140:143], v[220:223], v[84:87]
	v_mfma_f32_16x16x32_bf16 v[84:87], v[136:139], v[216:219], v[84:87]
	v_mfma_f32_16x16x32_bf16 v[68:71], v[136:139], v[224:227], v[68:71]
	v_mfma_f32_16x16x32_bf16 v[68:71], v[140:143], v[228:231], v[68:71]
	v_mfma_f32_16x16x32_bf16 v[76:79], v[96:99], v[228:231], v[76:79]
	v_mfma_f32_16x16x32_bf16 v[76:79], v[88:91], v[224:227], v[76:79]
	s_setprio 0
	s_setprio 1
	v_mfma_f32_16x16x32_bf16 v[132:135], v[144:147], v[178:181], v[132:135]
	v_mfma_f32_16x16x32_bf16 v[132:135], v[148:151], v[182:185], v[132:135]
	v_mfma_f32_16x16x32_bf16 v[124:127], v[156:159], v[182:185], v[124:127]
	v_mfma_f32_16x16x32_bf16 v[124:127], v[152:155], v[178:181], v[124:127]
	v_mfma_f32_16x16x32_bf16 v[104:107], v[152:155], v[186:189], v[104:107]
	v_mfma_f32_16x16x32_bf16 v[104:107], v[156:159], v[212:215], v[104:107]
	v_mfma_f32_16x16x32_bf16 v[112:115], v[148:151], v[212:215], v[112:115]
	v_mfma_f32_16x16x32_bf16 v[112:115], v[144:147], v[186:189], v[112:115]
	v_mfma_f32_16x16x32_bf16 v[92:95], v[144:147], v[216:219], v[92:95]
	v_mfma_f32_16x16x32_bf16 v[92:95], v[148:151], v[220:223], v[92:95]
	v_mfma_f32_16x16x32_bf16 v[80:83], v[156:159], v[220:223], v[80:83]
	v_mfma_f32_16x16x32_bf16 v[80:83], v[152:155], v[216:219], v[80:83]
	v_mfma_f32_16x16x32_bf16 v[64:67], v[152:155], v[224:227], v[64:67]
	v_mfma_f32_16x16x32_bf16 v[64:67], v[156:159], v[228:231], v[64:67]
	s_setprio 2
	s_barrier
	v_mfma_f32_16x16x32_bf16 v[72:75], v[148:151], v[228:231], v[72:75]
	v_mfma_f32_16x16x32_bf16 v[72:75], v[144:147], v[224:227], v[72:75]
	s_setprio 0
	s_add_i32 s44, s71, s65
	v_lshl_add_u64 v[200:201], s[56:57], 0, v[164:165]
	s_mov_b32 m0, s44
	ds_read_b128 v[178:181], v210 offset:16384
	ds_read_b128 v[182:185], v210 offset:17408
	ds_read_b128 v[186:189], v210 offset:18432
	ds_read_b128 v[212:215], v210 offset:19456
	ds_read_b128 v[216:219], v210 offset:20480
	ds_read_b128 v[220:223], v210 offset:21504
	ds_read_b128 v[224:227], v210 offset:22528
	ds_read_b128 v[228:231], v210 offset:23552
	global_load_lds_dwordx4 v[200:201], off
	s_add_i32 m0, s44, 0x2000
	s_add_u32 s78, s56, 0x80000
	v_lshl_add_u64 v[232:233], s[56:57], 0, v[168:169]
	s_addc_u32 s79, s57, 0
	s_add_i32 s44, s72, s65
	global_load_lds_dwordx4 v[232:233], off
	v_lshl_add_u64 v[234:235], s[78:79], 0, v[164:165]
	s_mov_b32 m0, s44
	v_lshl_add_u64 v[236:237], s[58:59], 0, v[168:169]
	global_load_lds_dwordx4 v[234:235], off
	v_lshl_add_u64 v[234:235], s[78:79], 0, v[168:169]
	s_add_i32 m0, s44, 0x2000
	s_nop 0
	global_load_lds_dwordx4 v[234:235], off
	v_lshl_add_u64 v[234:235], s[58:59], 0, v[164:165]
	s_mov_b32 m0, s49
	s_nop 0
	global_load_lds_dwordx4 v[234:235], off
	s_mov_b32 m0, s61
	s_nop 0
	global_load_lds_dwordx4 v[236:237], off
	s_waitcnt vmcnt(8)
	s_waitcnt lgkmcnt(0)
	s_barrier
; #define PG8_STAGE(bufoff, gbase, voff) do { _Pragma("unroll") for (int _i = 0; _i < 2; ++_i) \
;         __builtin_amdgcn_global_load_lds((const unsigned*)((const char*)(gbase) + (voff)[_i]), (PG8_LAS unsigned*)(lds + (bufoff) + ldsw + _i * 8192), 16, 0, 0); } while (0)
; #define PG8_LDA(dst, b, h) do { _Pragma("unroll") for (int m = 0; m < 4; ++m) _Pragma("unroll") for (int k = 0; k < 2; ++k) dst[m][k] = *(const PG8_LAS bf16x8*)(lds + PG8_SA(b, h) + aoff + m * 2048 + k * 1024); } while (0)
; #define PG8_LDB(dst, b, h) do { _Pragma("unroll") for (int n = 0; n < 2; ++n) _Pragma("unroll") for (int k = 0; k < 2; ++k) dst[n][k] = *(const PG8_LAS bf16x8*)(lds + PG8_SB(b, h) + boff + n * 2048 + k * 1024); } while (0)
; #define PG8_MMA(ai, bj, At, Bt) do { __builtin_amdgcn_s_setprio(1); _Pragma("unroll") for (int m = 0; m < 4; ++m) _Pragma("unroll") for (int n = 0; n < 2; ++n) _Pragma("unroll") for (int k = 0; k < 2; ++k) \
;         acc[ai][bj][m][n] = __builtin_amdgcn_mfma_f32_16x16x32_bf16(Bt[n][k], At[m][k], acc[ai][bj][m][n], 0, 0, 0); __builtin_amdgcn_s_setprio(0); } while (0)
; #define PG8_WAIT_V(n) asm volatile("s_waitcnt vmcnt(" #n ")" ::: "memory")
; #define PG8_WAIT_L(n) asm volatile("s_waitcnt lgkmcnt(" #n ")" ::: "memory")
; #define PG8_BAR __builtin_amdgcn_s_barrier()
; #define PG8_SCHED __builtin_amdgcn_sched_barrier(0)
; template <class Epi, class Sched, bool ALIGN_EPI = false, bool SP2 = false>
; __device__ __forceinline__ void gemm_phase(PG8_LAS unsigned char* lds, const Gemm g, const Sched& S, const Epi& E) {
;     ...
;             PG8_WAIT_V(8); PG8_WAIT_L(0); PG8_BAR; PG8_MMA(1, 0, At, B0); PG8_MMA(1, 1, At, B1); PG8_BAR; PG8_SCHED;
;             PG8_LDB(B0, 1, 0); PG8_LDB(B1, 1, 1); PG8_SCHED; PG8_LDA(At, 1, 0); PG8_STAGE(PG8_SA(0, 1), a2 + hstep, voffA);
;             PG8_WAIT_V(8); PG8_WAIT_L(0); PG8_BAR; PG8_MMA(0, 0, At, B0); PG8_MMA(0, 1, At, B1); PG8_BAR; PG8_SCHED;
	s_setprio 1
	s_waitcnt lgkmcnt(0)
	v_mfma_f32_16x16x32_bf16 v[56:59], v[88:91], v[178:181], v[56:59]
	v_mfma_f32_16x16x32_bf16 v[56:59], v[96:99], v[182:185], v[56:59]
	v_mfma_f32_16x16x32_bf16 v[48:51], v[140:143], v[182:185], v[48:51]
	v_mfma_f32_16x16x32_bf16 v[48:51], v[136:139], v[178:181], v[48:51]
	v_mfma_f32_16x16x32_bf16 v[36:39], v[136:139], v[186:189], v[36:39]
	v_mfma_f32_16x16x32_bf16 v[36:39], v[140:143], v[212:215], v[36:39]
	v_mfma_f32_16x16x32_bf16 v[44:47], v[96:99], v[212:215], v[44:47]
	v_mfma_f32_16x16x32_bf16 v[44:47], v[88:91], v[186:189], v[44:47]
	v_mfma_f32_16x16x32_bf16 v[28:31], v[88:91], v[216:219], v[28:31]
	v_mfma_f32_16x16x32_bf16 v[28:31], v[96:99], v[220:223], v[28:31]
	v_mfma_f32_16x16x32_bf16 v[20:23], v[140:143], v[220:223], v[20:23]
	v_mfma_f32_16x16x32_bf16 v[20:23], v[136:139], v[216:219], v[20:23]
	v_mfma_f32_16x16x32_bf16 v[4:7], v[136:139], v[224:227], v[4:7]
	v_mfma_f32_16x16x32_bf16 v[4:7], v[140:143], v[228:231], v[4:7]
	v_mfma_f32_16x16x32_bf16 v[12:15], v[96:99], v[228:231], v[12:15]
	v_mfma_f32_16x16x32_bf16 v[12:15], v[88:91], v[224:227], v[12:15]
	s_setprio 0
	s_setprio 1
	v_mfma_f32_16x16x32_bf16 v[60:63], v[144:147], v[178:181], v[60:63]
	v_mfma_f32_16x16x32_bf16 v[60:63], v[148:151], v[182:185], v[60:63]
	v_mfma_f32_16x16x32_bf16 v[52:55], v[156:159], v[182:185], v[52:55]
	v_mfma_f32_16x16x32_bf16 v[52:55], v[152:155], v[178:181], v[52:55]
	v_mfma_f32_16x16x32_bf16 v[32:35], v[152:155], v[186:189], v[32:35]
	v_mfma_f32_16x16x32_bf16 v[32:35], v[156:159], v[212:215], v[32:35]
	v_mfma_f32_16x16x32_bf16 v[40:43], v[148:151], v[212:215], v[40:43]
	v_mfma_f32_16x16x32_bf16 v[40:43], v[144:147], v[186:189], v[40:43]
	v_mfma_f32_16x16x32_bf16 v[24:27], v[144:147], v[216:219], v[24:27]
	v_mfma_f32_16x16x32_bf16 v[24:27], v[148:151], v[220:223], v[24:27]
	v_mfma_f32_16x16x32_bf16 v[16:19], v[156:159], v[220:223], v[16:19]
	v_mfma_f32_16x16x32_bf16 v[16:19], v[152:155], v[216:219], v[16:19]
	v_mfma_f32_16x16x32_bf16 v[0:3], v[152:155], v[224:227], v[0:3]
	v_mfma_f32_16x16x32_bf16 v[0:3], v[156:159], v[228:231], v[0:3]
	s_setprio 2
	s_barrier
	v_mfma_f32_16x16x32_bf16 v[8:11], v[148:151], v[228:231], v[8:11]
	v_mfma_f32_16x16x32_bf16 v[8:11], v[144:147], v[224:227], v[8:11]
	s_setprio 0
	s_add_i32 s44, 0, 0x18000
	s_add_i32 s45, 0, 0x1c000
	v_add_u32_e32 v140, s44, v163
	v_add_u32_e32 v156, s45, v163
	ds_read_b128 v[88:91], v140
	ds_read_b128 v[96:99], v140 offset:1024
	ds_read_b128 v[136:139], v140 offset:2048
	ds_read_b128 v[140:143], v140 offset:3072
	ds_read_b128 v[144:147], v156
	ds_read_b128 v[148:151], v156 offset:1024
	ds_read_b128 v[152:155], v156 offset:2048
	ds_read_b128 v[156:159], v156 offset:3072
	s_add_u32 s58, s58, 0x80000
	s_addc_u32 s59, s59, 0
	s_mov_b32 m0, s66
	v_lshl_add_u64 v[238:239], s[58:59], 0, v[164:165]
	ds_read_b128 v[178:181], v210 offset:32768
	ds_read_b128 v[182:185], v210 offset:33792
	ds_read_b128 v[186:189], v210 offset:34816
	ds_read_b128 v[212:215], v210 offset:35840
	ds_read_b128 v[216:219], v210 offset:36864
	ds_read_b128 v[220:223], v210 offset:37888
	ds_read_b128 v[224:227], v210 offset:38912
	ds_read_b128 v[228:231], v210 offset:39936
	global_load_lds_dwordx4 v[238:239], off
	v_lshl_add_u64 v[238:239], s[58:59], 0, v[168:169]
	s_mov_b32 m0, s67
	s_nop 0
	global_load_lds_dwordx4 v[238:239], off
	s_waitcnt vmcnt(8)
	s_waitcnt lgkmcnt(0)
	s_barrier
	s_setprio 1
	s_waitcnt lgkmcnt(0)
	v_mfma_f32_16x16x32_bf16 v[128:131], v[88:91], v[178:181], v[128:131]
	v_mfma_f32_16x16x32_bf16 v[128:131], v[96:99], v[182:185], v[128:131]
	v_mfma_f32_16x16x32_bf16 v[120:123], v[140:143], v[182:185], v[120:123]
	v_mfma_f32_16x16x32_bf16 v[120:123], v[136:139], v[178:181], v[120:123]
	v_mfma_f32_16x16x32_bf16 v[108:111], v[136:139], v[186:189], v[108:111]
	v_mfma_f32_16x16x32_bf16 v[108:111], v[140:143], v[212:215], v[108:111]
	v_mfma_f32_16x16x32_bf16 v[116:119], v[96:99], v[212:215], v[116:119]
	v_mfma_f32_16x16x32_bf16 v[116:119], v[88:91], v[186:189], v[116:119]
	v_mfma_f32_16x16x32_bf16 v[100:103], v[88:91], v[216:219], v[100:103]
	v_mfma_f32_16x16x32_bf16 v[100:103], v[96:99], v[220:223], v[100:103]
	v_mfma_f32_16x16x32_bf16 v[84:87], v[140:143], v[220:223], v[84:87]
	v_mfma_f32_16x16x32_bf16 v[84:87], v[136:139], v[216:219], v[84:87]
	v_mfma_f32_16x16x32_bf16 v[68:71], v[136:139], v[224:227], v[68:71]
	v_mfma_f32_16x16x32_bf16 v[68:71], v[140:143], v[228:231], v[68:71]
	v_mfma_f32_16x16x32_bf16 v[76:79], v[96:99], v[228:231], v[76:79]
	v_mfma_f32_16x16x32_bf16 v[76:79], v[88:91], v[224:227], v[76:79]
	s_setprio 0
	s_setprio 1
	v_mfma_f32_16x16x32_bf16 v[132:135], v[144:147], v[178:181], v[132:135]
	v_mfma_f32_16x16x32_bf16 v[132:135], v[148:151], v[182:185], v[132:135]
	v_mfma_f32_16x16x32_bf16 v[124:127], v[156:159], v[182:185], v[124:127]
	v_mfma_f32_16x16x32_bf16 v[124:127], v[152:155], v[178:181], v[124:127]
	v_mfma_f32_16x16x32_bf16 v[104:107], v[152:155], v[186:189], v[104:107]
	v_mfma_f32_16x16x32_bf16 v[104:107], v[156:159], v[212:215], v[104:107]
	v_mfma_f32_16x16x32_bf16 v[112:115], v[148:151], v[212:215], v[112:115]
	v_mfma_f32_16x16x32_bf16 v[112:115], v[144:147], v[186:189], v[112:115]
	v_mfma_f32_16x16x32_bf16 v[92:95], v[144:147], v[216:219], v[92:95]
	v_mfma_f32_16x16x32_bf16 v[92:95], v[148:151], v[220:223], v[92:95]
	v_mfma_f32_16x16x32_bf16 v[80:83], v[156:159], v[220:223], v[80:83]
	v_mfma_f32_16x16x32_bf16 v[80:83], v[152:155], v[216:219], v[80:83]
	v_mfma_f32_16x16x32_bf16 v[64:67], v[152:155], v[224:227], v[64:67]
	v_mfma_f32_16x16x32_bf16 v[64:67], v[156:159], v[228:231], v[64:67]
	s_setprio 2
	s_barrier
; #define PG8_STAGE(bufoff, gbase, voff) do { _Pragma("unroll") for (int _i = 0; _i < 2; ++_i) \
;         __builtin_amdgcn_global_load_lds((const unsigned*)((const char*)(gbase) + (voff)[_i]), (PG8_LAS unsigned*)(lds + (bufoff) + ldsw + _i * 8192), 16, 0, 0); } while (0)
; #define PG8_LDA(dst, b, h) do { _Pragma("unroll") for (int m = 0; m < 4; ++m) _Pragma("unroll") for (int k = 0; k < 2; ++k) dst[m][k] = *(const PG8_LAS bf16x8*)(lds + PG8_SA(b, h) + aoff + m * 2048 + k * 1024); } while (0)
; #define PG8_MMA(ai, bj, At, Bt) do { __builtin_amdgcn_s_setprio(1); _Pragma("unroll") for (int m = 0; m < 4; ++m) _Pragma("unroll") for (int n = 0; n < 2; ++n) _Pragma("unroll") for (int k = 0; k < 2; ++k) \
;         acc[ai][bj][m][n] = __builtin_amdgcn_mfma_f32_16x16x32_bf16(Bt[n][k], At[m][k], acc[ai][bj][m][n], 0, 0, 0); __builtin_amdgcn_s_setprio(0); } while (0)
; #define PG8_WAIT_V(n) asm volatile("s_waitcnt vmcnt(" #n ")" ::: "memory")
; #define PG8_WAIT_L(n) asm volatile("s_waitcnt lgkmcnt(" #n ")" ::: "memory")
; #define PG8_BAR __builtin_amdgcn_s_barrier()
; #define PG8_SCHED __builtin_amdgcn_sched_barrier(0)
; template <class Epi, class Sched, bool ALIGN_EPI = false, bool SP2 = false>
; __device__ __forceinline__ void gemm_phase(PG8_LAS unsigned char* lds, const Gemm g, const Sched& S, const Epi& E) {
;     ...
;             PG8_LDA(At, 1, 1); PG8_STAGE(PG8_SB(1, 0), b3, voffB); PG8_STAGE(PG8_SB(1, 1), b3 + hstep, voffB); PG8_STAGE(PG8_SA(1, 0), a3, voffA);
;             PG8_WAIT_V(8); PG8_WAIT_L(0); PG8_BAR; PG8_MMA(1, 0, At, B0); PG8_MMA(1, 1, At, B1); PG8_BAR; PG8_SCHED;
;     ...
;         if constexpr (ALIGN_EPI) { if (wr == 0) PG8_BAR; }
;         if constexpr (!Epi::AFTER_DRAIN) { E(acc, cur, wr, wc, fr, fq); S.done(cur); }
;         if (!has_next) break;
	v_mfma_f32_16x16x32_bf16 v[72:75], v[148:151], v[228:231], v[72:75]
	v_mfma_f32_16x16x32_bf16 v[72:75], v[144:147], v[224:227], v[72:75]
	s_setprio 0
	s_add_i32 s44, s44, s65
	v_lshl_add_u64 v[200:201], v[200:201], 0, s[18:19]
	s_mov_b32 m0, s44
	ds_read_b128 v[178:181], v210 offset:49152
	ds_read_b128 v[182:185], v210 offset:50176
	ds_read_b128 v[186:189], v210 offset:51200
	ds_read_b128 v[212:215], v210 offset:52224
	ds_read_b128 v[216:219], v210 offset:53248
	ds_read_b128 v[220:223], v210 offset:54272
	ds_read_b128 v[224:227], v210 offset:55296
	ds_read_b128 v[228:231], v210 offset:56320
	global_load_lds_dwordx4 v[200:201], off
	s_add_i32 m0, s44, 0x2000
	s_add_u32 s56, s56, 0x80080
	v_lshl_add_u64 v[200:201], v[232:233], 0, s[18:19]
	s_addc_u32 s57, s57, 0
	s_add_i32 s44, s45, s65
	global_load_lds_dwordx4 v[200:201], off
	v_lshl_add_u64 v[200:201], s[56:57], 0, v[164:165]
	s_mov_b32 m0, s44
	s_nop 0
	global_load_lds_dwordx4 v[200:201], off
	v_lshl_add_u64 v[200:201], s[56:57], 0, v[168:169]
	s_add_i32 m0, s44, 0x2000
	s_nop 0
	global_load_lds_dwordx4 v[200:201], off
	v_lshl_add_u64 v[200:201], v[234:235], 0, s[18:19]
	s_mov_b32 m0, s68
	s_nop 0
	global_load_lds_dwordx4 v[200:201], off
	v_lshl_add_u64 v[200:201], v[236:237], 0, s[18:19]
	s_mov_b32 m0, s69
	s_nop 0
	global_load_lds_dwordx4 v[200:201], off
	s_waitcnt vmcnt(8)
	s_waitcnt lgkmcnt(0)
	s_barrier
	s_setprio 1
	s_waitcnt lgkmcnt(0)
	v_mfma_f32_16x16x32_bf16 v[56:59], v[88:91], v[178:181], v[56:59]
	v_mfma_f32_16x16x32_bf16 v[56:59], v[96:99], v[182:185], v[56:59]
	v_mfma_f32_16x16x32_bf16 v[48:51], v[140:143], v[182:185], v[48:51]
	v_mfma_f32_16x16x32_bf16 v[48:51], v[136:139], v[178:181], v[48:51]
	v_mfma_f32_16x16x32_bf16 v[36:39], v[136:139], v[186:189], v[36:39]
	v_mfma_f32_16x16x32_bf16 v[36:39], v[140:143], v[212:215], v[36:39]
	v_mfma_f32_16x16x32_bf16 v[44:47], v[96:99], v[212:215], v[44:47]
	v_mfma_f32_16x16x32_bf16 v[44:47], v[88:91], v[186:189], v[44:47]
	v_mfma_f32_16x16x32_bf16 v[28:31], v[88:91], v[216:219], v[28:31]
	v_mfma_f32_16x16x32_bf16 v[28:31], v[96:99], v[220:223], v[28:31]
	v_mfma_f32_16x16x32_bf16 v[20:23], v[140:143], v[220:223], v[20:23]
	v_mfma_f32_16x16x32_bf16 v[20:23], v[136:139], v[216:219], v[20:23]
	v_mfma_f32_16x16x32_bf16 v[4:7], v[136:139], v[224:227], v[4:7]
	v_mfma_f32_16x16x32_bf16 v[4:7], v[140:143], v[228:231], v[4:7]
	v_mfma_f32_16x16x32_bf16 v[12:15], v[96:99], v[228:231], v[12:15]
	v_mfma_f32_16x16x32_bf16 v[12:15], v[88:91], v[224:227], v[12:15]
	s_setprio 0
	s_setprio 1
	v_mfma_f32_16x16x32_bf16 v[60:63], v[144:147], v[178:181], v[60:63]
	v_mfma_f32_16x16x32_bf16 v[60:63], v[148:151], v[182:185], v[60:63]
	v_mfma_f32_16x16x32_bf16 v[52:55], v[156:159], v[182:185], v[52:55]
	v_mfma_f32_16x16x32_bf16 v[52:55], v[152:155], v[178:181], v[52:55]
	v_mfma_f32_16x16x32_bf16 v[32:35], v[152:155], v[186:189], v[32:35]
	v_mfma_f32_16x16x32_bf16 v[32:35], v[156:159], v[212:215], v[32:35]
	v_mfma_f32_16x16x32_bf16 v[40:43], v[148:151], v[212:215], v[40:43]
	v_mfma_f32_16x16x32_bf16 v[40:43], v[144:147], v[186:189], v[40:43]
	v_mfma_f32_16x16x32_bf16 v[24:27], v[144:147], v[216:219], v[24:27]
	v_mfma_f32_16x16x32_bf16 v[24:27], v[148:151], v[220:223], v[24:27]
	v_mfma_f32_16x16x32_bf16 v[16:19], v[156:159], v[220:223], v[16:19]
	v_mfma_f32_16x16x32_bf16 v[16:19], v[152:155], v[216:219], v[16:19]
	v_mfma_f32_16x16x32_bf16 v[0:3], v[152:155], v[224:227], v[0:3]
	v_mfma_f32_16x16x32_bf16 v[0:3], v[156:159], v[228:231], v[0:3]
	s_setprio 2
	s_barrier
	v_mfma_f32_16x16x32_bf16 v[8:11], v[148:151], v[228:231], v[8:11]
	v_mfma_f32_16x16x32_bf16 v[8:11], v[144:147], v[224:227], v[8:11]
	s_setprio 0
	s_add_i32 s76, s76, 2
	s_add_u32 s62, s62, 0x100
	s_addc_u32 s63, s63, 0
	s_add_u32 s74, s74, 0x100
	s_addc_u32 s75, s75, 0
	s_cmp_gt_u32 s76, 29
	s_cbranch_scc0 .LBB0_719
	s_and_b64 vcc, exec, s[20:21]
	s_cbranch_vccz .LBB0_722
	s_barrier

; #define PG8_STAGE(bufoff, gbase, voff) do { _Pragma("unroll") for (int _i = 0; _i < 2; ++_i) \
;         __builtin_amdgcn_global_load_lds((const unsigned*)((const char*)(gbase) + (voff)[_i]), (PG8_LAS unsigned*)(lds + (bufoff) + ldsw + _i * 8192), 16, 0, 0); } while (0)
; #define PG8_LDA(dst, b, h) do { _Pragma("unroll") for (int m = 0; m < 4; ++m) _Pragma("unroll") for (int k = 0; k < 2; ++k) dst[m][k] = *(const PG8_LAS bf16x8*)(lds + PG8_SA(b, h) + aoff + m * 2048 + k * 1024); } while (0)
; #define PG8_LDB(dst, b, h) do { _Pragma("unroll") for (int n = 0; n < 2; ++n) _Pragma("unroll") for (int k = 0; k < 2; ++k) dst[n][k] = *(const PG8_LAS bf16x8*)(lds + PG8_SB(b, h) + boff + n * 2048 + k * 1024); } while (0)
; #define PG8_MMA(ai, bj, At, Bt) do { __builtin_amdgcn_s_setprio(1); _Pragma("unroll") for (int m = 0; m < 4; ++m) _Pragma("unroll") for (int n = 0; n < 2; ++n) _Pragma("unroll") for (int k = 0; k < 2; ++k) \
;         acc[ai][bj][m][n] = __builtin_amdgcn_mfma_f32_16x16x32_bf16(Bt[n][k], At[m][k], acc[ai][bj][m][n], 0, 0, 0); __builtin_amdgcn_s_setprio(0); } while (0)
; #define PG8_WAIT_V(n) asm volatile("s_waitcnt vmcnt(" #n ")" ::: "memory")
; #define PG8_WAIT_L(n) asm volatile("s_waitcnt lgkmcnt(" #n ")" ::: "memory")
; #define PG8_BAR __builtin_amdgcn_s_barrier()
; #define PG8_SCHED __builtin_amdgcn_sched_barrier(0)
; template <class Epi, class Sched, bool ALIGN_EPI = false, bool SP2 = false>
; __device__ __forceinline__ void gemm_phase(PG8_LAS unsigned char* lds, const Gemm g, const Sched& S, const Epi& E) {
;     ...
;             const bool last = (t == nt - 2);
;             const char* a1 = cA + (size_t)(t + 1) * kstep;
;             const char* a2 = last ? nA : cA + (size_t)(t + 2) * kstep; const char* b2 = last ? nB : cB + (size_t)(t + 2) * kstep;
;             const char* a3 = a2 + kstep; const char* b3 = b2 + kstep;
;             if (last && has_next) S.a_ready(nxt);
;             if constexpr (SP2) {
;             PG8_LDB(B0, 0, 0); PG8_LDB(B1, 0, 1); PG8_SCHED; PG8_LDA(At, 0, 0); PG8_STAGE(PG8_SA(1, 1), a1 + hstep, voffA);
;             PG8_WAIT_V(8); PG8_WAIT_L(0); PG8_BAR; PG8_MMA(0, 0, At, B0); PG8_MMA(0, 1, At, B1); PG8_BAR; PG8_SCHED;
;             PG8_LDA(At, 0, 1); PG8_STAGE(PG8_SB(0, 0), b2, voffB); PG8_STAGE(PG8_SB(0, 1), b2 + hstep, voffB); PG8_STAGE(PG8_SA(0, 0), a2, voffA);
.LBB0_774:
	ds_read_b128 v[136:139], v156
	ds_read_b128 v[140:143], v156 offset:1024
	ds_read_b128 v[172:175], v156 offset:2048
	ds_read_b128 v[176:179], v156 offset:3072
	ds_read_b128 v[180:183], v157
	ds_read_b128 v[184:187], v157 offset:1024
	ds_read_b128 v[208:211], v157 offset:2048
	ds_read_b128 v[212:215], v157 offset:3072
	s_add_u32 s42, s40, 0xfff80080
	s_addc_u32 s43, s41, -1
	s_cmp_eq_u32 s71, 28
	s_cselect_b32 s49, s23, s43
	s_cselect_b32 s48, s34, s42
	s_cselect_b32 s43, s21, s70
	s_cselect_b32 s42, s35, s69
	v_lshl_add_u64 v[188:189], s[40:41], 0, v[128:129]
	s_add_i32 m0, s11, 0xc000
	ds_read_b128 v[216:219], v158
	ds_read_b128 v[220:223], v158 offset:1024
	ds_read_b128 v[224:227], v158 offset:2048
	ds_read_b128 v[228:231], v158 offset:3072
	ds_read_b128 v[232:235], v158 offset:4096
	ds_read_b128 v[236:239], v158 offset:5120
	ds_read_b128 v[240:243], v158 offset:6144
	ds_read_b128 v[244:247], v158 offset:7168
	global_load_lds_dwordx4 v[188:189], off
	v_lshl_add_u64 v[188:189], s[40:41], 0, v[130:131]
	s_add_i32 m0, s11, 0xe000
	s_nop 0
	global_load_lds_dwordx4 v[188:189], off
	s_waitcnt vmcnt(8)
	s_waitcnt lgkmcnt(0)
	s_barrier
	s_setprio 1
	s_waitcnt lgkmcnt(0)
	v_mfma_f32_16x16x32_bf16 v[124:127], v[136:139], v[216:219], v[124:127]
	v_mfma_f32_16x16x32_bf16 v[124:127], v[140:143], v[220:223], v[124:127]
	v_mfma_f32_16x16x32_bf16 v[120:123], v[176:179], v[220:223], v[120:123]
	v_mfma_f32_16x16x32_bf16 v[120:123], v[172:175], v[216:219], v[120:123]
	v_mfma_f32_16x16x32_bf16 v[104:107], v[172:175], v[224:227], v[104:107]
	v_mfma_f32_16x16x32_bf16 v[104:107], v[176:179], v[228:231], v[104:107]
	v_mfma_f32_16x16x32_bf16 v[108:111], v[140:143], v[228:231], v[108:111]
	v_mfma_f32_16x16x32_bf16 v[108:111], v[136:139], v[224:227], v[108:111]
	v_mfma_f32_16x16x32_bf16 v[96:99], v[136:139], v[232:235], v[96:99]
	v_mfma_f32_16x16x32_bf16 v[96:99], v[140:143], v[236:239], v[96:99]
	v_mfma_f32_16x16x32_bf16 v[88:91], v[176:179], v[236:239], v[88:91]
	v_mfma_f32_16x16x32_bf16 v[88:91], v[172:175], v[232:235], v[88:91]
	v_mfma_f32_16x16x32_bf16 v[72:75], v[172:175], v[240:243], v[72:75]
	v_mfma_f32_16x16x32_bf16 v[72:75], v[176:179], v[244:247], v[72:75]
	v_mfma_f32_16x16x32_bf16 v[80:83], v[140:143], v[244:247], v[80:83]
	v_mfma_f32_16x16x32_bf16 v[80:83], v[136:139], v[240:243], v[80:83]
	s_setprio 0
	s_setprio 1
	v_mfma_f32_16x16x32_bf16 v[116:119], v[180:183], v[216:219], v[116:119]
	v_mfma_f32_16x16x32_bf16 v[116:119], v[184:187], v[220:223], v[116:119]
	v_mfma_f32_16x16x32_bf16 v[112:115], v[212:215], v[220:223], v[112:115]
	v_mfma_f32_16x16x32_bf16 v[112:115], v[208:211], v[216:219], v[112:115]
	v_mfma_f32_16x16x32_bf16 v[92:95], v[208:211], v[224:227], v[92:95]
	v_mfma_f32_16x16x32_bf16 v[92:95], v[212:215], v[228:231], v[92:95]
	v_mfma_f32_16x16x32_bf16 v[100:103], v[184:187], v[228:231], v[100:103]
	v_mfma_f32_16x16x32_bf16 v[100:103], v[180:183], v[224:227], v[100:103]
	v_mfma_f32_16x16x32_bf16 v[84:87], v[180:183], v[232:235], v[84:87]
	v_mfma_f32_16x16x32_bf16 v[84:87], v[184:187], v[236:239], v[84:87]
	v_mfma_f32_16x16x32_bf16 v[76:79], v[212:215], v[236:239], v[76:79]
	v_mfma_f32_16x16x32_bf16 v[76:79], v[208:211], v[232:235], v[76:79]
	v_mfma_f32_16x16x32_bf16 v[64:67], v[208:211], v[240:243], v[64:67]
	v_mfma_f32_16x16x32_bf16 v[64:67], v[212:215], v[244:247], v[64:67]
	s_setprio 2
	s_barrier
	v_mfma_f32_16x16x32_bf16 v[68:71], v[184:187], v[244:247], v[68:71]
	v_mfma_f32_16x16x32_bf16 v[68:71], v[180:183], v[240:243], v[68:71]
	s_setprio 0
	s_add_i32 s44, s64, s52
	v_lshl_add_u64 v[188:189], s[42:43], 0, v[166:167]
	s_mov_b32 m0, s44
	ds_read_b128 v[216:219], v158 offset:16384
	ds_read_b128 v[220:223], v158 offset:17408
	ds_read_b128 v[224:227], v158 offset:18432
	ds_read_b128 v[228:231], v158 offset:19456
	ds_read_b128 v[232:235], v158 offset:20480
	ds_read_b128 v[236:239], v158 offset:21504
	ds_read_b128 v[240:243], v158 offset:22528
	ds_read_b128 v[244:247], v158 offset:23552
	global_load_lds_dwordx4 v[188:189], off
	s_add_i32 m0, s44, 0x2000
	s_add_u32 s72, s42, 0x80000
	v_lshl_add_u64 v[200:201], s[42:43], 0, v[170:171]
	s_addc_u32 s73, s43, 0
	s_add_i32 s44, s65, s52
	global_load_lds_dwordx4 v[200:201], off
	v_lshl_add_u64 v[248:249], s[72:73], 0, v[166:167]
	s_mov_b32 m0, s44
	v_lshl_add_u64 v[250:251], s[48:49], 0, v[168:169]
	global_load_lds_dwordx4 v[248:249], off
	v_lshl_add_u64 v[248:249], s[72:73], 0, v[170:171]
	s_add_i32 m0, s44, 0x2000
	s_nop 0
	global_load_lds_dwordx4 v[248:249], off
	v_lshl_add_u64 v[248:249], s[48:49], 0, v[164:165]
	s_mov_b32 m0, s11
	s_nop 0
	global_load_lds_dwordx4 v[248:249], off
	s_mov_b32 m0, s58
	s_nop 0
	global_load_lds_dwordx4 v[250:251], off
	s_waitcnt vmcnt(8)
	s_waitcnt lgkmcnt(0)
	s_barrier
; #define PG8_STAGE(bufoff, gbase, voff) do { _Pragma("unroll") for (int _i = 0; _i < 2; ++_i) \
;         __builtin_amdgcn_global_load_lds((const unsigned*)((const char*)(gbase) + (voff)[_i]), (PG8_LAS unsigned*)(lds + (bufoff) + ldsw + _i * 8192), 16, 0, 0); } while (0)
; #define PG8_LDA(dst, b, h) do { _Pragma("unroll") for (int m = 0; m < 4; ++m) _Pragma("unroll") for (int k = 0; k < 2; ++k) dst[m][k] = *(const PG8_LAS bf16x8*)(lds + PG8_SA(b, h) + aoff + m * 2048 + k * 1024); } while (0)
; #define PG8_LDB(dst, b, h) do { _Pragma("unroll") for (int n = 0; n < 2; ++n) _Pragma("unroll") for (int k = 0; k < 2; ++k) dst[n][k] = *(const PG8_LAS bf16x8*)(lds + PG8_SB(b, h) + boff + n * 2048 + k * 1024); } while (0)
; #define PG8_MMA(ai, bj, At, Bt) do { __builtin_amdgcn_s_setprio(1); _Pragma("unroll") for (int m = 0; m < 4; ++m) _Pragma("unroll") for (int n = 0; n < 2; ++n) _Pragma("unroll") for (int k = 0; k < 2; ++k) \
;         acc[ai][bj][m][n] = __builtin_amdgcn_mfma_f32_16x16x32_bf16(Bt[n][k], At[m][k], acc[ai][bj][m][n], 0, 0, 0); __builtin_amdgcn_s_setprio(0); } while (0)
; #define PG8_WAIT_V(n) asm volatile("s_waitcnt vmcnt(" #n ")" ::: "memory")
; #define PG8_WAIT_L(n) asm volatile("s_waitcnt lgkmcnt(" #n ")" ::: "memory")
; #define PG8_BAR __builtin_amdgcn_s_barrier()
; #define PG8_SCHED __builtin_amdgcn_sched_barrier(0)
; template <class Epi, class Sched, bool ALIGN_EPI = false, bool SP2 = false>
; __device__ __forceinline__ void gemm_phase(PG8_LAS unsigned char* lds, const Gemm g, const Sched& S, const Epi& E) {
;     ...
;             PG8_WAIT_V(8); PG8_WAIT_L(0); PG8_BAR; PG8_MMA(1, 0, At, B0); PG8_MMA(1, 1, At, B1); PG8_BAR; PG8_SCHED;
;             PG8_LDB(B0, 1, 0); PG8_LDB(B1, 1, 1); PG8_SCHED; PG8_LDA(At, 1, 0); PG8_STAGE(PG8_SA(0, 1), a2 + hstep, voffA);
;             PG8_WAIT_V(8); PG8_WAIT_L(0); PG8_BAR; PG8_MMA(0, 0, At, B0); PG8_MMA(0, 1, At, B1); PG8_BAR; PG8_SCHED;
	s_setprio 1
	s_waitcnt lgkmcnt(0)
	v_mfma_f32_16x16x32_bf16 v[60:63], v[136:139], v[216:219], v[60:63]
	v_mfma_f32_16x16x32_bf16 v[60:63], v[140:143], v[220:223], v[60:63]
	v_mfma_f32_16x16x32_bf16 v[56:59], v[176:179], v[220:223], v[56:59]
	v_mfma_f32_16x16x32_bf16 v[56:59], v[172:175], v[216:219], v[56:59]
	v_mfma_f32_16x16x32_bf16 v[40:43], v[172:175], v[224:227], v[40:43]
	v_mfma_f32_16x16x32_bf16 v[40:43], v[176:179], v[228:231], v[40:43]
	v_mfma_f32_16x16x32_bf16 v[48:51], v[140:143], v[228:231], v[48:51]
	v_mfma_f32_16x16x32_bf16 v[48:51], v[136:139], v[224:227], v[48:51]
	v_mfma_f32_16x16x32_bf16 v[32:35], v[136:139], v[232:235], v[32:35]
	v_mfma_f32_16x16x32_bf16 v[32:35], v[140:143], v[236:239], v[32:35]
	v_mfma_f32_16x16x32_bf16 v[24:27], v[176:179], v[236:239], v[24:27]
	v_mfma_f32_16x16x32_bf16 v[24:27], v[172:175], v[232:235], v[24:27]
	v_mfma_f32_16x16x32_bf16 v[8:11], v[172:175], v[240:243], v[8:11]
	v_mfma_f32_16x16x32_bf16 v[8:11], v[176:179], v[244:247], v[8:11]
	v_mfma_f32_16x16x32_bf16 v[12:15], v[140:143], v[244:247], v[12:15]
	v_mfma_f32_16x16x32_bf16 v[12:15], v[136:139], v[240:243], v[12:15]
	s_setprio 0
	s_setprio 1
	v_mfma_f32_16x16x32_bf16 v[52:55], v[180:183], v[216:219], v[52:55]
	v_mfma_f32_16x16x32_bf16 v[52:55], v[184:187], v[220:223], v[52:55]
	v_mfma_f32_16x16x32_bf16 v[44:47], v[212:215], v[220:223], v[44:47]
	v_mfma_f32_16x16x32_bf16 v[44:47], v[208:211], v[216:219], v[44:47]
	v_mfma_f32_16x16x32_bf16 v[28:31], v[208:211], v[224:227], v[28:31]
	v_mfma_f32_16x16x32_bf16 v[28:31], v[212:215], v[228:231], v[28:31]
	v_mfma_f32_16x16x32_bf16 v[36:39], v[184:187], v[228:231], v[36:39]
	v_mfma_f32_16x16x32_bf16 v[36:39], v[180:183], v[224:227], v[36:39]
	v_mfma_f32_16x16x32_bf16 v[20:23], v[180:183], v[232:235], v[20:23]
	v_mfma_f32_16x16x32_bf16 v[20:23], v[184:187], v[236:239], v[20:23]
	v_mfma_f32_16x16x32_bf16 v[16:19], v[212:215], v[236:239], v[16:19]
	v_mfma_f32_16x16x32_bf16 v[16:19], v[208:211], v[232:235], v[16:19]
	v_mfma_f32_16x16x32_bf16 v[0:3], v[208:211], v[240:243], v[0:3]
	v_mfma_f32_16x16x32_bf16 v[0:3], v[212:215], v[244:247], v[0:3]
	s_setprio 2
	s_barrier
	v_mfma_f32_16x16x32_bf16 v[4:7], v[184:187], v[244:247], v[4:7]
	v_mfma_f32_16x16x32_bf16 v[4:7], v[180:183], v[240:243], v[4:7]
	s_setprio 0
	s_add_i32 s44, 0, 0x18000
	v_add_u32_e32 v144, s44, v146
	s_add_i32 s45, 0, 0x1c000
	ds_read_b128 v[136:139], v144
	ds_read_b128 v[140:143], v144 offset:1024
	ds_read_b128 v[172:175], v144 offset:2048
	ds_read_b128 v[176:179], v144 offset:3072
	v_add_u32_e32 v144, s45, v146
	ds_read_b128 v[180:183], v144
	ds_read_b128 v[184:187], v144 offset:1024
	ds_read_b128 v[208:211], v144 offset:2048
	ds_read_b128 v[212:215], v144 offset:3072
	s_add_u32 s48, s48, 0x80000
	s_addc_u32 s49, s49, 0
	s_mov_b32 m0, s59
	v_lshl_add_u64 v[252:253], s[48:49], 0, v[164:165]
	ds_read_b128 v[216:219], v158 offset:32768
	ds_read_b128 v[220:223], v158 offset:33792
	ds_read_b128 v[224:227], v158 offset:34816
	ds_read_b128 v[228:231], v158 offset:35840
	ds_read_b128 v[232:235], v158 offset:36864
	ds_read_b128 v[236:239], v158 offset:37888
	ds_read_b128 v[240:243], v158 offset:38912
	ds_read_b128 v[244:247], v158 offset:39936
	global_load_lds_dwordx4 v[252:253], off
	v_lshl_add_u64 v[252:253], s[48:49], 0, v[168:169]
	s_mov_b32 m0, s60
	s_nop 0
	global_load_lds_dwordx4 v[252:253], off
	s_waitcnt vmcnt(8)
	s_waitcnt lgkmcnt(0)
	s_barrier
	s_setprio 1
	s_waitcnt lgkmcnt(0)
	v_mfma_f32_16x16x32_bf16 v[124:127], v[136:139], v[216:219], v[124:127]
	v_mfma_f32_16x16x32_bf16 v[124:127], v[140:143], v[220:223], v[124:127]
	v_mfma_f32_16x16x32_bf16 v[120:123], v[176:179], v[220:223], v[120:123]
	v_mfma_f32_16x16x32_bf16 v[120:123], v[172:175], v[216:219], v[120:123]
	v_mfma_f32_16x16x32_bf16 v[104:107], v[172:175], v[224:227], v[104:107]
	v_mfma_f32_16x16x32_bf16 v[104:107], v[176:179], v[228:231], v[104:107]
	v_mfma_f32_16x16x32_bf16 v[108:111], v[140:143], v[228:231], v[108:111]
	v_mfma_f32_16x16x32_bf16 v[108:111], v[136:139], v[224:227], v[108:111]
	v_mfma_f32_16x16x32_bf16 v[96:99], v[136:139], v[232:235], v[96:99]
	v_mfma_f32_16x16x32_bf16 v[96:99], v[140:143], v[236:239], v[96:99]
	v_mfma_f32_16x16x32_bf16 v[88:91], v[176:179], v[236:239], v[88:91]
	v_mfma_f32_16x16x32_bf16 v[88:91], v[172:175], v[232:235], v[88:91]
	v_mfma_f32_16x16x32_bf16 v[72:75], v[172:175], v[240:243], v[72:75]
	v_mfma_f32_16x16x32_bf16 v[72:75], v[176:179], v[244:247], v[72:75]
	v_mfma_f32_16x16x32_bf16 v[80:83], v[140:143], v[244:247], v[80:83]
	v_mfma_f32_16x16x32_bf16 v[80:83], v[136:139], v[240:243], v[80:83]
	s_setprio 0
	s_setprio 1
	v_mfma_f32_16x16x32_bf16 v[116:119], v[180:183], v[216:219], v[116:119]
	v_mfma_f32_16x16x32_bf16 v[116:119], v[184:187], v[220:223], v[116:119]
	v_mfma_f32_16x16x32_bf16 v[112:115], v[212:215], v[220:223], v[112:115]
	v_mfma_f32_16x16x32_bf16 v[112:115], v[208:211], v[216:219], v[112:115]
	v_mfma_f32_16x16x32_bf16 v[92:95], v[208:211], v[224:227], v[92:95]
	v_mfma_f32_16x16x32_bf16 v[92:95], v[212:215], v[228:231], v[92:95]
	v_mfma_f32_16x16x32_bf16 v[100:103], v[184:187], v[228:231], v[100:103]
	v_mfma_f32_16x16x32_bf16 v[100:103], v[180:183], v[224:227], v[100:103]
	v_mfma_f32_16x16x32_bf16 v[84:87], v[180:183], v[232:235], v[84:87]
	v_mfma_f32_16x16x32_bf16 v[84:87], v[184:187], v[236:239], v[84:87]
	v_mfma_f32_16x16x32_bf16 v[76:79], v[212:215], v[236:239], v[76:79]
	v_mfma_f32_16x16x32_bf16 v[76:79], v[208:211], v[232:235], v[76:79]
	v_mfma_f32_16x16x32_bf16 v[64:67], v[208:211], v[240:243], v[64:67]
	v_mfma_f32_16x16x32_bf16 v[64:67], v[212:215], v[244:247], v[64:67]
	s_setprio 2
	s_barrier
; #define PG8_STAGE(bufoff, gbase, voff) do { _Pragma("unroll") for (int _i = 0; _i < 2; ++_i) \
;         __builtin_amdgcn_global_load_lds((const unsigned*)((const char*)(gbase) + (voff)[_i]), (PG8_LAS unsigned*)(lds + (bufoff) + ldsw + _i * 8192), 16, 0, 0); } while (0)
; #define PG8_LDA(dst, b, h) do { _Pragma("unroll") for (int m = 0; m < 4; ++m) _Pragma("unroll") for (int k = 0; k < 2; ++k) dst[m][k] = *(const PG8_LAS bf16x8*)(lds + PG8_SA(b, h) + aoff + m * 2048 + k * 1024); } while (0)
; #define PG8_MMA(ai, bj, At, Bt) do { __builtin_amdgcn_s_setprio(1); _Pragma("unroll") for (int m = 0; m < 4; ++m) _Pragma("unroll") for (int n = 0; n < 2; ++n) _Pragma("unroll") for (int k = 0; k < 2; ++k) \
;         acc[ai][bj][m][n] = __builtin_amdgcn_mfma_f32_16x16x32_bf16(Bt[n][k], At[m][k], acc[ai][bj][m][n], 0, 0, 0); __builtin_amdgcn_s_setprio(0); } while (0)
; #define PG8_WAIT_V(n) asm volatile("s_waitcnt vmcnt(" #n ")" ::: "memory")
; #define PG8_WAIT_L(n) asm volatile("s_waitcnt lgkmcnt(" #n ")" ::: "memory")
; #define PG8_BAR __builtin_amdgcn_s_barrier()
; #define PG8_SCHED __builtin_amdgcn_sched_barrier(0)
; template <class Epi, class Sched, bool ALIGN_EPI = false, bool SP2 = false>
; __device__ __forceinline__ void gemm_phase(PG8_LAS unsigned char* lds, const Gemm g, const Sched& S, const Epi& E) {
;     ...
;             PG8_WAIT_V(8); PG8_WAIT_L(0); PG8_BAR; PG8_MMA(0, 0, At, B0); PG8_MMA(0, 1, At, B1); PG8_BAR; PG8_SCHED;
;             PG8_LDA(At, 1, 1); PG8_STAGE(PG8_SB(1, 0), b3, voffB); PG8_STAGE(PG8_SB(1, 1), b3 + hstep, voffB); PG8_STAGE(PG8_SA(1, 0), a3, voffA);
;             PG8_WAIT_V(8); PG8_WAIT_L(0); PG8_BAR; PG8_MMA(1, 0, At, B0); PG8_MMA(1, 1, At, B1); PG8_BAR; PG8_SCHED;
;     ...
;         if constexpr (ALIGN_EPI) { if (wr == 0) PG8_BAR; }
	v_mfma_f32_16x16x32_bf16 v[68:71], v[184:187], v[244:247], v[68:71]
	v_mfma_f32_16x16x32_bf16 v[68:71], v[180:183], v[240:243], v[68:71]
	s_setprio 0
	s_add_i32 s44, s44, s52
	v_lshl_add_u64 v[188:189], v[188:189], 0, s[16:17]
	s_mov_b32 m0, s44
	ds_read_b128 v[216:219], v158 offset:49152
	ds_read_b128 v[220:223], v158 offset:50176
	ds_read_b128 v[224:227], v158 offset:51200
	ds_read_b128 v[228:231], v158 offset:52224
	ds_read_b128 v[232:235], v158 offset:53248
	ds_read_b128 v[236:239], v158 offset:54272
	ds_read_b128 v[240:243], v158 offset:55296
	ds_read_b128 v[244:247], v158 offset:56320
	global_load_lds_dwordx4 v[188:189], off
	s_add_i32 m0, s44, 0x2000
	s_add_u32 s42, s42, 0x80080
	v_lshl_add_u64 v[188:189], v[200:201], 0, s[16:17]
	s_addc_u32 s43, s43, 0
	s_add_i32 s44, s45, s52
	global_load_lds_dwordx4 v[188:189], off
	v_lshl_add_u64 v[188:189], s[42:43], 0, v[166:167]
	s_mov_b32 m0, s44
	s_nop 0
	global_load_lds_dwordx4 v[188:189], off
	v_lshl_add_u64 v[188:189], s[42:43], 0, v[170:171]
	s_add_i32 m0, s44, 0x2000
	s_nop 0
	global_load_lds_dwordx4 v[188:189], off
	v_lshl_add_u64 v[188:189], v[248:249], 0, s[16:17]
	s_mov_b32 m0, s62
	s_nop 0
	global_load_lds_dwordx4 v[188:189], off
	v_lshl_add_u64 v[188:189], v[250:251], 0, s[16:17]
	s_mov_b32 m0, s63
	s_nop 0
	global_load_lds_dwordx4 v[188:189], off
	s_waitcnt vmcnt(8)
	s_waitcnt lgkmcnt(0)
	s_barrier
	s_setprio 1
	s_waitcnt lgkmcnt(0)
	v_mfma_f32_16x16x32_bf16 v[60:63], v[136:139], v[216:219], v[60:63]
	v_mfma_f32_16x16x32_bf16 v[60:63], v[140:143], v[220:223], v[60:63]
	v_mfma_f32_16x16x32_bf16 v[56:59], v[176:179], v[220:223], v[56:59]
	v_mfma_f32_16x16x32_bf16 v[56:59], v[172:175], v[216:219], v[56:59]
	v_mfma_f32_16x16x32_bf16 v[40:43], v[172:175], v[224:227], v[40:43]
	v_mfma_f32_16x16x32_bf16 v[40:43], v[176:179], v[228:231], v[40:43]
	v_mfma_f32_16x16x32_bf16 v[48:51], v[140:143], v[228:231], v[48:51]
	v_mfma_f32_16x16x32_bf16 v[48:51], v[136:139], v[224:227], v[48:51]
	v_mfma_f32_16x16x32_bf16 v[32:35], v[136:139], v[232:235], v[32:35]
	v_mfma_f32_16x16x32_bf16 v[32:35], v[140:143], v[236:239], v[32:35]
	v_mfma_f32_16x16x32_bf16 v[24:27], v[176:179], v[236:239], v[24:27]
	v_mfma_f32_16x16x32_bf16 v[24:27], v[172:175], v[232:235], v[24:27]
	v_mfma_f32_16x16x32_bf16 v[8:11], v[172:175], v[240:243], v[8:11]
	v_mfma_f32_16x16x32_bf16 v[8:11], v[176:179], v[244:247], v[8:11]
	v_mfma_f32_16x16x32_bf16 v[12:15], v[140:143], v[244:247], v[12:15]
	v_mfma_f32_16x16x32_bf16 v[12:15], v[136:139], v[240:243], v[12:15]
	s_setprio 0
	s_setprio 1
	v_mfma_f32_16x16x32_bf16 v[52:55], v[180:183], v[216:219], v[52:55]
	v_mfma_f32_16x16x32_bf16 v[52:55], v[184:187], v[220:223], v[52:55]
	v_mfma_f32_16x16x32_bf16 v[44:47], v[212:215], v[220:223], v[44:47]
	v_mfma_f32_16x16x32_bf16 v[44:47], v[208:211], v[216:219], v[44:47]
	v_mfma_f32_16x16x32_bf16 v[28:31], v[208:211], v[224:227], v[28:31]
	v_mfma_f32_16x16x32_bf16 v[28:31], v[212:215], v[228:231], v[28:31]
	v_mfma_f32_16x16x32_bf16 v[36:39], v[184:187], v[228:231], v[36:39]
	v_mfma_f32_16x16x32_bf16 v[36:39], v[180:183], v[224:227], v[36:39]
	v_mfma_f32_16x16x32_bf16 v[20:23], v[180:183], v[232:235], v[20:23]
	v_mfma_f32_16x16x32_bf16 v[20:23], v[184:187], v[236:239], v[20:23]
	v_mfma_f32_16x16x32_bf16 v[16:19], v[212:215], v[236:239], v[16:19]
	v_mfma_f32_16x16x32_bf16 v[16:19], v[208:211], v[232:235], v[16:19]
	v_mfma_f32_16x16x32_bf16 v[0:3], v[208:211], v[240:243], v[0:3]
	v_mfma_f32_16x16x32_bf16 v[0:3], v[212:215], v[244:247], v[0:3]
	s_setprio 2
	s_barrier
	v_mfma_f32_16x16x32_bf16 v[4:7], v[184:187], v[244:247], v[4:7]
	v_mfma_f32_16x16x32_bf16 v[4:7], v[180:183], v[240:243], v[4:7]
	s_setprio 0
	s_add_i32 s71, s71, 2
	s_add_u32 s40, s40, 0x100
	s_addc_u32 s41, s41, 0
	s_add_u32 s69, s69, 0x100
	s_addc_u32 s70, s70, 0
	s_cmp_gt_u32 s71, 29
	s_cbranch_scc0 .LBB0_774
	s_and_b64 vcc, exec, s[18:19]
	s_cbranch_vccz .LBB0_777
	s_barrier

; #define PG8_STAGE(bufoff, gbase, voff) do { _Pragma("unroll") for (int _i = 0; _i < 2; ++_i) \
;         __builtin_amdgcn_global_load_lds((const unsigned*)((const char*)(gbase) + (voff)[_i]), (PG8_LAS unsigned*)(lds + (bufoff) + ldsw + _i * 8192), 16, 0, 0); } while (0)
; #define PG8_LDA(dst, b, h) do { _Pragma("unroll") for (int m = 0; m < 4; ++m) _Pragma("unroll") for (int k = 0; k < 2; ++k) dst[m][k] = *(const PG8_LAS bf16x8*)(lds + PG8_SA(b, h) + aoff + m * 2048 + k * 1024); } while (0)
; #define PG8_LDB(dst, b, h) do { _Pragma("unroll") for (int n = 0; n < 2; ++n) _Pragma("unroll") for (int k = 0; k < 2; ++k) dst[n][k] = *(const PG8_LAS bf16x8*)(lds + PG8_SB(b, h) + boff + n * 2048 + k * 1024); } while (0)
; #define PG8_MMA(ai, bj, At, Bt) do { __builtin_amdgcn_s_setprio(1); _Pragma("unroll") for (int m = 0; m < 4; ++m) _Pragma("unroll") for (int n = 0; n < 2; ++n) _Pragma("unroll") for (int k = 0; k < 2; ++k) \
;         acc[ai][bj][m][n] = __builtin_amdgcn_mfma_f32_16x16x32_bf16(Bt[n][k], At[m][k], acc[ai][bj][m][n], 0, 0, 0); __builtin_amdgcn_s_setprio(0); } while (0)
; #define PG8_WAIT_V(n) asm volatile("s_waitcnt vmcnt(" #n ")" ::: "memory")
; #define PG8_WAIT_L(n) asm volatile("s_waitcnt lgkmcnt(" #n ")" ::: "memory")
; template <class Epi, class Sched, bool ALIGN_EPI = false, bool SP2 = false>
; __device__ __forceinline__ void gemm_phase(PG8_LAS unsigned char* lds, const Gemm g, const Sched& S, const Epi& E) {
;     ...
;             const bool last = (t == nt - 2);
;             const char* a1 = cA + (size_t)(t + 1) * kstep;
;             const char* a2 = last ? nA : cA + (size_t)(t + 2) * kstep; const char* b2 = last ? nB : cB + (size_t)(t + 2) * kstep;
;             const char* a3 = a2 + kstep; const char* b3 = b2 + kstep;
;             if (last && has_next) S.a_ready(nxt);
;             if constexpr (SP2) {
;             PG8_LDB(B0, 0, 0); PG8_LDB(B1, 0, 1); PG8_SCHED; PG8_LDA(At, 0, 0); PG8_STAGE(PG8_SA(1, 1), a1 + hstep, voffA);
;             PG8_WAIT_V(8); PG8_WAIT_L(0); PG8_BAR; PG8_MMA(0, 0, At, B0); PG8_MMA(0, 1, At, B1); PG8_BAR; PG8_SCHED;
;             PG8_LDA(At, 0, 1); PG8_STAGE(PG8_SB(0, 0), b2, voffB); PG8_STAGE(PG8_SB(0, 1), b2 + hstep, voffB); PG8_STAGE(PG8_SA(0, 0), a2, voffA);
;             PG8_WAIT_V(8); PG8_WAIT_L(0); PG8_BAR; PG8_MMA(1, 0, At, B0); PG8_MMA(1, 1, At, B1); PG8_BAR; PG8_SCHED;
.LBB0_837:
	ds_read_b128 v[134:137], v143
	ds_read_b128 v[146:149], v143 offset:1024
	ds_read_b128 v[150:153], v143 offset:2048
	ds_read_b128 v[154:157], v143 offset:3072
	ds_read_b128 v[172:175], v144
	ds_read_b128 v[176:179], v144 offset:1024
	ds_read_b128 v[180:183], v144 offset:2048
	ds_read_b128 v[184:187], v144 offset:3072
	s_add_u32 s44, s42, 0xffea0080
	s_addc_u32 s45, s43, -1
	s_cmpk_eq_i32 s75, 0x54
	s_cselect_b32 s53, s39, s45
	s_cselect_b32 s52, s38, s44
	s_cselect_b32 s49, s41, s35
	s_cselect_b32 s48, s40, s34
	v_lshl_add_u64 v[138:139], s[42:43], 0, v[128:129]
	s_add_i32 m0, s61, 0xc000
	ds_read_b128 v[208:211], v145
	ds_read_b128 v[212:215], v145 offset:1024
	ds_read_b128 v[216:219], v145 offset:2048
	ds_read_b128 v[220:223], v145 offset:3072
	ds_read_b128 v[224:227], v145 offset:4096
	ds_read_b128 v[228:231], v145 offset:5120
	ds_read_b128 v[232:235], v145 offset:6144
	ds_read_b128 v[236:239], v145 offset:7168
	global_load_lds_dwordx4 v[138:139], off
	v_lshl_add_u64 v[138:139], s[42:43], 0, v[130:131]
	s_add_i32 m0, s61, 0xe000
	s_nop 0
	global_load_lds_dwordx4 v[138:139], off
	s_waitcnt vmcnt(8)
	s_waitcnt lgkmcnt(0)
	s_barrier
	s_setprio 1
	s_waitcnt lgkmcnt(0)
	v_mfma_f32_16x16x32_bf16 v[124:127], v[134:137], v[208:211], v[124:127]
	v_mfma_f32_16x16x32_bf16 v[124:127], v[146:149], v[212:215], v[124:127]
	v_mfma_f32_16x16x32_bf16 v[120:123], v[154:157], v[212:215], v[120:123]
	v_mfma_f32_16x16x32_bf16 v[120:123], v[150:153], v[208:211], v[120:123]
	v_mfma_f32_16x16x32_bf16 v[112:115], v[150:153], v[216:219], v[112:115]
	v_mfma_f32_16x16x32_bf16 v[112:115], v[154:157], v[220:223], v[112:115]
	v_mfma_f32_16x16x32_bf16 v[116:119], v[146:149], v[220:223], v[116:119]
	v_mfma_f32_16x16x32_bf16 v[116:119], v[134:137], v[216:219], v[116:119]
	v_mfma_f32_16x16x32_bf16 v[92:95], v[134:137], v[224:227], v[92:95]
	v_mfma_f32_16x16x32_bf16 v[92:95], v[146:149], v[228:231], v[92:95]
	v_mfma_f32_16x16x32_bf16 v[88:91], v[154:157], v[228:231], v[88:91]
	v_mfma_f32_16x16x32_bf16 v[88:91], v[150:153], v[224:227], v[88:91]
	v_mfma_f32_16x16x32_bf16 v[80:83], v[150:153], v[232:235], v[80:83]
	v_mfma_f32_16x16x32_bf16 v[80:83], v[154:157], v[236:239], v[80:83]
	v_mfma_f32_16x16x32_bf16 v[84:87], v[146:149], v[236:239], v[84:87]
	v_mfma_f32_16x16x32_bf16 v[84:87], v[134:137], v[232:235], v[84:87]
	s_setprio 0
	s_setprio 1
	v_mfma_f32_16x16x32_bf16 v[108:111], v[172:175], v[208:211], v[108:111]
	v_mfma_f32_16x16x32_bf16 v[108:111], v[176:179], v[212:215], v[108:111]
	v_mfma_f32_16x16x32_bf16 v[104:107], v[184:187], v[212:215], v[104:107]
	v_mfma_f32_16x16x32_bf16 v[104:107], v[180:183], v[208:211], v[104:107]
	v_mfma_f32_16x16x32_bf16 v[96:99], v[180:183], v[216:219], v[96:99]
	v_mfma_f32_16x16x32_bf16 v[96:99], v[184:187], v[220:223], v[96:99]
	v_mfma_f32_16x16x32_bf16 v[100:103], v[176:179], v[220:223], v[100:103]
	v_mfma_f32_16x16x32_bf16 v[100:103], v[172:175], v[216:219], v[100:103]
	v_mfma_f32_16x16x32_bf16 v[76:79], v[172:175], v[224:227], v[76:79]
	v_mfma_f32_16x16x32_bf16 v[76:79], v[176:179], v[228:231], v[76:79]
	v_mfma_f32_16x16x32_bf16 v[72:75], v[184:187], v[228:231], v[72:75]
	v_mfma_f32_16x16x32_bf16 v[72:75], v[180:183], v[224:227], v[72:75]
	v_mfma_f32_16x16x32_bf16 v[64:67], v[180:183], v[232:235], v[64:67]
	v_mfma_f32_16x16x32_bf16 v[64:67], v[184:187], v[236:239], v[64:67]
	s_setprio 2
	s_barrier
	v_mfma_f32_16x16x32_bf16 v[68:71], v[176:179], v[236:239], v[68:71]
	v_mfma_f32_16x16x32_bf16 v[68:71], v[172:175], v[232:235], v[68:71]
	s_setprio 0
	s_add_i32 s44, s68, s60
	v_lshl_add_u64 v[138:139], s[48:49], 0, v[160:161]
	s_mov_b32 m0, s44
	ds_read_b128 v[208:211], v145 offset:16384
	ds_read_b128 v[212:215], v145 offset:17408
	ds_read_b128 v[216:219], v145 offset:18432
	ds_read_b128 v[220:223], v145 offset:19456
	ds_read_b128 v[224:227], v145 offset:20480
	ds_read_b128 v[228:231], v145 offset:21504
	ds_read_b128 v[232:235], v145 offset:22528
	ds_read_b128 v[236:239], v145 offset:23552
	global_load_lds_dwordx4 v[138:139], off
	s_add_i32 m0, s44, 0x2000
	s_add_u32 s76, s48, 0x160000
	v_lshl_add_u64 v[158:159], s[48:49], 0, v[162:163]
	s_addc_u32 s77, s49, 0
	s_add_i32 s44, s69, s60
	global_load_lds_dwordx4 v[158:159], off
	v_lshl_add_u64 v[188:189], s[76:77], 0, v[160:161]
	s_mov_b32 m0, s44
	v_lshl_add_u64 v[200:201], s[52:53], 0, v[162:163]
	global_load_lds_dwordx4 v[188:189], off
	v_lshl_add_u64 v[188:189], s[76:77], 0, v[162:163]
	s_add_i32 m0, s44, 0x2000
	s_nop 0
	global_load_lds_dwordx4 v[188:189], off
	v_lshl_add_u64 v[188:189], s[52:53], 0, v[160:161]
	s_mov_b32 m0, s61
	s_nop 0
	global_load_lds_dwordx4 v[188:189], off
	s_mov_b32 m0, s62
	s_nop 0
	global_load_lds_dwordx4 v[200:201], off
	s_waitcnt vmcnt(8)
	s_waitcnt lgkmcnt(0)
	s_barrier
; #define PG8_STAGE(bufoff, gbase, voff) do { _Pragma("unroll") for (int _i = 0; _i < 2; ++_i) \
;         __builtin_amdgcn_global_load_lds((const unsigned*)((const char*)(gbase) + (voff)[_i]), (PG8_LAS unsigned*)(lds + (bufoff) + ldsw + _i * 8192), 16, 0, 0); } while (0)
; #define PG8_LDA(dst, b, h) do { _Pragma("unroll") for (int m = 0; m < 4; ++m) _Pragma("unroll") for (int k = 0; k < 2; ++k) dst[m][k] = *(const PG8_LAS bf16x8*)(lds + PG8_SA(b, h) + aoff + m * 2048 + k * 1024); } while (0)
; #define PG8_LDB(dst, b, h) do { _Pragma("unroll") for (int n = 0; n < 2; ++n) _Pragma("unroll") for (int k = 0; k < 2; ++k) dst[n][k] = *(const PG8_LAS bf16x8*)(lds + PG8_SB(b, h) + boff + n * 2048 + k * 1024); } while (0)
; #define PG8_MMA(ai, bj, At, Bt) do { __builtin_amdgcn_s_setprio(1); _Pragma("unroll") for (int m = 0; m < 4; ++m) _Pragma("unroll") for (int n = 0; n < 2; ++n) _Pragma("unroll") for (int k = 0; k < 2; ++k) \
;         acc[ai][bj][m][n] = __builtin_amdgcn_mfma_f32_16x16x32_bf16(Bt[n][k], At[m][k], acc[ai][bj][m][n], 0, 0, 0); __builtin_amdgcn_s_setprio(0); } while (0)
; #define PG8_WAIT_V(n) asm volatile("s_waitcnt vmcnt(" #n ")" ::: "memory")
; #define PG8_WAIT_L(n) asm volatile("s_waitcnt lgkmcnt(" #n ")" ::: "memory")
; #define PG8_BAR __builtin_amdgcn_s_barrier()
; #define PG8_SCHED __builtin_amdgcn_sched_barrier(0)
; template <class Epi, class Sched, bool ALIGN_EPI = false, bool SP2 = false>
; __device__ __forceinline__ void gemm_phase(PG8_LAS unsigned char* lds, const Gemm g, const Sched& S, const Epi& E) {
;     ...
;             PG8_WAIT_V(8); PG8_WAIT_L(0); PG8_BAR; PG8_MMA(1, 0, At, B0); PG8_MMA(1, 1, At, B1); PG8_BAR; PG8_SCHED;
;             PG8_LDB(B0, 1, 0); PG8_LDB(B1, 1, 1); PG8_SCHED; PG8_LDA(At, 1, 0); PG8_STAGE(PG8_SA(0, 1), a2 + hstep, voffA);
;             PG8_WAIT_V(8); PG8_WAIT_L(0); PG8_BAR; PG8_MMA(0, 0, At, B0); PG8_MMA(0, 1, At, B1); PG8_BAR; PG8_SCHED;
	s_setprio 1
	s_waitcnt lgkmcnt(0)
	v_mfma_f32_16x16x32_bf16 v[60:63], v[134:137], v[208:211], v[60:63]
	v_mfma_f32_16x16x32_bf16 v[60:63], v[146:149], v[212:215], v[60:63]
	v_mfma_f32_16x16x32_bf16 v[56:59], v[154:157], v[212:215], v[56:59]
	v_mfma_f32_16x16x32_bf16 v[56:59], v[150:153], v[208:211], v[56:59]
	v_mfma_f32_16x16x32_bf16 v[48:51], v[150:153], v[216:219], v[48:51]
	v_mfma_f32_16x16x32_bf16 v[48:51], v[154:157], v[220:223], v[48:51]
	v_mfma_f32_16x16x32_bf16 v[52:55], v[146:149], v[220:223], v[52:55]
	v_mfma_f32_16x16x32_bf16 v[52:55], v[134:137], v[216:219], v[52:55]
	v_mfma_f32_16x16x32_bf16 v[28:31], v[134:137], v[224:227], v[28:31]
	v_mfma_f32_16x16x32_bf16 v[28:31], v[146:149], v[228:231], v[28:31]
	v_mfma_f32_16x16x32_bf16 v[24:27], v[154:157], v[228:231], v[24:27]
	v_mfma_f32_16x16x32_bf16 v[24:27], v[150:153], v[224:227], v[24:27]
	v_mfma_f32_16x16x32_bf16 v[16:19], v[150:153], v[232:235], v[16:19]
	v_mfma_f32_16x16x32_bf16 v[16:19], v[154:157], v[236:239], v[16:19]
	v_mfma_f32_16x16x32_bf16 v[20:23], v[146:149], v[236:239], v[20:23]
	v_mfma_f32_16x16x32_bf16 v[20:23], v[134:137], v[232:235], v[20:23]
	s_setprio 0
	s_setprio 1
	v_mfma_f32_16x16x32_bf16 v[44:47], v[172:175], v[208:211], v[44:47]
	v_mfma_f32_16x16x32_bf16 v[44:47], v[176:179], v[212:215], v[44:47]
	v_mfma_f32_16x16x32_bf16 v[40:43], v[184:187], v[212:215], v[40:43]
	v_mfma_f32_16x16x32_bf16 v[40:43], v[180:183], v[208:211], v[40:43]
	v_mfma_f32_16x16x32_bf16 v[32:35], v[180:183], v[216:219], v[32:35]
	v_mfma_f32_16x16x32_bf16 v[32:35], v[184:187], v[220:223], v[32:35]
	v_mfma_f32_16x16x32_bf16 v[36:39], v[176:179], v[220:223], v[36:39]
	v_mfma_f32_16x16x32_bf16 v[36:39], v[172:175], v[216:219], v[36:39]
	v_mfma_f32_16x16x32_bf16 v[12:15], v[172:175], v[224:227], v[12:15]
	v_mfma_f32_16x16x32_bf16 v[12:15], v[176:179], v[228:231], v[12:15]
	v_mfma_f32_16x16x32_bf16 v[8:11], v[184:187], v[228:231], v[8:11]
	v_mfma_f32_16x16x32_bf16 v[8:11], v[180:183], v[224:227], v[8:11]
	v_mfma_f32_16x16x32_bf16 v[0:3], v[180:183], v[232:235], v[0:3]
	v_mfma_f32_16x16x32_bf16 v[0:3], v[184:187], v[236:239], v[0:3]
	s_setprio 2
	s_barrier
	v_mfma_f32_16x16x32_bf16 v[4:7], v[176:179], v[236:239], v[4:7]
	v_mfma_f32_16x16x32_bf16 v[4:7], v[172:175], v[232:235], v[4:7]
	s_setprio 0
	s_add_i32 s44, 0, 0x18000
	s_add_i32 s45, 0, 0x1c000
	v_add_u32_e32 v154, s44, v141
	v_add_u32_e32 v165, s45, v141
	ds_read_b128 v[134:137], v154
	ds_read_b128 v[146:149], v154 offset:1024
	ds_read_b128 v[150:153], v154 offset:2048
	ds_read_b128 v[154:157], v154 offset:3072
	ds_read_b128 v[172:175], v165
	ds_read_b128 v[176:179], v165 offset:1024
	ds_read_b128 v[180:183], v165 offset:2048
	ds_read_b128 v[184:187], v165 offset:3072
	s_add_u32 s52, s52, 0x160000
	s_addc_u32 s53, s53, 0
	s_mov_b32 m0, s63
	v_lshl_add_u64 v[240:241], s[52:53], 0, v[160:161]
	ds_read_b128 v[208:211], v145 offset:32768
	ds_read_b128 v[212:215], v145 offset:33792
	ds_read_b128 v[216:219], v145 offset:34816
	ds_read_b128 v[220:223], v145 offset:35840
	ds_read_b128 v[224:227], v145 offset:36864
	ds_read_b128 v[228:231], v145 offset:37888
	ds_read_b128 v[232:235], v145 offset:38912
	ds_read_b128 v[236:239], v145 offset:39936
	global_load_lds_dwordx4 v[240:241], off
	v_lshl_add_u64 v[240:241], s[52:53], 0, v[162:163]
	s_mov_b32 m0, s64
	s_nop 0
	global_load_lds_dwordx4 v[240:241], off
	s_waitcnt vmcnt(8)
	s_waitcnt lgkmcnt(0)
	s_barrier
	s_setprio 1
	s_waitcnt lgkmcnt(0)
	v_mfma_f32_16x16x32_bf16 v[124:127], v[134:137], v[208:211], v[124:127]
	v_mfma_f32_16x16x32_bf16 v[124:127], v[146:149], v[212:215], v[124:127]
	v_mfma_f32_16x16x32_bf16 v[120:123], v[154:157], v[212:215], v[120:123]
	v_mfma_f32_16x16x32_bf16 v[120:123], v[150:153], v[208:211], v[120:123]
	v_mfma_f32_16x16x32_bf16 v[112:115], v[150:153], v[216:219], v[112:115]
	v_mfma_f32_16x16x32_bf16 v[112:115], v[154:157], v[220:223], v[112:115]
	v_mfma_f32_16x16x32_bf16 v[116:119], v[146:149], v[220:223], v[116:119]
	v_mfma_f32_16x16x32_bf16 v[116:119], v[134:137], v[216:219], v[116:119]
	v_mfma_f32_16x16x32_bf16 v[92:95], v[134:137], v[224:227], v[92:95]
	v_mfma_f32_16x16x32_bf16 v[92:95], v[146:149], v[228:231], v[92:95]
	v_mfma_f32_16x16x32_bf16 v[88:91], v[154:157], v[228:231], v[88:91]
	v_mfma_f32_16x16x32_bf16 v[88:91], v[150:153], v[224:227], v[88:91]
	v_mfma_f32_16x16x32_bf16 v[80:83], v[150:153], v[232:235], v[80:83]
	v_mfma_f32_16x16x32_bf16 v[80:83], v[154:157], v[236:239], v[80:83]
	v_mfma_f32_16x16x32_bf16 v[84:87], v[146:149], v[236:239], v[84:87]
	v_mfma_f32_16x16x32_bf16 v[84:87], v[134:137], v[232:235], v[84:87]
	s_setprio 0
	s_setprio 1
	v_mfma_f32_16x16x32_bf16 v[108:111], v[172:175], v[208:211], v[108:111]
	v_mfma_f32_16x16x32_bf16 v[108:111], v[176:179], v[212:215], v[108:111]
	v_mfma_f32_16x16x32_bf16 v[104:107], v[184:187], v[212:215], v[104:107]
	v_mfma_f32_16x16x32_bf16 v[104:107], v[180:183], v[208:211], v[104:107]
	v_mfma_f32_16x16x32_bf16 v[96:99], v[180:183], v[216:219], v[96:99]
	v_mfma_f32_16x16x32_bf16 v[96:99], v[184:187], v[220:223], v[96:99]
	v_mfma_f32_16x16x32_bf16 v[100:103], v[176:179], v[220:223], v[100:103]
	v_mfma_f32_16x16x32_bf16 v[100:103], v[172:175], v[216:219], v[100:103]
	v_mfma_f32_16x16x32_bf16 v[76:79], v[172:175], v[224:227], v[76:79]
	v_mfma_f32_16x16x32_bf16 v[76:79], v[176:179], v[228:231], v[76:79]
	v_mfma_f32_16x16x32_bf16 v[72:75], v[184:187], v[228:231], v[72:75]
	v_mfma_f32_16x16x32_bf16 v[72:75], v[180:183], v[224:227], v[72:75]
	v_mfma_f32_16x16x32_bf16 v[64:67], v[180:183], v[232:235], v[64:67]
	v_mfma_f32_16x16x32_bf16 v[64:67], v[184:187], v[236:239], v[64:67]
	s_setprio 2
	s_barrier
; #define PG8_STAGE(bufoff, gbase, voff) do { _Pragma("unroll") for (int _i = 0; _i < 2; ++_i) \
;         __builtin_amdgcn_global_load_lds((const unsigned*)((const char*)(gbase) + (voff)[_i]), (PG8_LAS unsigned*)(lds + (bufoff) + ldsw + _i * 8192), 16, 0, 0); } while (0)
; #define PG8_LDA(dst, b, h) do { _Pragma("unroll") for (int m = 0; m < 4; ++m) _Pragma("unroll") for (int k = 0; k < 2; ++k) dst[m][k] = *(const PG8_LAS bf16x8*)(lds + PG8_SA(b, h) + aoff + m * 2048 + k * 1024); } while (0)
; #define PG8_MMA(ai, bj, At, Bt) do { __builtin_amdgcn_s_setprio(1); _Pragma("unroll") for (int m = 0; m < 4; ++m) _Pragma("unroll") for (int n = 0; n < 2; ++n) _Pragma("unroll") for (int k = 0; k < 2; ++k) \
;         acc[ai][bj][m][n] = __builtin_amdgcn_mfma_f32_16x16x32_bf16(Bt[n][k], At[m][k], acc[ai][bj][m][n], 0, 0, 0); __builtin_amdgcn_s_setprio(0); } while (0)
; #define PG8_WAIT_V(n) asm volatile("s_waitcnt vmcnt(" #n ")" ::: "memory")
; #define PG8_WAIT_L(n) asm volatile("s_waitcnt lgkmcnt(" #n ")" ::: "memory")
; #define PG8_BAR __builtin_amdgcn_s_barrier()
; #define PG8_SCHED __builtin_amdgcn_sched_barrier(0)
; template <class Epi, class Sched, bool ALIGN_EPI = false, bool SP2 = false>
; __device__ __forceinline__ void gemm_phase(PG8_LAS unsigned char* lds, const Gemm g, const Sched& S, const Epi& E) {
;     ...
;             PG8_WAIT_V(8); PG8_WAIT_L(0); PG8_BAR; PG8_MMA(0, 0, At, B0); PG8_MMA(0, 1, At, B1); PG8_BAR; PG8_SCHED;
;             PG8_LDA(At, 1, 1); PG8_STAGE(PG8_SB(1, 0), b3, voffB); PG8_STAGE(PG8_SB(1, 1), b3 + hstep, voffB); PG8_STAGE(PG8_SA(1, 0), a3, voffA);
;             PG8_WAIT_V(8); PG8_WAIT_L(0); PG8_BAR; PG8_MMA(1, 0, At, B0); PG8_MMA(1, 1, At, B1); PG8_BAR; PG8_SCHED;
;     ...
;         if constexpr (ALIGN_EPI) { if (wr == 0) PG8_BAR; }
	v_mfma_f32_16x16x32_bf16 v[68:71], v[176:179], v[236:239], v[68:71]
	v_mfma_f32_16x16x32_bf16 v[68:71], v[172:175], v[232:235], v[68:71]
	s_setprio 0
	s_add_i32 s44, s44, s60
	v_lshl_add_u64 v[138:139], v[138:139], 0, s[16:17]
	s_mov_b32 m0, s44
	ds_read_b128 v[208:211], v145 offset:49152
	ds_read_b128 v[212:215], v145 offset:50176
	ds_read_b128 v[216:219], v145 offset:51200
	ds_read_b128 v[220:223], v145 offset:52224
	ds_read_b128 v[224:227], v145 offset:53248
	ds_read_b128 v[228:231], v145 offset:54272
	ds_read_b128 v[232:235], v145 offset:55296
	ds_read_b128 v[236:239], v145 offset:56320
	global_load_lds_dwordx4 v[138:139], off
	s_add_i32 m0, s44, 0x2000
	s_add_u32 s48, s48, 0x160080
	v_lshl_add_u64 v[138:139], v[158:159], 0, s[16:17]
	s_addc_u32 s49, s49, 0
	s_add_i32 s44, s45, s60
	global_load_lds_dwordx4 v[138:139], off
	v_lshl_add_u64 v[138:139], s[48:49], 0, v[160:161]
	s_mov_b32 m0, s44
	s_nop 0
	global_load_lds_dwordx4 v[138:139], off
	v_lshl_add_u64 v[138:139], s[48:49], 0, v[162:163]
	s_add_i32 m0, s44, 0x2000
	s_nop 0
	global_load_lds_dwordx4 v[138:139], off
	v_lshl_add_u64 v[138:139], v[188:189], 0, s[16:17]
	s_mov_b32 m0, s65
	s_nop 0
	global_load_lds_dwordx4 v[138:139], off
	v_lshl_add_u64 v[138:139], v[200:201], 0, s[16:17]
	s_mov_b32 m0, s66
	s_nop 0
	global_load_lds_dwordx4 v[138:139], off
	s_waitcnt vmcnt(8)
	s_waitcnt lgkmcnt(0)
	s_barrier
	s_setprio 1
	s_waitcnt lgkmcnt(0)
	v_mfma_f32_16x16x32_bf16 v[60:63], v[134:137], v[208:211], v[60:63]
	v_mfma_f32_16x16x32_bf16 v[60:63], v[146:149], v[212:215], v[60:63]
	v_mfma_f32_16x16x32_bf16 v[56:59], v[154:157], v[212:215], v[56:59]
	v_mfma_f32_16x16x32_bf16 v[56:59], v[150:153], v[208:211], v[56:59]
	v_mfma_f32_16x16x32_bf16 v[48:51], v[150:153], v[216:219], v[48:51]
	v_mfma_f32_16x16x32_bf16 v[48:51], v[154:157], v[220:223], v[48:51]
	v_mfma_f32_16x16x32_bf16 v[52:55], v[146:149], v[220:223], v[52:55]
	v_mfma_f32_16x16x32_bf16 v[52:55], v[134:137], v[216:219], v[52:55]
	v_mfma_f32_16x16x32_bf16 v[28:31], v[134:137], v[224:227], v[28:31]
	v_mfma_f32_16x16x32_bf16 v[28:31], v[146:149], v[228:231], v[28:31]
	v_mfma_f32_16x16x32_bf16 v[24:27], v[154:157], v[228:231], v[24:27]
	v_mfma_f32_16x16x32_bf16 v[24:27], v[150:153], v[224:227], v[24:27]
	v_mfma_f32_16x16x32_bf16 v[16:19], v[150:153], v[232:235], v[16:19]
	v_mfma_f32_16x16x32_bf16 v[16:19], v[154:157], v[236:239], v[16:19]
	v_mfma_f32_16x16x32_bf16 v[20:23], v[146:149], v[236:239], v[20:23]
	v_mfma_f32_16x16x32_bf16 v[20:23], v[134:137], v[232:235], v[20:23]
	s_setprio 0
	s_setprio 1
	v_mfma_f32_16x16x32_bf16 v[44:47], v[172:175], v[208:211], v[44:47]
	v_mfma_f32_16x16x32_bf16 v[44:47], v[176:179], v[212:215], v[44:47]
	v_mfma_f32_16x16x32_bf16 v[40:43], v[184:187], v[212:215], v[40:43]
	v_mfma_f32_16x16x32_bf16 v[40:43], v[180:183], v[208:211], v[40:43]
	v_mfma_f32_16x16x32_bf16 v[32:35], v[180:183], v[216:219], v[32:35]
	v_mfma_f32_16x16x32_bf16 v[32:35], v[184:187], v[220:223], v[32:35]
	v_mfma_f32_16x16x32_bf16 v[36:39], v[176:179], v[220:223], v[36:39]
	v_mfma_f32_16x16x32_bf16 v[36:39], v[172:175], v[216:219], v[36:39]
	v_mfma_f32_16x16x32_bf16 v[12:15], v[172:175], v[224:227], v[12:15]
	v_mfma_f32_16x16x32_bf16 v[12:15], v[176:179], v[228:231], v[12:15]
	v_mfma_f32_16x16x32_bf16 v[8:11], v[184:187], v[228:231], v[8:11]
	v_mfma_f32_16x16x32_bf16 v[8:11], v[180:183], v[224:227], v[8:11]
	v_mfma_f32_16x16x32_bf16 v[0:3], v[180:183], v[232:235], v[0:3]
	v_mfma_f32_16x16x32_bf16 v[0:3], v[184:187], v[236:239], v[0:3]
	s_setprio 2
	s_barrier
	v_mfma_f32_16x16x32_bf16 v[4:7], v[176:179], v[236:239], v[4:7]
	v_mfma_f32_16x16x32_bf16 v[4:7], v[172:175], v[232:235], v[4:7]
	s_setprio 0
	s_add_i32 s75, s75, 2
	s_add_u32 s42, s42, 0x100
	s_addc_u32 s43, s43, 0
	s_add_u32 s34, s34, 0x100
	s_addc_u32 s35, s35, 0
	s_cmpk_gt_u32 s75, 0x55
	s_cbranch_scc0 .LBB0_837
	s_and_b64 vcc, exec, s[18:19]
	s_cbranch_vccz .LBB0_840
	s_barrier

; #define PG8_STAGE(bufoff, gbase, voff) do { _Pragma("unroll") for (int _i = 0; _i < 2; ++_i) \
;         __builtin_amdgcn_global_load_lds((const unsigned*)((const char*)(gbase) + (voff)[_i]), (PG8_LAS unsigned*)(lds + (bufoff) + ldsw + _i * 8192), 16, 0, 0); } while (0)
; #define PG8_LDA(dst, b, h) do { _Pragma("unroll") for (int m = 0; m < 4; ++m) _Pragma("unroll") for (int k = 0; k < 2; ++k) dst[m][k] = *(const PG8_LAS bf16x8*)(lds + PG8_SA(b, h) + aoff + m * 2048 + k * 1024); } while (0)
; #define PG8_LDB(dst, b, h) do { _Pragma("unroll") for (int n = 0; n < 2; ++n) _Pragma("unroll") for (int k = 0; k < 2; ++k) dst[n][k] = *(const PG8_LAS bf16x8*)(lds + PG8_SB(b, h) + boff + n * 2048 + k * 1024); } while (0)
; #define PG8_MMA(ai, bj, At, Bt) do { __builtin_amdgcn_s_setprio(1); _Pragma("unroll") for (int m = 0; m < 4; ++m) _Pragma("unroll") for (int n = 0; n < 2; ++n) _Pragma("unroll") for (int k = 0; k < 2; ++k) \
;         acc[ai][bj][m][n] = __builtin_amdgcn_mfma_f32_16x16x32_bf16(Bt[n][k], At[m][k], acc[ai][bj][m][n], 0, 0, 0); __builtin_amdgcn_s_setprio(0); } while (0)
; #define PG8_WAIT_V(n) asm volatile("s_waitcnt vmcnt(" #n ")" ::: "memory")
; #define PG8_WAIT_L(n) asm volatile("s_waitcnt lgkmcnt(" #n ")" ::: "memory")
; template <class Epi, class Sched, bool ALIGN_EPI = false, bool SP2 = false>
; __device__ __forceinline__ void gemm_phase(PG8_LAS unsigned char* lds, const Gemm g, const Sched& S, const Epi& E) {
;     ...
;             const bool last = (t == nt - 2);
;             const char* a1 = cA + (size_t)(t + 1) * kstep;
;             const char* a2 = last ? nA : cA + (size_t)(t + 2) * kstep; const char* b2 = last ? nB : cB + (size_t)(t + 2) * kstep;
;             const char* a3 = a2 + kstep; const char* b3 = b2 + kstep;
;             if (last && has_next) S.a_ready(nxt);
;             if constexpr (SP2) {
;             PG8_LDB(B0, 0, 0); PG8_LDB(B1, 0, 1); PG8_SCHED; PG8_LDA(At, 0, 0); PG8_STAGE(PG8_SA(1, 1), a1 + hstep, voffA);
;             PG8_WAIT_V(8); PG8_WAIT_L(0); PG8_BAR; PG8_MMA(0, 0, At, B0); PG8_MMA(0, 1, At, B1); PG8_BAR; PG8_SCHED;
;             PG8_LDA(At, 0, 1); PG8_STAGE(PG8_SB(0, 0), b2, voffB); PG8_STAGE(PG8_SB(0, 1), b2 + hstep, voffB); PG8_STAGE(PG8_SA(0, 0), a2, voffA);
;             PG8_WAIT_V(8); PG8_WAIT_L(0); PG8_BAR; PG8_MMA(1, 0, At, B0); PG8_MMA(1, 1, At, B1); PG8_BAR; PG8_SCHED;
.LBB0_880:
	ds_read_b128 v[136:139], v156
	ds_read_b128 v[140:143], v156 offset:1024
	ds_read_b128 v[172:175], v156 offset:2048
	ds_read_b128 v[176:179], v156 offset:3072
	ds_read_b128 v[180:183], v157
	ds_read_b128 v[184:187], v157 offset:1024
	ds_read_b128 v[196:199], v157 offset:2048
	ds_read_b128 v[208:211], v157 offset:3072
	s_add_u32 s40, s38, 0xfff80080
	s_addc_u32 s41, s39, -1
	s_cmp_eq_u32 s63, 28
	s_cselect_b32 s43, s19, s41
	s_cselect_b32 s42, s34, s40
	s_cselect_b32 s41, s21, s62
	s_cselect_b32 s40, s35, s61
	v_lshl_add_u64 v[188:189], s[38:39], 0, v[128:129]
	s_add_i32 m0, s7, 0xc000
	ds_read_b128 v[212:215], v158
	ds_read_b128 v[216:219], v158 offset:1024
	ds_read_b128 v[220:223], v158 offset:2048
	ds_read_b128 v[224:227], v158 offset:3072
	ds_read_b128 v[228:231], v158 offset:4096
	ds_read_b128 v[232:235], v158 offset:5120
	ds_read_b128 v[236:239], v158 offset:6144
	ds_read_b128 v[240:243], v158 offset:7168
	global_load_lds_dwordx4 v[188:189], off
	v_lshl_add_u64 v[188:189], s[38:39], 0, v[130:131]
	s_add_i32 m0, s7, 0xe000
	s_nop 0
	global_load_lds_dwordx4 v[188:189], off
	s_waitcnt vmcnt(8)
	s_waitcnt lgkmcnt(0)
	s_barrier
	s_setprio 1
	s_waitcnt lgkmcnt(0)
	v_mfma_f32_16x16x32_bf16 v[124:127], v[136:139], v[212:215], v[124:127]
	v_mfma_f32_16x16x32_bf16 v[124:127], v[140:143], v[216:219], v[124:127]
	v_mfma_f32_16x16x32_bf16 v[120:123], v[176:179], v[216:219], v[120:123]
	v_mfma_f32_16x16x32_bf16 v[120:123], v[172:175], v[212:215], v[120:123]
	v_mfma_f32_16x16x32_bf16 v[104:107], v[172:175], v[220:223], v[104:107]
	v_mfma_f32_16x16x32_bf16 v[104:107], v[176:179], v[224:227], v[104:107]
	v_mfma_f32_16x16x32_bf16 v[108:111], v[140:143], v[224:227], v[108:111]
	v_mfma_f32_16x16x32_bf16 v[108:111], v[136:139], v[220:223], v[108:111]
	v_mfma_f32_16x16x32_bf16 v[96:99], v[136:139], v[228:231], v[96:99]
	v_mfma_f32_16x16x32_bf16 v[96:99], v[140:143], v[232:235], v[96:99]
	v_mfma_f32_16x16x32_bf16 v[88:91], v[176:179], v[232:235], v[88:91]
	v_mfma_f32_16x16x32_bf16 v[88:91], v[172:175], v[228:231], v[88:91]
	v_mfma_f32_16x16x32_bf16 v[72:75], v[172:175], v[236:239], v[72:75]
	v_mfma_f32_16x16x32_bf16 v[72:75], v[176:179], v[240:243], v[72:75]
	v_mfma_f32_16x16x32_bf16 v[80:83], v[140:143], v[240:243], v[80:83]
	v_mfma_f32_16x16x32_bf16 v[80:83], v[136:139], v[236:239], v[80:83]
	s_setprio 0
	s_setprio 1
	v_mfma_f32_16x16x32_bf16 v[116:119], v[180:183], v[212:215], v[116:119]
	v_mfma_f32_16x16x32_bf16 v[116:119], v[184:187], v[216:219], v[116:119]
	v_mfma_f32_16x16x32_bf16 v[112:115], v[208:211], v[216:219], v[112:115]
	v_mfma_f32_16x16x32_bf16 v[112:115], v[196:199], v[212:215], v[112:115]
	v_mfma_f32_16x16x32_bf16 v[92:95], v[196:199], v[220:223], v[92:95]
	v_mfma_f32_16x16x32_bf16 v[92:95], v[208:211], v[224:227], v[92:95]
	v_mfma_f32_16x16x32_bf16 v[100:103], v[184:187], v[224:227], v[100:103]
	v_mfma_f32_16x16x32_bf16 v[100:103], v[180:183], v[220:223], v[100:103]
	v_mfma_f32_16x16x32_bf16 v[84:87], v[180:183], v[228:231], v[84:87]
	v_mfma_f32_16x16x32_bf16 v[84:87], v[184:187], v[232:235], v[84:87]
	v_mfma_f32_16x16x32_bf16 v[76:79], v[208:211], v[232:235], v[76:79]
	v_mfma_f32_16x16x32_bf16 v[76:79], v[196:199], v[228:231], v[76:79]
	v_mfma_f32_16x16x32_bf16 v[64:67], v[196:199], v[236:239], v[64:67]
	v_mfma_f32_16x16x32_bf16 v[64:67], v[208:211], v[240:243], v[64:67]
	s_setprio 2
	s_barrier
	v_mfma_f32_16x16x32_bf16 v[68:71], v[184:187], v[240:243], v[68:71]
	v_mfma_f32_16x16x32_bf16 v[68:71], v[180:183], v[236:239], v[68:71]
	s_setprio 0
	s_add_i32 s44, s52, s33
	v_lshl_add_u64 v[188:189], s[40:41], 0, v[166:167]
	s_mov_b32 m0, s44
	ds_read_b128 v[212:215], v158 offset:16384
	ds_read_b128 v[216:219], v158 offset:17408
	ds_read_b128 v[220:223], v158 offset:18432
	ds_read_b128 v[224:227], v158 offset:19456
	ds_read_b128 v[228:231], v158 offset:20480
	ds_read_b128 v[232:235], v158 offset:21504
	ds_read_b128 v[236:239], v158 offset:22528
	ds_read_b128 v[240:243], v158 offset:23552
	global_load_lds_dwordx4 v[188:189], off
	s_add_i32 m0, s44, 0x2000
	s_add_u32 s64, s40, 0x80000
	v_lshl_add_u64 v[200:201], s[40:41], 0, v[170:171]
	s_addc_u32 s65, s41, 0
	s_add_i32 s44, s53, s33
	global_load_lds_dwordx4 v[200:201], off
	v_lshl_add_u64 v[244:245], s[64:65], 0, v[166:167]
	s_mov_b32 m0, s44
	v_lshl_add_u64 v[246:247], s[42:43], 0, v[168:169]
	global_load_lds_dwordx4 v[244:245], off
	v_lshl_add_u64 v[244:245], s[64:65], 0, v[170:171]
	s_add_i32 m0, s44, 0x2000
	s_nop 0
	global_load_lds_dwordx4 v[244:245], off
	v_lshl_add_u64 v[244:245], s[42:43], 0, v[164:165]
	s_mov_b32 m0, s7
	s_nop 0
	global_load_lds_dwordx4 v[244:245], off
	s_mov_b32 m0, s37
	s_nop 0
	global_load_lds_dwordx4 v[246:247], off
	s_waitcnt vmcnt(8)
	s_waitcnt lgkmcnt(0)
	s_barrier
; #define PG8_STAGE(bufoff, gbase, voff) do { _Pragma("unroll") for (int _i = 0; _i < 2; ++_i) \
;         __builtin_amdgcn_global_load_lds((const unsigned*)((const char*)(gbase) + (voff)[_i]), (PG8_LAS unsigned*)(lds + (bufoff) + ldsw + _i * 8192), 16, 0, 0); } while (0)
; #define PG8_LDA(dst, b, h) do { _Pragma("unroll") for (int m = 0; m < 4; ++m) _Pragma("unroll") for (int k = 0; k < 2; ++k) dst[m][k] = *(const PG8_LAS bf16x8*)(lds + PG8_SA(b, h) + aoff + m * 2048 + k * 1024); } while (0)
; #define PG8_LDB(dst, b, h) do { _Pragma("unroll") for (int n = 0; n < 2; ++n) _Pragma("unroll") for (int k = 0; k < 2; ++k) dst[n][k] = *(const PG8_LAS bf16x8*)(lds + PG8_SB(b, h) + boff + n * 2048 + k * 1024); } while (0)
; #define PG8_MMA(ai, bj, At, Bt) do { __builtin_amdgcn_s_setprio(1); _Pragma("unroll") for (int m = 0; m < 4; ++m) _Pragma("unroll") for (int n = 0; n < 2; ++n) _Pragma("unroll") for (int k = 0; k < 2; ++k) \
;         acc[ai][bj][m][n] = __builtin_amdgcn_mfma_f32_16x16x32_bf16(Bt[n][k], At[m][k], acc[ai][bj][m][n], 0, 0, 0); __builtin_amdgcn_s_setprio(0); } while (0)
; #define PG8_WAIT_V(n) asm volatile("s_waitcnt vmcnt(" #n ")" ::: "memory")
; #define PG8_WAIT_L(n) asm volatile("s_waitcnt lgkmcnt(" #n ")" ::: "memory")
; #define PG8_BAR __builtin_amdgcn_s_barrier()
; #define PG8_SCHED __builtin_amdgcn_sched_barrier(0)
; template <class Epi, class Sched, bool ALIGN_EPI = false, bool SP2 = false>
; __device__ __forceinline__ void gemm_phase(PG8_LAS unsigned char* lds, const Gemm g, const Sched& S, const Epi& E) {
;     ...
;             PG8_WAIT_V(8); PG8_WAIT_L(0); PG8_BAR; PG8_MMA(1, 0, At, B0); PG8_MMA(1, 1, At, B1); PG8_BAR; PG8_SCHED;
;             PG8_LDB(B0, 1, 0); PG8_LDB(B1, 1, 1); PG8_SCHED; PG8_LDA(At, 1, 0); PG8_STAGE(PG8_SA(0, 1), a2 + hstep, voffA);
;             PG8_WAIT_V(8); PG8_WAIT_L(0); PG8_BAR; PG8_MMA(0, 0, At, B0); PG8_MMA(0, 1, At, B1); PG8_BAR; PG8_SCHED;
	s_setprio 1
	s_waitcnt lgkmcnt(0)
	v_mfma_f32_16x16x32_bf16 v[60:63], v[136:139], v[212:215], v[60:63]
	v_mfma_f32_16x16x32_bf16 v[60:63], v[140:143], v[216:219], v[60:63]
	v_mfma_f32_16x16x32_bf16 v[56:59], v[176:179], v[216:219], v[56:59]
	v_mfma_f32_16x16x32_bf16 v[56:59], v[172:175], v[212:215], v[56:59]
	v_mfma_f32_16x16x32_bf16 v[40:43], v[172:175], v[220:223], v[40:43]
	v_mfma_f32_16x16x32_bf16 v[40:43], v[176:179], v[224:227], v[40:43]
	v_mfma_f32_16x16x32_bf16 v[48:51], v[140:143], v[224:227], v[48:51]
	v_mfma_f32_16x16x32_bf16 v[48:51], v[136:139], v[220:223], v[48:51]
	v_mfma_f32_16x16x32_bf16 v[32:35], v[136:139], v[228:231], v[32:35]
	v_mfma_f32_16x16x32_bf16 v[32:35], v[140:143], v[232:235], v[32:35]
	v_mfma_f32_16x16x32_bf16 v[24:27], v[176:179], v[232:235], v[24:27]
	v_mfma_f32_16x16x32_bf16 v[24:27], v[172:175], v[228:231], v[24:27]
	v_mfma_f32_16x16x32_bf16 v[8:11], v[172:175], v[236:239], v[8:11]
	v_mfma_f32_16x16x32_bf16 v[8:11], v[176:179], v[240:243], v[8:11]
	v_mfma_f32_16x16x32_bf16 v[12:15], v[140:143], v[240:243], v[12:15]
	v_mfma_f32_16x16x32_bf16 v[12:15], v[136:139], v[236:239], v[12:15]
	s_setprio 0
	s_setprio 1
	v_mfma_f32_16x16x32_bf16 v[52:55], v[180:183], v[212:215], v[52:55]
	v_mfma_f32_16x16x32_bf16 v[52:55], v[184:187], v[216:219], v[52:55]
	v_mfma_f32_16x16x32_bf16 v[44:47], v[208:211], v[216:219], v[44:47]
	v_mfma_f32_16x16x32_bf16 v[44:47], v[196:199], v[212:215], v[44:47]
	v_mfma_f32_16x16x32_bf16 v[28:31], v[196:199], v[220:223], v[28:31]
	v_mfma_f32_16x16x32_bf16 v[28:31], v[208:211], v[224:227], v[28:31]
	v_mfma_f32_16x16x32_bf16 v[36:39], v[184:187], v[224:227], v[36:39]
	v_mfma_f32_16x16x32_bf16 v[36:39], v[180:183], v[220:223], v[36:39]
	v_mfma_f32_16x16x32_bf16 v[20:23], v[180:183], v[228:231], v[20:23]
	v_mfma_f32_16x16x32_bf16 v[20:23], v[184:187], v[232:235], v[20:23]
	v_mfma_f32_16x16x32_bf16 v[16:19], v[208:211], v[232:235], v[16:19]
	v_mfma_f32_16x16x32_bf16 v[16:19], v[196:199], v[228:231], v[16:19]
	v_mfma_f32_16x16x32_bf16 v[0:3], v[196:199], v[236:239], v[0:3]
	v_mfma_f32_16x16x32_bf16 v[0:3], v[208:211], v[240:243], v[0:3]
	s_setprio 2
	s_barrier
	v_mfma_f32_16x16x32_bf16 v[4:7], v[184:187], v[240:243], v[4:7]
	v_mfma_f32_16x16x32_bf16 v[4:7], v[180:183], v[236:239], v[4:7]
	s_setprio 0
	s_add_i32 s44, 0, 0x18000
	v_add_u32_e32 v144, s44, v146
	s_add_i32 s45, 0, 0x1c000
	ds_read_b128 v[136:139], v144
	ds_read_b128 v[140:143], v144 offset:1024
	ds_read_b128 v[172:175], v144 offset:2048
	ds_read_b128 v[176:179], v144 offset:3072
	v_add_u32_e32 v144, s45, v146
	ds_read_b128 v[180:183], v144
	ds_read_b128 v[184:187], v144 offset:1024
	ds_read_b128 v[196:199], v144 offset:2048
	ds_read_b128 v[208:211], v144 offset:3072
	s_add_u32 s42, s42, 0x80000
	s_addc_u32 s43, s43, 0
	s_mov_b32 m0, s48
	v_lshl_add_u64 v[248:249], s[42:43], 0, v[164:165]
	ds_read_b128 v[212:215], v158 offset:32768
	ds_read_b128 v[216:219], v158 offset:33792
	ds_read_b128 v[220:223], v158 offset:34816
	ds_read_b128 v[224:227], v158 offset:35840
	ds_read_b128 v[228:231], v158 offset:36864
	ds_read_b128 v[232:235], v158 offset:37888
	ds_read_b128 v[236:239], v158 offset:38912
	ds_read_b128 v[240:243], v158 offset:39936
	global_load_lds_dwordx4 v[248:249], off
	v_lshl_add_u64 v[248:249], s[42:43], 0, v[168:169]
	s_mov_b32 m0, s49
	s_nop 0
	global_load_lds_dwordx4 v[248:249], off
	s_waitcnt vmcnt(8)
	s_waitcnt lgkmcnt(0)
	s_barrier
	s_setprio 1
	s_waitcnt lgkmcnt(0)
	v_mfma_f32_16x16x32_bf16 v[124:127], v[136:139], v[212:215], v[124:127]
	v_mfma_f32_16x16x32_bf16 v[124:127], v[140:143], v[216:219], v[124:127]
	v_mfma_f32_16x16x32_bf16 v[120:123], v[176:179], v[216:219], v[120:123]
	v_mfma_f32_16x16x32_bf16 v[120:123], v[172:175], v[212:215], v[120:123]
	v_mfma_f32_16x16x32_bf16 v[104:107], v[172:175], v[220:223], v[104:107]
	v_mfma_f32_16x16x32_bf16 v[104:107], v[176:179], v[224:227], v[104:107]
	v_mfma_f32_16x16x32_bf16 v[108:111], v[140:143], v[224:227], v[108:111]
	v_mfma_f32_16x16x32_bf16 v[108:111], v[136:139], v[220:223], v[108:111]
	v_mfma_f32_16x16x32_bf16 v[96:99], v[136:139], v[228:231], v[96:99]
	v_mfma_f32_16x16x32_bf16 v[96:99], v[140:143], v[232:235], v[96:99]
	v_mfma_f32_16x16x32_bf16 v[88:91], v[176:179], v[232:235], v[88:91]
	v_mfma_f32_16x16x32_bf16 v[88:91], v[172:175], v[228:231], v[88:91]
	v_mfma_f32_16x16x32_bf16 v[72:75], v[172:175], v[236:239], v[72:75]
	v_mfma_f32_16x16x32_bf16 v[72:75], v[176:179], v[240:243], v[72:75]
	v_mfma_f32_16x16x32_bf16 v[80:83], v[140:143], v[240:243], v[80:83]
	v_mfma_f32_16x16x32_bf16 v[80:83], v[136:139], v[236:239], v[80:83]
	s_setprio 0
	s_setprio 1
	v_mfma_f32_16x16x32_bf16 v[116:119], v[180:183], v[212:215], v[116:119]
	v_mfma_f32_16x16x32_bf16 v[116:119], v[184:187], v[216:219], v[116:119]
	v_mfma_f32_16x16x32_bf16 v[112:115], v[208:211], v[216:219], v[112:115]
	v_mfma_f32_16x16x32_bf16 v[112:115], v[196:199], v[212:215], v[112:115]
	v_mfma_f32_16x16x32_bf16 v[92:95], v[196:199], v[220:223], v[92:95]
	v_mfma_f32_16x16x32_bf16 v[92:95], v[208:211], v[224:227], v[92:95]
	v_mfma_f32_16x16x32_bf16 v[100:103], v[184:187], v[224:227], v[100:103]
	v_mfma_f32_16x16x32_bf16 v[100:103], v[180:183], v[220:223], v[100:103]
	v_mfma_f32_16x16x32_bf16 v[84:87], v[180:183], v[228:231], v[84:87]
	v_mfma_f32_16x16x32_bf16 v[84:87], v[184:187], v[232:235], v[84:87]
	v_mfma_f32_16x16x32_bf16 v[76:79], v[208:211], v[232:235], v[76:79]
	v_mfma_f32_16x16x32_bf16 v[76:79], v[196:199], v[228:231], v[76:79]
	v_mfma_f32_16x16x32_bf16 v[64:67], v[196:199], v[236:239], v[64:67]
	v_mfma_f32_16x16x32_bf16 v[64:67], v[208:211], v[240:243], v[64:67]
	s_setprio 2
	s_barrier
; #define PG8_STAGE(bufoff, gbase, voff) do { _Pragma("unroll") for (int _i = 0; _i < 2; ++_i) \
;         __builtin_amdgcn_global_load_lds((const unsigned*)((const char*)(gbase) + (voff)[_i]), (PG8_LAS unsigned*)(lds + (bufoff) + ldsw + _i * 8192), 16, 0, 0); } while (0)
; #define PG8_LDA(dst, b, h) do { _Pragma("unroll") for (int m = 0; m < 4; ++m) _Pragma("unroll") for (int k = 0; k < 2; ++k) dst[m][k] = *(const PG8_LAS bf16x8*)(lds + PG8_SA(b, h) + aoff + m * 2048 + k * 1024); } while (0)
; #define PG8_MMA(ai, bj, At, Bt) do { __builtin_amdgcn_s_setprio(1); _Pragma("unroll") for (int m = 0; m < 4; ++m) _Pragma("unroll") for (int n = 0; n < 2; ++n) _Pragma("unroll") for (int k = 0; k < 2; ++k) \
;         acc[ai][bj][m][n] = __builtin_amdgcn_mfma_f32_16x16x32_bf16(Bt[n][k], At[m][k], acc[ai][bj][m][n], 0, 0, 0); __builtin_amdgcn_s_setprio(0); } while (0)
; #define PG8_WAIT_V(n) asm volatile("s_waitcnt vmcnt(" #n ")" ::: "memory")
; #define PG8_WAIT_L(n) asm volatile("s_waitcnt lgkmcnt(" #n ")" ::: "memory")
; #define PG8_BAR __builtin_amdgcn_s_barrier()
; #define PG8_SCHED __builtin_amdgcn_sched_barrier(0)
; template <class Epi, class Sched, bool ALIGN_EPI = false, bool SP2 = false>
; __device__ __forceinline__ void gemm_phase(PG8_LAS unsigned char* lds, const Gemm g, const Sched& S, const Epi& E) {
;     ...
;             PG8_WAIT_V(8); PG8_WAIT_L(0); PG8_BAR; PG8_MMA(0, 0, At, B0); PG8_MMA(0, 1, At, B1); PG8_BAR; PG8_SCHED;
;             PG8_LDA(At, 1, 1); PG8_STAGE(PG8_SB(1, 0), b3, voffB); PG8_STAGE(PG8_SB(1, 1), b3 + hstep, voffB); PG8_STAGE(PG8_SA(1, 0), a3, voffA);
;             PG8_WAIT_V(8); PG8_WAIT_L(0); PG8_BAR; PG8_MMA(1, 0, At, B0); PG8_MMA(1, 1, At, B1); PG8_BAR; PG8_SCHED;
;     ...
;         if constexpr (ALIGN_EPI) { if (wr == 0) PG8_BAR; }
	v_mfma_f32_16x16x32_bf16 v[68:71], v[184:187], v[240:243], v[68:71]
	v_mfma_f32_16x16x32_bf16 v[68:71], v[180:183], v[236:239], v[68:71]
	s_setprio 0
	s_add_i32 s42, s44, s33
	v_lshl_add_u64 v[188:189], v[188:189], 0, s[14:15]
	s_mov_b32 m0, s42
	ds_read_b128 v[212:215], v158 offset:49152
	ds_read_b128 v[216:219], v158 offset:50176
	ds_read_b128 v[220:223], v158 offset:51200
	ds_read_b128 v[224:227], v158 offset:52224
	ds_read_b128 v[228:231], v158 offset:53248
	ds_read_b128 v[232:235], v158 offset:54272
	ds_read_b128 v[236:239], v158 offset:55296
	ds_read_b128 v[240:243], v158 offset:56320
	global_load_lds_dwordx4 v[188:189], off
	s_add_i32 m0, s42, 0x2000
	s_add_u32 s40, s40, 0x80080
	v_lshl_add_u64 v[188:189], v[200:201], 0, s[14:15]
	s_addc_u32 s41, s41, 0
	s_add_i32 s42, s45, s33
	global_load_lds_dwordx4 v[188:189], off
	v_lshl_add_u64 v[188:189], s[40:41], 0, v[166:167]
	s_mov_b32 m0, s42
	s_nop 0
	global_load_lds_dwordx4 v[188:189], off
	v_lshl_add_u64 v[188:189], s[40:41], 0, v[170:171]
	s_add_i32 m0, s42, 0x2000
	s_nop 0
	global_load_lds_dwordx4 v[188:189], off
	v_lshl_add_u64 v[188:189], v[244:245], 0, s[14:15]
	s_mov_b32 m0, s50
	s_nop 0
	global_load_lds_dwordx4 v[188:189], off
	v_lshl_add_u64 v[188:189], v[246:247], 0, s[14:15]
	s_mov_b32 m0, s51
	s_nop 0
	global_load_lds_dwordx4 v[188:189], off
	s_waitcnt vmcnt(8)
	s_waitcnt lgkmcnt(0)
	s_barrier
	s_setprio 1
	s_waitcnt lgkmcnt(0)
	v_mfma_f32_16x16x32_bf16 v[60:63], v[136:139], v[212:215], v[60:63]
	v_mfma_f32_16x16x32_bf16 v[60:63], v[140:143], v[216:219], v[60:63]
	v_mfma_f32_16x16x32_bf16 v[56:59], v[176:179], v[216:219], v[56:59]
	v_mfma_f32_16x16x32_bf16 v[56:59], v[172:175], v[212:215], v[56:59]
	v_mfma_f32_16x16x32_bf16 v[40:43], v[172:175], v[220:223], v[40:43]
	v_mfma_f32_16x16x32_bf16 v[40:43], v[176:179], v[224:227], v[40:43]
	v_mfma_f32_16x16x32_bf16 v[48:51], v[140:143], v[224:227], v[48:51]
	v_mfma_f32_16x16x32_bf16 v[48:51], v[136:139], v[220:223], v[48:51]
	v_mfma_f32_16x16x32_bf16 v[32:35], v[136:139], v[228:231], v[32:35]
	v_mfma_f32_16x16x32_bf16 v[32:35], v[140:143], v[232:235], v[32:35]
	v_mfma_f32_16x16x32_bf16 v[24:27], v[176:179], v[232:235], v[24:27]
	v_mfma_f32_16x16x32_bf16 v[24:27], v[172:175], v[228:231], v[24:27]
	v_mfma_f32_16x16x32_bf16 v[8:11], v[172:175], v[236:239], v[8:11]
	v_mfma_f32_16x16x32_bf16 v[8:11], v[176:179], v[240:243], v[8:11]
	v_mfma_f32_16x16x32_bf16 v[12:15], v[140:143], v[240:243], v[12:15]
	v_mfma_f32_16x16x32_bf16 v[12:15], v[136:139], v[236:239], v[12:15]
	s_setprio 0
	s_setprio 1
	v_mfma_f32_16x16x32_bf16 v[52:55], v[180:183], v[212:215], v[52:55]
	v_mfma_f32_16x16x32_bf16 v[52:55], v[184:187], v[216:219], v[52:55]
	v_mfma_f32_16x16x32_bf16 v[44:47], v[208:211], v[216:219], v[44:47]
	v_mfma_f32_16x16x32_bf16 v[44:47], v[196:199], v[212:215], v[44:47]
	v_mfma_f32_16x16x32_bf16 v[28:31], v[196:199], v[220:223], v[28:31]
	v_mfma_f32_16x16x32_bf16 v[28:31], v[208:211], v[224:227], v[28:31]
	v_mfma_f32_16x16x32_bf16 v[36:39], v[184:187], v[224:227], v[36:39]
	v_mfma_f32_16x16x32_bf16 v[36:39], v[180:183], v[220:223], v[36:39]
	v_mfma_f32_16x16x32_bf16 v[20:23], v[180:183], v[228:231], v[20:23]
	v_mfma_f32_16x16x32_bf16 v[20:23], v[184:187], v[232:235], v[20:23]
	v_mfma_f32_16x16x32_bf16 v[16:19], v[208:211], v[232:235], v[16:19]
	v_mfma_f32_16x16x32_bf16 v[16:19], v[196:199], v[228:231], v[16:19]
	v_mfma_f32_16x16x32_bf16 v[0:3], v[196:199], v[236:239], v[0:3]
	v_mfma_f32_16x16x32_bf16 v[0:3], v[208:211], v[240:243], v[0:3]
	s_setprio 2
	s_barrier
	v_mfma_f32_16x16x32_bf16 v[4:7], v[184:187], v[240:243], v[4:7]
	v_mfma_f32_16x16x32_bf16 v[4:7], v[180:183], v[236:239], v[4:7]
	s_setprio 0
	s_add_i32 s63, s63, 2
	s_add_u32 s38, s38, 0x100
	s_addc_u32 s39, s39, 0
	s_add_u32 s61, s61, 0x100
	s_addc_u32 s62, s62, 0
	s_cmp_gt_u32 s63, 29
	s_cbranch_scc0 .LBB0_880
	s_and_b64 vcc, exec, s[16:17]
	s_cbranch_vccz .LBB0_883
	s_barrier

; #define PG8_STAGE(bufoff, gbase, voff) do { _Pragma("unroll") for (int _i = 0; _i < 2; ++_i) \
;         __builtin_amdgcn_global_load_lds((const unsigned*)((const char*)(gbase) + (voff)[_i]), (PG8_LAS unsigned*)(lds + (bufoff) + ldsw + _i * 8192), 16, 0, 0); } while (0)
; #define PG8_LDA(dst, b, h) do { _Pragma("unroll") for (int m = 0; m < 4; ++m) _Pragma("unroll") for (int k = 0; k < 2; ++k) dst[m][k] = *(const PG8_LAS bf16x8*)(lds + PG8_SA(b, h) + aoff + m * 2048 + k * 1024); } while (0)
; #define PG8_LDB(dst, b, h) do { _Pragma("unroll") for (int n = 0; n < 2; ++n) _Pragma("unroll") for (int k = 0; k < 2; ++k) dst[n][k] = *(const PG8_LAS bf16x8*)(lds + PG8_SB(b, h) + boff + n * 2048 + k * 1024); } while (0)
; #define PG8_MMA(ai, bj, At, Bt) do { __builtin_amdgcn_s_setprio(1); _Pragma("unroll") for (int m = 0; m < 4; ++m) _Pragma("unroll") for (int n = 0; n < 2; ++n) _Pragma("unroll") for (int k = 0; k < 2; ++k) \
;         acc[ai][bj][m][n] = __builtin_amdgcn_mfma_f32_16x16x32_bf16(Bt[n][k], At[m][k], acc[ai][bj][m][n], 0, 0, 0); __builtin_amdgcn_s_setprio(0); } while (0)
; #define PG8_WAIT_V(n) asm volatile("s_waitcnt vmcnt(" #n ")" ::: "memory")
; #define PG8_WAIT_L(n) asm volatile("s_waitcnt lgkmcnt(" #n ")" ::: "memory")
; template <class Epi, class Sched, bool ALIGN_EPI = false, bool SP2 = false>
; __device__ __forceinline__ void gemm_phase(PG8_LAS unsigned char* lds, const Gemm g, const Sched& S, const Epi& E) {
;     ...
;             const bool last = (t == nt - 2);
;             const char* a1 = cA + (size_t)(t + 1) * kstep;
;             const char* a2 = last ? nA : cA + (size_t)(t + 2) * kstep; const char* b2 = last ? nB : cB + (size_t)(t + 2) * kstep;
;             const char* a3 = a2 + kstep; const char* b3 = b2 + kstep;
;             if (last && has_next) S.a_ready(nxt);
;             if constexpr (SP2) {
;             PG8_LDB(B0, 0, 0); PG8_LDB(B1, 0, 1); PG8_SCHED; PG8_LDA(At, 0, 0); PG8_STAGE(PG8_SA(1, 1), a1 + hstep, voffA);
;             PG8_WAIT_V(8); PG8_WAIT_L(0); PG8_BAR; PG8_MMA(0, 0, At, B0); PG8_MMA(0, 1, At, B1); PG8_BAR; PG8_SCHED;
;             PG8_LDA(At, 0, 1); PG8_STAGE(PG8_SB(0, 0), b2, voffB); PG8_STAGE(PG8_SB(0, 1), b2 + hstep, voffB); PG8_STAGE(PG8_SA(0, 0), a2, voffA);
;             PG8_WAIT_V(8); PG8_WAIT_L(0); PG8_BAR; PG8_MMA(1, 0, At, B0); PG8_MMA(1, 1, At, B1); PG8_BAR; PG8_SCHED;
.LBB0_937:
	ds_read_b128 v[128:131], v199
	ds_read_b128 v[132:135], v199 offset:1024
	ds_read_b128 v[136:139], v199 offset:2048
	ds_read_b128 v[140:143], v199 offset:3072
	ds_read_b128 v[150:153], v200
	ds_read_b128 v[154:157], v200 offset:1024
	ds_read_b128 v[164:167], v200 offset:2048
	ds_read_b128 v[168:171], v200 offset:3072
	s_add_u32 s22, s20, 0xffea0080
	s_addc_u32 s23, s21, -1
	s_cmpk_eq_i32 s49, 0x54
	s_cselect_b32 s25, s17, s23
	s_cselect_b32 s24, s16, s22
	s_cselect_b32 s23, s19, s48
	s_cselect_b32 s22, s18, s47
	v_lshl_add_u64 v[158:159], s[20:21], 0, v[144:145]
	s_add_i32 m0, s31, 0xc000
	ds_read_b128 v[172:175], v201
	ds_read_b128 v[176:179], v201 offset:1024
	ds_read_b128 v[180:183], v201 offset:2048
	ds_read_b128 v[184:187], v201 offset:3072
	ds_read_b128 v[188:191], v201 offset:4096
	ds_read_b128 v[204:207], v201 offset:5120
	ds_read_b128 v[208:211], v201 offset:6144
	ds_read_b128 v[212:215], v201 offset:7168
	global_load_lds_dwordx4 v[158:159], off
	v_lshl_add_u64 v[158:159], s[20:21], 0, v[146:147]
	s_add_i32 m0, s31, 0xe000
	s_nop 0
	global_load_lds_dwordx4 v[158:159], off
	s_waitcnt vmcnt(8)
	s_waitcnt lgkmcnt(0)
	s_barrier
	s_setprio 1
	s_waitcnt lgkmcnt(0)
	v_mfma_f32_16x16x32_bf16 v[124:127], v[128:131], v[172:175], v[124:127]
	v_mfma_f32_16x16x32_bf16 v[124:127], v[132:135], v[176:179], v[124:127]
	v_mfma_f32_16x16x32_bf16 v[120:123], v[140:143], v[176:179], v[120:123]
	v_mfma_f32_16x16x32_bf16 v[120:123], v[136:139], v[172:175], v[120:123]
	v_mfma_f32_16x16x32_bf16 v[104:107], v[136:139], v[180:183], v[104:107]
	v_mfma_f32_16x16x32_bf16 v[104:107], v[140:143], v[184:187], v[104:107]
	v_mfma_f32_16x16x32_bf16 v[108:111], v[132:135], v[184:187], v[108:111]
	v_mfma_f32_16x16x32_bf16 v[108:111], v[128:131], v[180:183], v[108:111]
	v_mfma_f32_16x16x32_bf16 v[92:95], v[128:131], v[188:191], v[92:95]
	v_mfma_f32_16x16x32_bf16 v[92:95], v[132:135], v[204:207], v[92:95]
	v_mfma_f32_16x16x32_bf16 v[88:91], v[140:143], v[204:207], v[88:91]
	v_mfma_f32_16x16x32_bf16 v[88:91], v[136:139], v[188:191], v[88:91]
	v_mfma_f32_16x16x32_bf16 v[72:75], v[136:139], v[208:211], v[72:75]
	v_mfma_f32_16x16x32_bf16 v[72:75], v[140:143], v[212:215], v[72:75]
	v_mfma_f32_16x16x32_bf16 v[76:79], v[132:135], v[212:215], v[76:79]
	v_mfma_f32_16x16x32_bf16 v[76:79], v[128:131], v[208:211], v[76:79]
	s_setprio 0
	s_setprio 1
	v_mfma_f32_16x16x32_bf16 v[116:119], v[150:153], v[172:175], v[116:119]
	v_mfma_f32_16x16x32_bf16 v[116:119], v[154:157], v[176:179], v[116:119]
	v_mfma_f32_16x16x32_bf16 v[112:115], v[168:171], v[176:179], v[112:115]
	v_mfma_f32_16x16x32_bf16 v[112:115], v[164:167], v[172:175], v[112:115]
	v_mfma_f32_16x16x32_bf16 v[96:99], v[164:167], v[180:183], v[96:99]
	v_mfma_f32_16x16x32_bf16 v[96:99], v[168:171], v[184:187], v[96:99]
	v_mfma_f32_16x16x32_bf16 v[100:103], v[154:157], v[184:187], v[100:103]
	v_mfma_f32_16x16x32_bf16 v[100:103], v[150:153], v[180:183], v[100:103]
	v_mfma_f32_16x16x32_bf16 v[84:87], v[150:153], v[188:191], v[84:87]
	v_mfma_f32_16x16x32_bf16 v[84:87], v[154:157], v[204:207], v[84:87]
	v_mfma_f32_16x16x32_bf16 v[80:83], v[168:171], v[204:207], v[80:83]
	v_mfma_f32_16x16x32_bf16 v[80:83], v[164:167], v[188:191], v[80:83]
	v_mfma_f32_16x16x32_bf16 v[64:67], v[164:167], v[208:211], v[64:67]
	v_mfma_f32_16x16x32_bf16 v[64:67], v[168:171], v[212:215], v[64:67]
	s_setprio 2
	s_barrier
	v_mfma_f32_16x16x32_bf16 v[68:71], v[154:157], v[212:215], v[68:71]
	v_mfma_f32_16x16x32_bf16 v[68:71], v[150:153], v[208:211], v[68:71]
	s_setprio 0
	s_add_i32 s50, s41, s30
	v_lshl_add_u64 v[158:159], s[22:23], 0, v[160:161]
	s_mov_b32 m0, s50
	ds_read_b128 v[172:175], v201 offset:16384
	ds_read_b128 v[176:179], v201 offset:17408
	ds_read_b128 v[180:183], v201 offset:18432
	ds_read_b128 v[184:187], v201 offset:19456
	ds_read_b128 v[188:191], v201 offset:20480
	ds_read_b128 v[204:207], v201 offset:21504
	ds_read_b128 v[208:211], v201 offset:22528
	ds_read_b128 v[212:215], v201 offset:23552
	global_load_lds_dwordx4 v[158:159], off
	s_add_i32 m0, s50, 0x2000
	s_add_u32 s50, s22, 0x160000
	v_lshl_add_u64 v[192:193], s[22:23], 0, v[162:163]
	s_addc_u32 s51, s23, 0
	s_add_i32 s52, s42, s30
	global_load_lds_dwordx4 v[192:193], off
	v_lshl_add_u64 v[216:217], s[50:51], 0, v[160:161]
	s_mov_b32 m0, s52
	v_lshl_add_u64 v[218:219], s[24:25], 0, v[162:163]
	global_load_lds_dwordx4 v[216:217], off
	v_lshl_add_u64 v[216:217], s[50:51], 0, v[162:163]
	s_add_i32 m0, s52, 0x2000
	s_nop 0
	global_load_lds_dwordx4 v[216:217], off
	v_lshl_add_u64 v[216:217], s[24:25], 0, v[160:161]
	s_mov_b32 m0, s31
	s_nop 0
	global_load_lds_dwordx4 v[216:217], off
	s_mov_b32 m0, s33
	s_nop 0
	global_load_lds_dwordx4 v[218:219], off
	s_waitcnt vmcnt(8)
	s_waitcnt lgkmcnt(0)
	s_barrier
; #define PG8_STAGE(bufoff, gbase, voff) do { _Pragma("unroll") for (int _i = 0; _i < 2; ++_i) \
;         __builtin_amdgcn_global_load_lds((const unsigned*)((const char*)(gbase) + (voff)[_i]), (PG8_LAS unsigned*)(lds + (bufoff) + ldsw + _i * 8192), 16, 0, 0); } while (0)
; #define PG8_LDA(dst, b, h) do { _Pragma("unroll") for (int m = 0; m < 4; ++m) _Pragma("unroll") for (int k = 0; k < 2; ++k) dst[m][k] = *(const PG8_LAS bf16x8*)(lds + PG8_SA(b, h) + aoff + m * 2048 + k * 1024); } while (0)
; #define PG8_LDB(dst, b, h) do { _Pragma("unroll") for (int n = 0; n < 2; ++n) _Pragma("unroll") for (int k = 0; k < 2; ++k) dst[n][k] = *(const PG8_LAS bf16x8*)(lds + PG8_SB(b, h) + boff + n * 2048 + k * 1024); } while (0)
; #define PG8_MMA(ai, bj, At, Bt) do { __builtin_amdgcn_s_setprio(1); _Pragma("unroll") for (int m = 0; m < 4; ++m) _Pragma("unroll") for (int n = 0; n < 2; ++n) _Pragma("unroll") for (int k = 0; k < 2; ++k) \
;         acc[ai][bj][m][n] = __builtin_amdgcn_mfma_f32_16x16x32_bf16(Bt[n][k], At[m][k], acc[ai][bj][m][n], 0, 0, 0); __builtin_amdgcn_s_setprio(0); } while (0)
; #define PG8_WAIT_V(n) asm volatile("s_waitcnt vmcnt(" #n ")" ::: "memory")
; #define PG8_WAIT_L(n) asm volatile("s_waitcnt lgkmcnt(" #n ")" ::: "memory")
; #define PG8_BAR __builtin_amdgcn_s_barrier()
; #define PG8_SCHED __builtin_amdgcn_sched_barrier(0)
; template <class Epi, class Sched, bool ALIGN_EPI = false, bool SP2 = false>
; __device__ __forceinline__ void gemm_phase(PG8_LAS unsigned char* lds, const Gemm g, const Sched& S, const Epi& E) {
;     ...
;             PG8_WAIT_V(8); PG8_WAIT_L(0); PG8_BAR; PG8_MMA(1, 0, At, B0); PG8_MMA(1, 1, At, B1); PG8_BAR; PG8_SCHED;
;             PG8_LDB(B0, 1, 0); PG8_LDB(B1, 1, 1); PG8_SCHED; PG8_LDA(At, 1, 0); PG8_STAGE(PG8_SA(0, 1), a2 + hstep, voffA);
;             PG8_WAIT_V(8); PG8_WAIT_L(0); PG8_BAR; PG8_MMA(0, 0, At, B0); PG8_MMA(0, 1, At, B1); PG8_BAR; PG8_SCHED;
	s_setprio 1
	s_waitcnt lgkmcnt(0)
	v_mfma_f32_16x16x32_bf16 v[60:63], v[128:131], v[172:175], v[60:63]
	v_mfma_f32_16x16x32_bf16 v[60:63], v[132:135], v[176:179], v[60:63]
	v_mfma_f32_16x16x32_bf16 v[56:59], v[140:143], v[176:179], v[56:59]
	v_mfma_f32_16x16x32_bf16 v[56:59], v[136:139], v[172:175], v[56:59]
	v_mfma_f32_16x16x32_bf16 v[40:43], v[136:139], v[180:183], v[40:43]
	v_mfma_f32_16x16x32_bf16 v[40:43], v[140:143], v[184:187], v[40:43]
	v_mfma_f32_16x16x32_bf16 v[44:47], v[132:135], v[184:187], v[44:47]
	v_mfma_f32_16x16x32_bf16 v[44:47], v[128:131], v[180:183], v[44:47]
	v_mfma_f32_16x16x32_bf16 v[28:31], v[128:131], v[188:191], v[28:31]
	v_mfma_f32_16x16x32_bf16 v[28:31], v[132:135], v[204:207], v[28:31]
	v_mfma_f32_16x16x32_bf16 v[24:27], v[140:143], v[204:207], v[24:27]
	v_mfma_f32_16x16x32_bf16 v[24:27], v[136:139], v[188:191], v[24:27]
	v_mfma_f32_16x16x32_bf16 v[8:11], v[136:139], v[208:211], v[8:11]
	v_mfma_f32_16x16x32_bf16 v[8:11], v[140:143], v[212:215], v[8:11]
	v_mfma_f32_16x16x32_bf16 v[12:15], v[132:135], v[212:215], v[12:15]
	v_mfma_f32_16x16x32_bf16 v[12:15], v[128:131], v[208:211], v[12:15]
	s_setprio 0
	s_setprio 1
	v_mfma_f32_16x16x32_bf16 v[52:55], v[150:153], v[172:175], v[52:55]
	v_mfma_f32_16x16x32_bf16 v[52:55], v[154:157], v[176:179], v[52:55]
	v_mfma_f32_16x16x32_bf16 v[48:51], v[168:171], v[176:179], v[48:51]
	v_mfma_f32_16x16x32_bf16 v[48:51], v[164:167], v[172:175], v[48:51]
	v_mfma_f32_16x16x32_bf16 v[32:35], v[164:167], v[180:183], v[32:35]
	v_mfma_f32_16x16x32_bf16 v[32:35], v[168:171], v[184:187], v[32:35]
	v_mfma_f32_16x16x32_bf16 v[36:39], v[154:157], v[184:187], v[36:39]
	v_mfma_f32_16x16x32_bf16 v[36:39], v[150:153], v[180:183], v[36:39]
	v_mfma_f32_16x16x32_bf16 v[20:23], v[150:153], v[188:191], v[20:23]
	v_mfma_f32_16x16x32_bf16 v[20:23], v[154:157], v[204:207], v[20:23]
	v_mfma_f32_16x16x32_bf16 v[16:19], v[168:171], v[204:207], v[16:19]
	v_mfma_f32_16x16x32_bf16 v[16:19], v[164:167], v[188:191], v[16:19]
	v_mfma_f32_16x16x32_bf16 v[0:3], v[164:167], v[208:211], v[0:3]
	v_mfma_f32_16x16x32_bf16 v[0:3], v[168:171], v[212:215], v[0:3]
	s_setprio 2
	s_barrier
	v_mfma_f32_16x16x32_bf16 v[4:7], v[154:157], v[212:215], v[4:7]
	v_mfma_f32_16x16x32_bf16 v[4:7], v[150:153], v[208:211], v[4:7]
	s_setprio 0
	s_add_i32 s50, 0, 0x18000
	s_add_i32 s51, 0, 0x1c000
	v_add_u32_e32 v140, s50, v196
	v_add_u32_e32 v168, s51, v196
	ds_read_b128 v[128:131], v140
	ds_read_b128 v[132:135], v140 offset:1024
	ds_read_b128 v[136:139], v140 offset:2048
	ds_read_b128 v[140:143], v140 offset:3072
	ds_read_b128 v[150:153], v168
	ds_read_b128 v[154:157], v168 offset:1024
	ds_read_b128 v[164:167], v168 offset:2048
	ds_read_b128 v[168:171], v168 offset:3072
	s_add_u32 s24, s24, 0x160000
	s_addc_u32 s25, s25, 0
	s_mov_b32 m0, s34
	v_lshl_add_u64 v[220:221], s[24:25], 0, v[160:161]
	ds_read_b128 v[172:175], v201 offset:32768
	ds_read_b128 v[176:179], v201 offset:33792
	ds_read_b128 v[180:183], v201 offset:34816
	ds_read_b128 v[184:187], v201 offset:35840
	ds_read_b128 v[188:191], v201 offset:36864
	ds_read_b128 v[204:207], v201 offset:37888
	ds_read_b128 v[208:211], v201 offset:38912
	ds_read_b128 v[212:215], v201 offset:39936
	global_load_lds_dwordx4 v[220:221], off
	v_lshl_add_u64 v[220:221], s[24:25], 0, v[162:163]
	s_mov_b32 m0, s35
	s_nop 0
	global_load_lds_dwordx4 v[220:221], off
	s_waitcnt vmcnt(8)
	s_waitcnt lgkmcnt(0)
	s_barrier
	s_setprio 1
	s_waitcnt lgkmcnt(0)
	v_mfma_f32_16x16x32_bf16 v[124:127], v[128:131], v[172:175], v[124:127]
	v_mfma_f32_16x16x32_bf16 v[124:127], v[132:135], v[176:179], v[124:127]
	v_mfma_f32_16x16x32_bf16 v[120:123], v[140:143], v[176:179], v[120:123]
	v_mfma_f32_16x16x32_bf16 v[120:123], v[136:139], v[172:175], v[120:123]
	v_mfma_f32_16x16x32_bf16 v[104:107], v[136:139], v[180:183], v[104:107]
	v_mfma_f32_16x16x32_bf16 v[104:107], v[140:143], v[184:187], v[104:107]
	v_mfma_f32_16x16x32_bf16 v[108:111], v[132:135], v[184:187], v[108:111]
	v_mfma_f32_16x16x32_bf16 v[108:111], v[128:131], v[180:183], v[108:111]
	v_mfma_f32_16x16x32_bf16 v[92:95], v[128:131], v[188:191], v[92:95]
	v_mfma_f32_16x16x32_bf16 v[92:95], v[132:135], v[204:207], v[92:95]
	v_mfma_f32_16x16x32_bf16 v[88:91], v[140:143], v[204:207], v[88:91]
	v_mfma_f32_16x16x32_bf16 v[88:91], v[136:139], v[188:191], v[88:91]
	v_mfma_f32_16x16x32_bf16 v[72:75], v[136:139], v[208:211], v[72:75]
	v_mfma_f32_16x16x32_bf16 v[72:75], v[140:143], v[212:215], v[72:75]
	v_mfma_f32_16x16x32_bf16 v[76:79], v[132:135], v[212:215], v[76:79]
	v_mfma_f32_16x16x32_bf16 v[76:79], v[128:131], v[208:211], v[76:79]
	s_setprio 0
	s_setprio 1
	v_mfma_f32_16x16x32_bf16 v[116:119], v[150:153], v[172:175], v[116:119]
	v_mfma_f32_16x16x32_bf16 v[116:119], v[154:157], v[176:179], v[116:119]
	v_mfma_f32_16x16x32_bf16 v[112:115], v[168:171], v[176:179], v[112:115]
	v_mfma_f32_16x16x32_bf16 v[112:115], v[164:167], v[172:175], v[112:115]
	v_mfma_f32_16x16x32_bf16 v[96:99], v[164:167], v[180:183], v[96:99]
	v_mfma_f32_16x16x32_bf16 v[96:99], v[168:171], v[184:187], v[96:99]
	v_mfma_f32_16x16x32_bf16 v[100:103], v[154:157], v[184:187], v[100:103]
	v_mfma_f32_16x16x32_bf16 v[100:103], v[150:153], v[180:183], v[100:103]
	v_mfma_f32_16x16x32_bf16 v[84:87], v[150:153], v[188:191], v[84:87]
	v_mfma_f32_16x16x32_bf16 v[84:87], v[154:157], v[204:207], v[84:87]
	v_mfma_f32_16x16x32_bf16 v[80:83], v[168:171], v[204:207], v[80:83]
	v_mfma_f32_16x16x32_bf16 v[80:83], v[164:167], v[188:191], v[80:83]
	v_mfma_f32_16x16x32_bf16 v[64:67], v[164:167], v[208:211], v[64:67]
	v_mfma_f32_16x16x32_bf16 v[64:67], v[168:171], v[212:215], v[64:67]
	s_setprio 2
	s_barrier
; #define PG8_STAGE(bufoff, gbase, voff) do { _Pragma("unroll") for (int _i = 0; _i < 2; ++_i) \
;         __builtin_amdgcn_global_load_lds((const unsigned*)((const char*)(gbase) + (voff)[_i]), (PG8_LAS unsigned*)(lds + (bufoff) + ldsw + _i * 8192), 16, 0, 0); } while (0)
; #define PG8_LDA(dst, b, h) do { _Pragma("unroll") for (int m = 0; m < 4; ++m) _Pragma("unroll") for (int k = 0; k < 2; ++k) dst[m][k] = *(const PG8_LAS bf16x8*)(lds + PG8_SA(b, h) + aoff + m * 2048 + k * 1024); } while (0)
; #define PG8_MMA(ai, bj, At, Bt) do { __builtin_amdgcn_s_setprio(1); _Pragma("unroll") for (int m = 0; m < 4; ++m) _Pragma("unroll") for (int n = 0; n < 2; ++n) _Pragma("unroll") for (int k = 0; k < 2; ++k) \
;         acc[ai][bj][m][n] = __builtin_amdgcn_mfma_f32_16x16x32_bf16(Bt[n][k], At[m][k], acc[ai][bj][m][n], 0, 0, 0); __builtin_amdgcn_s_setprio(0); } while (0)
; #define PG8_WAIT_V(n) asm volatile("s_waitcnt vmcnt(" #n ")" ::: "memory")
; #define PG8_WAIT_L(n) asm volatile("s_waitcnt lgkmcnt(" #n ")" ::: "memory")
; #define PG8_BAR __builtin_amdgcn_s_barrier()
; #define PG8_SCHED __builtin_amdgcn_sched_barrier(0)
; template <class Epi, class Sched, bool ALIGN_EPI = false, bool SP2 = false>
; __device__ __forceinline__ void gemm_phase(PG8_LAS unsigned char* lds, const Gemm g, const Sched& S, const Epi& E) {
;     ...
;             PG8_WAIT_V(8); PG8_WAIT_L(0); PG8_BAR; PG8_MMA(0, 0, At, B0); PG8_MMA(0, 1, At, B1); PG8_BAR; PG8_SCHED;
;             PG8_LDA(At, 1, 1); PG8_STAGE(PG8_SB(1, 0), b3, voffB); PG8_STAGE(PG8_SB(1, 1), b3 + hstep, voffB); PG8_STAGE(PG8_SA(1, 0), a3, voffA);
;             PG8_WAIT_V(8); PG8_WAIT_L(0); PG8_BAR; PG8_MMA(1, 0, At, B0); PG8_MMA(1, 1, At, B1); PG8_BAR; PG8_SCHED;
;     ...
;         if constexpr (ALIGN_EPI) { if (wr == 0) PG8_BAR; }
	v_mfma_f32_16x16x32_bf16 v[68:71], v[154:157], v[212:215], v[68:71]
	v_mfma_f32_16x16x32_bf16 v[68:71], v[150:153], v[208:211], v[68:71]
	s_setprio 0
	s_add_i32 s24, s50, s30
	v_lshl_add_u64 v[158:159], v[158:159], 0, s[12:13]
	s_mov_b32 m0, s24
	ds_read_b128 v[172:175], v201 offset:49152
	ds_read_b128 v[176:179], v201 offset:50176
	ds_read_b128 v[180:183], v201 offset:51200
	ds_read_b128 v[184:187], v201 offset:52224
	ds_read_b128 v[188:191], v201 offset:53248
	ds_read_b128 v[204:207], v201 offset:54272
	ds_read_b128 v[208:211], v201 offset:55296
	ds_read_b128 v[212:215], v201 offset:56320
	global_load_lds_dwordx4 v[158:159], off
	s_add_i32 m0, s24, 0x2000
	s_add_u32 s22, s22, 0x160080
	v_lshl_add_u64 v[158:159], v[192:193], 0, s[12:13]
	s_addc_u32 s23, s23, 0
	s_add_i32 s24, s51, s30
	global_load_lds_dwordx4 v[158:159], off
	v_lshl_add_u64 v[158:159], s[22:23], 0, v[160:161]
	s_mov_b32 m0, s24
	s_nop 0
	global_load_lds_dwordx4 v[158:159], off
	v_lshl_add_u64 v[158:159], s[22:23], 0, v[162:163]
	s_add_i32 m0, s24, 0x2000
	s_nop 0
	global_load_lds_dwordx4 v[158:159], off
	v_lshl_add_u64 v[158:159], v[216:217], 0, s[12:13]
	s_mov_b32 m0, s39
	s_nop 0
	global_load_lds_dwordx4 v[158:159], off
	v_lshl_add_u64 v[158:159], v[218:219], 0, s[12:13]
	s_mov_b32 m0, s40
	s_nop 0
	global_load_lds_dwordx4 v[158:159], off
	s_waitcnt vmcnt(8)
	s_waitcnt lgkmcnt(0)
	s_barrier
	s_setprio 1
	s_waitcnt lgkmcnt(0)
	v_mfma_f32_16x16x32_bf16 v[60:63], v[128:131], v[172:175], v[60:63]
	v_mfma_f32_16x16x32_bf16 v[60:63], v[132:135], v[176:179], v[60:63]
	v_mfma_f32_16x16x32_bf16 v[56:59], v[140:143], v[176:179], v[56:59]
	v_mfma_f32_16x16x32_bf16 v[56:59], v[136:139], v[172:175], v[56:59]
	v_mfma_f32_16x16x32_bf16 v[40:43], v[136:139], v[180:183], v[40:43]
	v_mfma_f32_16x16x32_bf16 v[40:43], v[140:143], v[184:187], v[40:43]
	v_mfma_f32_16x16x32_bf16 v[44:47], v[132:135], v[184:187], v[44:47]
	v_mfma_f32_16x16x32_bf16 v[44:47], v[128:131], v[180:183], v[44:47]
	v_mfma_f32_16x16x32_bf16 v[28:31], v[128:131], v[188:191], v[28:31]
	v_mfma_f32_16x16x32_bf16 v[28:31], v[132:135], v[204:207], v[28:31]
	v_mfma_f32_16x16x32_bf16 v[24:27], v[140:143], v[204:207], v[24:27]
	v_mfma_f32_16x16x32_bf16 v[24:27], v[136:139], v[188:191], v[24:27]
	v_mfma_f32_16x16x32_bf16 v[8:11], v[136:139], v[208:211], v[8:11]
	v_mfma_f32_16x16x32_bf16 v[8:11], v[140:143], v[212:215], v[8:11]
	v_mfma_f32_16x16x32_bf16 v[12:15], v[132:135], v[212:215], v[12:15]
	v_mfma_f32_16x16x32_bf16 v[12:15], v[128:131], v[208:211], v[12:15]
	s_setprio 0
	s_setprio 1
	v_mfma_f32_16x16x32_bf16 v[52:55], v[150:153], v[172:175], v[52:55]
	v_mfma_f32_16x16x32_bf16 v[52:55], v[154:157], v[176:179], v[52:55]
	v_mfma_f32_16x16x32_bf16 v[48:51], v[168:171], v[176:179], v[48:51]
	v_mfma_f32_16x16x32_bf16 v[48:51], v[164:167], v[172:175], v[48:51]
	v_mfma_f32_16x16x32_bf16 v[32:35], v[164:167], v[180:183], v[32:35]
	v_mfma_f32_16x16x32_bf16 v[32:35], v[168:171], v[184:187], v[32:35]
	v_mfma_f32_16x16x32_bf16 v[36:39], v[154:157], v[184:187], v[36:39]
	v_mfma_f32_16x16x32_bf16 v[36:39], v[150:153], v[180:183], v[36:39]
	v_mfma_f32_16x16x32_bf16 v[20:23], v[150:153], v[188:191], v[20:23]
	v_mfma_f32_16x16x32_bf16 v[20:23], v[154:157], v[204:207], v[20:23]
	v_mfma_f32_16x16x32_bf16 v[16:19], v[168:171], v[204:207], v[16:19]
	v_mfma_f32_16x16x32_bf16 v[16:19], v[164:167], v[188:191], v[16:19]
	v_mfma_f32_16x16x32_bf16 v[0:3], v[164:167], v[208:211], v[0:3]
	v_mfma_f32_16x16x32_bf16 v[0:3], v[168:171], v[212:215], v[0:3]
	s_setprio 2
	s_barrier
	v_mfma_f32_16x16x32_bf16 v[4:7], v[154:157], v[212:215], v[4:7]
	v_mfma_f32_16x16x32_bf16 v[4:7], v[150:153], v[208:211], v[4:7]
	s_setprio 0
	s_add_i32 s49, s49, 2
	s_add_u32 s20, s20, 0x100
	s_addc_u32 s21, s21, 0
	s_add_u32 s47, s47, 0x100
	s_addc_u32 s48, s48, 0
	s_cmpk_gt_u32 s49, 0x55
	s_cbranch_scc0 .LBB0_937
	s_and_b64 vcc, exec, s[14:15]
	s_cbranch_vccz .LBB0_940
	s_barrier
